# row-sum accumulation with scalar v_add_f32 pairs instead of v_pk_add_f32 (packed f32 next to MFMAs was very expensive)
# speedup vs baseline: 1.0897x; 1.0529x over previous
; #define LAS __attribute__((address_space(3)))
; __device__ __forceinline__ void attn_unit(LAS unsigned char* lds, const bf16_t* Z, bf16_t* A2, const float* tabg, int seq_base, int S, int h, int qb, float lam) {
;     ...
;         {
;             bf16x8 kf[8];
; #pragma unroll
;             for (int ds = 0; ds < 4; ++ds) { kf[2 * ds] = *(const LAS bf16x8*)(Kt + (kfo ^ (unsigned)(ds << 5))); kf[2 * ds + 1] = *(const LAS bf16x8*)(Kt + 32 * 256 + (kfo ^ (unsigned)(ds << 5))); }
;             __builtin_amdgcn_sched_barrier(0);
;             p0 = __builtin_amdgcn_mfma_f32_32x32x16_bf16(kf[0], qf[0], cblk, 0, 0, 0);
;             p1 = __builtin_amdgcn_mfma_f32_32x32x16_bf16(kf[1], qf[0], cblk, 0, 0, 0);
; #pragma unroll
;             for (int ds = 1; ds < 4; ++ds) {
;     ...
;         float mx = max2f(max16f(p0), max16f(p1));
;         const bool first = (t == 0);
;         if (first || __any(mx > THR)) {
;             { auto rr = __builtin_amdgcn_permlane32_swap(__float_as_uint(mx), __float_as_uint(mx), false, false); mx = max2f(__uint_as_float(rr[0]), __uint_as_float(rr[1])); }
;             const float delta = first ? mx : fmaxf(mx, 0.f);
;             const float alpha = first ? 1.0f : __builtin_amdgcn_exp2f(-delta);
;             mu += delta; ls2 *= alpha;
;             if (!first) {
;                 asm volatile("" ::: "memory");
;                 scr[r32] = alpha;
;                 asm volatile("s_waitcnt lgkmcnt(0)" ::: "memory");
; #pragma unroll
;                 for (int g = 0; g < 4; ++g) { const f32x4 a4 = *(const LAS f32x4*)(scr + 8 * g + 4 * hi);
; #pragma unroll
;                     for (int d = 0; d < 4; ++d) { O[d][4 * g + 0] *= a4[0]; O[d][4 * g + 1] *= a4[1]; O[d][4 * g + 2] *= a4[2]; O[d][4 * g + 3] *= a4[3]; } }
;                 asm volatile("s_waitcnt lgkmcnt(0)" ::: "memory");
;             }
; #pragma unroll
;             for (int r = 0; r < 16; ++r) { p0[r] -= delta; p1[r] -= delta; }
;             asm volatile("" : "+v"(p0), "+v"(p1));
;         }
; #pragma unroll
;         for (int r = 0; r < 16; ++r) { p0[r] = __builtin_amdgcn_exp2f(p0[r]); p1[r] = __builtin_amdgcn_exp2f(p1[r]); }
; #pragma unroll
;         for (int r = 0; r < 16; r += 2) { ls2 += (f32x2){p0[r], p0[r + 1]}; ls2 += (f32x2){p1[r], p1[r + 1]}; }
;         bf16x8 pa[4]; pa[0] = pack8(p0, 0); pa[1] = pack8(p0, 8); pa[2] = pack8(p1, 0); pa[3] = pack8(p1, 8);
.LatA_p0_nonear:
	v_max3_f32 v251, v84, v85, v86
	v_max3_f32 v252, v87, v88, v89
	v_max3_f32 v251, v251, v90, v91
	v_max3_f32 v252, v252, v92, v93
	v_max3_f32 v251, v251, v94, v95
	v_max3_f32 v252, v252, v96, v97
	v_max3_f32 v251, v251, v98, v99
	v_max3_f32 v252, v252, v100, v101
	v_max3_f32 v251, v251, v102, v103
	v_max3_f32 v252, v252, v104, v105
	v_max3_f32 v251, v251, v106, v107
	v_max3_f32 v252, v252, v108, v109
	v_max3_f32 v251, v251, v110, v111
	v_max3_f32 v252, v252, v112, v113
	v_max3_f32 v251, v251, v114, v115
	v_max_f32_e32 v251, v251, v252
	v_mov_b32_e32 v252, v251
	s_nop 1
	v_permlane32_swap_b32_e32 v251, v252
	v_max_f32_e32 v186, v251, v252
	v_sub_f32_e32 v84, v84, v186
	v_sub_f32_e32 v85, v85, v186
	v_sub_f32_e32 v86, v86, v186
	v_sub_f32_e32 v87, v87, v186
	v_sub_f32_e32 v88, v88, v186
	v_sub_f32_e32 v89, v89, v186
	v_sub_f32_e32 v90, v90, v186
	v_sub_f32_e32 v91, v91, v186
	v_sub_f32_e32 v92, v92, v186
	v_sub_f32_e32 v93, v93, v186
	v_sub_f32_e32 v94, v94, v186
	v_sub_f32_e32 v95, v95, v186
	v_sub_f32_e32 v96, v96, v186
	v_sub_f32_e32 v97, v97, v186
	v_sub_f32_e32 v98, v98, v186
	v_sub_f32_e32 v99, v99, v186
	v_sub_f32_e32 v100, v100, v186
	v_sub_f32_e32 v101, v101, v186
	v_sub_f32_e32 v102, v102, v186
	v_sub_f32_e32 v103, v103, v186
	v_sub_f32_e32 v104, v104, v186
	v_sub_f32_e32 v105, v105, v186
	v_sub_f32_e32 v106, v106, v186
	v_sub_f32_e32 v107, v107, v186
	v_sub_f32_e32 v108, v108, v186
	v_sub_f32_e32 v109, v109, v186
	v_sub_f32_e32 v110, v110, v186
	v_sub_f32_e32 v111, v111, v186
	v_sub_f32_e32 v112, v112, v186
	v_sub_f32_e32 v113, v113, v186
	v_sub_f32_e32 v114, v114, v186
	v_sub_f32_e32 v115, v115, v186
	s_add_u32 s38, s5, 64
	s_cmp_lt_u32 s38, s11
	s_cselect_b32 s37, 1, 0
	s_cmp_gt_u32 s38, s31
	s_cselect_b32 s40, 2, 0
	s_or_b32 s37, s37, s40
	s_mov_b32 s35, s37
	v_mov_b32_e32 v251, 0
	s_cmp_eq_u32 s37, 1
	s_cselect_b64 vcc, -1, 0
	v_cndmask_b32_e32 v251, v251, v177, vcc
	s_cmp_eq_u32 s37, 2
	s_cselect_b64 vcc, -1, 0
	v_cndmask_b32_e32 v251, v251, v178, vcc
	v_sub_f32_e32 v2, v251, v186
	v_mov_b32_e32 v3, v2
	v_mov_b64_e32 v[4:5], v[2:3]
	v_mov_b64_e32 v[6:7], v[2:3]
	v_mov_b64_e32 v[8:9], v[2:3]
	v_mov_b64_e32 v[10:11], v[2:3]
	v_mov_b64_e32 v[12:13], v[2:3]
	v_mov_b64_e32 v[14:15], v[2:3]
	v_mov_b64_e32 v[16:17], v[2:3]
	s_waitcnt vmcnt(0)
	s_barrier
	ds_read_b128 v[132:135], v19 offset:16384
	ds_read_b128 v[136:139], v19 offset:24576
	ds_read_b128 v[140:143], v180 offset:16384
	ds_read_b128 v[144:147], v180 offset:24576
	ds_read_b128 v[220:223], v181 offset:16384
	ds_read_b128 v[224:227], v181 offset:24576
	ds_read_b128 v[232:235], v182 offset:16384
	s_waitcnt lgkmcnt(6)
	s_add_u32 m0, s28, 0x1d000
	v_mfma_f32_32x32x16_bf16 v[188:203], v[132:135], v[116:119], v[2:17]
	global_load_lds_dwordx4 v172, s[8:9]
	ds_read_b128 v[236:239], v182 offset:24576
	v_exp_f32_e32 v84, v84
	v_exp_f32_e32 v85, v85
	v_exp_f32_e32 v86, v86
	v_exp_f32_e32 v87, v87
	v_exp_f32_e32 v88, v88
	v_add_f32_e32 v252, v84, v86
	v_add_f32_e32 v253, v85, v87
	v_exp_f32_e32 v89, v89
	s_waitcnt lgkmcnt(6)
	s_add_u32 m0, s29, 0x8000
	v_mfma_f32_32x32x16_bf16 v[204:219], v[136:139], v[116:119], v[2:17]
	global_load_lds_dwordx4 v174, s[8:9]
	ds_read_b64_tr_b16 v[132:133], v228 offset:0
	ds_read_b64_tr_b16 v[134:135], v228 offset:2048
	v_cvt_pk_bf16_f32 v84, v84, v85
	v_cvt_pk_bf16_f32 v85, v86, v87
	v_exp_f32_e32 v90, v90
	v_exp_f32_e32 v91, v91
	v_add_f32_e32 v252, v252, v88
	v_add_f32_e32 v253, v253, v89
	v_add_f32_e32 v252, v252, v90
	v_add_f32_e32 v253, v253, v91
	v_cvt_pk_bf16_f32 v86, v88, v89
	v_cvt_pk_bf16_f32 v87, v90, v91
	v_exp_f32_e32 v92, v92
	s_waitcnt lgkmcnt(7)
	s_add_u32 m0, s28, 0x1f000
	v_mfma_f32_32x32x16_bf16 v[188:203], v[140:143], v[120:123], v[188:203]
	global_load_lds_dwordx4 v173, s[8:9]
	ds_read_b64_tr_b16 v[136:137], v229 offset:0
	ds_read_b64_tr_b16 v[138:139], v229 offset:2048
	v_exp_f32_e32 v93, v93
	v_exp_f32_e32 v94, v94
	v_exp_f32_e32 v95, v95
	v_add_f32_e32 v252, v252, v92
	v_add_f32_e32 v253, v253, v93
	v_add_f32_e32 v252, v252, v94
	v_add_f32_e32 v253, v253, v95
	v_exp_f32_e32 v96, v96
	s_waitcnt lgkmcnt(8)
	s_add_u32 m0, s29, 0xa000
	v_mfma_f32_32x32x16_bf16 v[204:219], v[144:147], v[120:123], v[204:219]
	global_load_lds_dwordx4 v175, s[8:9]
	ds_read_b64_tr_b16 v[140:141], v230 offset:0
	ds_read_b64_tr_b16 v[142:143], v230 offset:2048
	v_exp_f32_e32 v97, v97
	v_cvt_pk_bf16_f32 v88, v92, v93
	v_cvt_pk_bf16_f32 v89, v94, v95
	v_exp_f32_e32 v98, v98
	v_exp_f32_e32 v99, v99
	v_add_f32_e32 v252, v252, v96
	v_add_f32_e32 v253, v253, v97
	v_add_f32_e32 v252, v252, v98
	v_add_f32_e32 v253, v253, v99
	v_cvt_pk_bf16_f32 v90, v96, v97
	v_cvt_pk_bf16_f32 v91, v98, v99
	s_waitcnt lgkmcnt(9)
	v_mfma_f32_32x32x16_bf16 v[188:203], v[220:223], v[124:127], v[188:203]
	ds_read_b64_tr_b16 v[144:145], v231 offset:0
	ds_read_b64_tr_b16 v[146:147], v231 offset:2048
	v_exp_f32_e32 v100, v100
	v_exp_f32_e32 v101, v101
	v_exp_f32_e32 v102, v102
	v_exp_f32_e32 v103, v103
	v_add_f32_e32 v252, v252, v100
	v_add_f32_e32 v253, v253, v101
	v_add_f32_e32 v252, v252, v102
	v_add_f32_e32 v253, v253, v103
	v_exp_f32_e32 v104, v104
	s_waitcnt lgkmcnt(10)
	v_mfma_f32_32x32x16_bf16 v[204:219], v[224:227], v[124:127], v[204:219]
	ds_read_b64_tr_b16 v[220:221], v228 offset:4096
	ds_read_b64_tr_b16 v[222:223], v228 offset:6144
	v_exp_f32_e32 v105, v105
	v_cvt_pk_bf16_f32 v100, v100, v101
	v_cvt_pk_bf16_f32 v101, v102, v103
	v_exp_f32_e32 v106, v106
	v_exp_f32_e32 v107, v107
	v_add_f32_e32 v252, v252, v104
	v_add_f32_e32 v253, v253, v105
	v_add_f32_e32 v252, v252, v106
	v_add_f32_e32 v253, v253, v107
	v_cvt_pk_bf16_f32 v102, v104, v105
	v_cvt_pk_bf16_f32 v103, v106, v107
	s_waitcnt lgkmcnt(11)
	v_mfma_f32_32x32x16_bf16 v[188:203], v[232:235], v[128:131], v[188:203]
	ds_read_b64_tr_b16 v[224:225], v229 offset:4096
	ds_read_b64_tr_b16 v[226:227], v229 offset:6144
	v_exp_f32_e32 v108, v108
	v_exp_f32_e32 v109, v109
	v_exp_f32_e32 v110, v110
	v_exp_f32_e32 v111, v111
	v_add_f32_e32 v252, v252, v108
	v_add_f32_e32 v253, v253, v109
	v_add_f32_e32 v252, v252, v110
	v_add_f32_e32 v253, v253, v111
	v_exp_f32_e32 v112, v112
	s_waitcnt lgkmcnt(12)
	v_mfma_f32_32x32x16_bf16 v[204:219], v[236:239], v[128:131], v[204:219]
	ds_read_b64_tr_b16 v[232:233], v230 offset:4096
	ds_read_b64_tr_b16 v[234:235], v230 offset:6144
	v_exp_f32_e32 v113, v113
	v_cvt_pk_bf16_f32 v104, v108, v109
	v_cvt_pk_bf16_f32 v105, v110, v111
	v_exp_f32_e32 v114, v114
	v_exp_f32_e32 v115, v115
	v_add_f32_e32 v252, v252, v112
	v_add_f32_e32 v253, v253, v113
	v_add_f32_e32 v252, v252, v114
	v_add_f32_e32 v253, v253, v115
	v_cvt_pk_bf16_f32 v106, v112, v113
	v_cvt_pk_bf16_f32 v107, v114, v115
	v_max_f32_e32 v251, v252, v253
	v_cmp_nge_f32_e32 vcc, 0x45800000, v251
	s_cbranch_vccnz .LatA_recs_h0
; #define VREADS1(arr, d_) do { const unsigned ad_ = vbase ^ (unsigned)((d_) << 6); __builtin_amdgcn_sched_barrier(0); \
;         _Pragma("unroll") for (int ks_ = 0; ks_ < 4; ++ks_) { VTR(arr[ks_ * 2], ad_, ks_ * 4096); VTR(arr[ks_ * 2 + 1], ad_, ks_ * 4096 + 2048); } __builtin_amdgcn_sched_barrier(0); } while (0)
; #define PV1(arr, d_) do { _Pragma("unroll") for (int ks_ = 0; ks_ < 4; ++ks_) { const s16x4 lo_ = arr[ks_ * 2], hh_ = arr[ks_ * 2 + 1]; \
;         const bf16x8 bv_ = (bf16x8){lo_[0], lo_[1], lo_[2], lo_[3], hh_[0], hh_[1], hh_[2], hh_[3]}; \
;         O[d_] = __builtin_amdgcn_mfma_f32_32x32x16_bf16(pa[ks_], bv_, O[d_], 0, 0, 0); } __builtin_amdgcn_sched_barrier(0); } while (0)
; #define LGKM0() do { __builtin_amdgcn_sched_barrier(0); asm volatile("s_waitcnt lgkmcnt(0)" ::: "memory"); __builtin_amdgcn_sched_barrier(0); } while (0)
; __device__ __forceinline__ void attn_unit(LAS unsigned char* lds, const bf16_t* Z, bf16_t* A2, const float* tabg, int seq_base, int S, int h, int qb, float lam) {
;     ...
;         for (int r = 0; r < 16; r += 2) { ls2 += (f32x2){p0[r], p0[r + 1]}; ls2 += (f32x2){p1[r], p1[r + 1]}; }
;         bf16x8 pa[4]; pa[0] = pack8(p0, 0); pa[1] = pack8(p0, 8); pa[2] = pack8(p1, 0); pa[3] = pack8(p1, 8);
;         LGKM0(); VREADS1(vb, 1); PV1(va, 0); LGKM0(); VREADS1(va, 2); PV1(vb, 1); LGKM0(); VREADS1(vb, 3); PV1(va, 2); LGKM0(); PV1(vb, 3);
;     ...
;         if (t + 2 < NT) asm volatile("s_waitcnt vmcnt(4) lgkmcnt(0)" ::: "memory"); else asm volatile("s_waitcnt vmcnt(0) lgkmcnt(0)" ::: "memory");
;         __builtin_amdgcn_s_barrier(); asm volatile("" ::: "memory");
;         bc = (bc == NST - 1) ? 0 : bc + 1; bn = (bn == NST - 1) ? 0 : bn + 1;
.LatA_recret_h0:
	v_add_f32_e32 v150, v150, v252
	v_add_f32_e32 v151, v151, v253
	s_add_u32 s8, s8, 0x40000
	s_addc_u32 s9, s9, 0
	s_waitcnt vmcnt(4)
	s_barrier
	s_sub_u32 s10, s10, 1
	s_cbranch_scc1 .LatA_evs_h1
; __device__ __forceinline__ void attn_unit(LAS unsigned char* lds, const bf16_t* Z, bf16_t* A2, const float* tabg, int seq_base, int S, int h, int qb, float lam) {
;     ...
;         {
;             bf16x8 kf[8];
; #pragma unroll
;             for (int ds = 0; ds < 4; ++ds) { kf[2 * ds] = *(const LAS bf16x8*)(Kt + (kfo ^ (unsigned)(ds << 5))); kf[2 * ds + 1] = *(const LAS bf16x8*)(Kt + 32 * 256 + (kfo ^ (unsigned)(ds << 5))); }
;             __builtin_amdgcn_sched_barrier(0);
;             p0 = __builtin_amdgcn_mfma_f32_32x32x16_bf16(kf[0], qf[0], cblk, 0, 0, 0);
;             p1 = __builtin_amdgcn_mfma_f32_32x32x16_bf16(kf[1], qf[0], cblk, 0, 0, 0);
; #pragma unroll
;             for (int ds = 1; ds < 4; ++ds) {
;                 p0 = __builtin_amdgcn_mfma_f32_32x32x16_bf16(kf[2 * ds], qf[ds], p0, 0, 0, 0);
;                 p1 = __builtin_amdgcn_mfma_f32_32x32x16_bf16(kf[2 * ds + 1], qf[ds], p1, 0, 0, 0);
;             }
;         }
;     ...
;         const unsigned vbase = (unsigned)(size_t)Vt + vfo;
;         s16x4 va[8], vb[8];
;         VREADS1(va, 0);
;         if (near) {
;             const LAS float* tp = tab + (kv0 + 4 * hi - (qlo + r32) + 224);
; #pragma unroll
;             for (int r = 0; r < 16; ++r) { p0[r] += tp[(r & 3) + 8 * (r >> 2)]; p1[r] += tp[32 + (r & 3) + 8 * (r >> 2)]; }
;         }
;         float mx = max2f(max16f(p0), max16f(p1));
;         const bool first = (t == 0);
;         if (first || __any(mx > THR)) {
;             { auto rr = __builtin_amdgcn_permlane32_swap(__float_as_uint(mx), __float_as_uint(mx), false, false); mx = max2f(__uint_as_float(rr[0]), __uint_as_float(rr[1])); }
;             const float delta = first ? mx : fmaxf(mx, 0.f);
;             const float alpha = first ? 1.0f : __builtin_amdgcn_exp2f(-delta);
;             mu += delta; ls2 *= alpha;
;             if (!first) {
;                 asm volatile("" ::: "memory");
;                 scr[r32] = alpha;
;                 asm volatile("s_waitcnt lgkmcnt(0)" ::: "memory");
; #pragma unroll
;                 for (int g = 0; g < 4; ++g) { const f32x4 a4 = *(const LAS f32x4*)(scr + 8 * g + 4 * hi);
; #pragma unroll
;                     for (int d = 0; d < 4; ++d) { O[d][4 * g + 0] *= a4[0]; O[d][4 * g + 1] *= a4[1]; O[d][4 * g + 2] *= a4[2]; O[d][4 * g + 3] *= a4[3]; } }
;                 asm volatile("s_waitcnt lgkmcnt(0)" ::: "memory");
;             }
; #pragma unroll
.LatA_evret_h1:
	s_waitcnt lgkmcnt(12)
	v_mfma_f32_32x32x16_bf16 v[20:35], v[84:87], v[132:135], v[20:35]
	ds_read_b64_tr_b16 v[236:237], v231 offset:4096
	ds_read_b64_tr_b16 v[238:239], v231 offset:6144
	v_exp_f32_e32 v188, v188
	v_exp_f32_e32 v189, v189
	s_waitcnt lgkmcnt(12)
	v_mfma_f32_32x32x16_bf16 v[36:51], v[84:87], v[136:139], v[36:51]
	ds_read_b64_tr_b16 v[132:133], v228 offset:8192
	ds_read_b64_tr_b16 v[134:135], v228 offset:10240
	v_exp_f32_e32 v190, v190
	v_exp_f32_e32 v191, v191
	s_waitcnt lgkmcnt(12)
	v_mfma_f32_32x32x16_bf16 v[52:67], v[84:87], v[140:143], v[52:67]
	ds_read_b64_tr_b16 v[136:137], v229 offset:8192
	ds_read_b64_tr_b16 v[138:139], v229 offset:10240
	v_exp_f32_e32 v192, v192
	v_add_f32_e32 v252, v188, v190
	v_add_f32_e32 v253, v189, v191
	v_exp_f32_e32 v193, v193
	s_waitcnt lgkmcnt(12)
	s_mov_b32 m0, s28
	v_mfma_f32_32x32x16_bf16 v[68:83], v[84:87], v[144:147], v[68:83]
	global_load_lds_dwordx4 v172, s[8:9]
	ds_read_b64_tr_b16 v[140:141], v230 offset:8192
	ds_read_b64_tr_b16 v[142:143], v230 offset:10240
	v_cvt_pk_bf16_f32 v188, v188, v189
	v_cvt_pk_bf16_f32 v189, v190, v191
	v_exp_f32_e32 v194, v194
	s_waitcnt lgkmcnt(12)
	v_mfma_f32_32x32x16_bf16 v[20:35], v[88:91], v[220:223], v[20:35]
	ds_read_b64_tr_b16 v[144:145], v231 offset:8192
	ds_read_b64_tr_b16 v[146:147], v231 offset:10240
	v_exp_f32_e32 v195, v195
	v_add_f32_e32 v252, v252, v192
	v_add_f32_e32 v253, v253, v193
	v_add_f32_e32 v252, v252, v194
	s_waitcnt lgkmcnt(12)
	v_mfma_f32_32x32x16_bf16 v[36:51], v[88:91], v[224:227], v[36:51]
	ds_read_b64_tr_b16 v[220:221], v228 offset:12288
	ds_read_b64_tr_b16 v[222:223], v228 offset:14336
	v_add_f32_e32 v253, v253, v195
	v_cvt_pk_bf16_f32 v190, v192, v193
	v_cvt_pk_bf16_f32 v191, v194, v195
	v_exp_f32_e32 v196, v196
	s_waitcnt lgkmcnt(12)
	v_mfma_f32_32x32x16_bf16 v[52:67], v[88:91], v[232:235], v[52:67]
	ds_read_b64_tr_b16 v[224:225], v229 offset:12288
	ds_read_b64_tr_b16 v[226:227], v229 offset:14336
	v_exp_f32_e32 v197, v197
	v_exp_f32_e32 v198, v198
	s_waitcnt lgkmcnt(12)
	s_add_u32 m0, s29, 0xd000
	v_mfma_f32_32x32x16_bf16 v[68:83], v[88:91], v[236:239], v[68:83]
	global_load_lds_dwordx4 v174, s[8:9]
	ds_read_b64_tr_b16 v[232:233], v230 offset:12288
	ds_read_b64_tr_b16 v[234:235], v230 offset:14336
	v_exp_f32_e32 v199, v199
	v_add_f32_e32 v252, v252, v196
	v_add_f32_e32 v253, v253, v197
	v_add_f32_e32 v252, v252, v198
	s_waitcnt lgkmcnt(12)
	v_mfma_f32_32x32x16_bf16 v[20:35], v[100:103], v[132:135], v[20:35]
	ds_read_b64_tr_b16 v[236:237], v231 offset:12288
	ds_read_b64_tr_b16 v[238:239], v231 offset:14336
	v_add_f32_e32 v253, v253, v199
	v_exp_f32_e32 v200, v200
	s_waitcnt lgkmcnt(12)
	v_mfma_f32_32x32x16_bf16 v[36:51], v[100:103], v[136:139], v[36:51]
	ds_read_b128 v[132:135], v19 offset:32768
	v_exp_f32_e32 v201, v201
	v_cvt_pk_bf16_f32 v192, v196, v197
	v_cvt_pk_bf16_f32 v193, v198, v199
	v_exp_f32_e32 v202, v202
	s_waitcnt lgkmcnt(11)
	v_mfma_f32_32x32x16_bf16 v[52:67], v[100:103], v[140:143], v[52:67]
	ds_read_b128 v[136:139], v19 offset:40960
	v_exp_f32_e32 v203, v203
	v_add_f32_e32 v252, v252, v200
	v_add_f32_e32 v253, v253, v201
	s_waitcnt lgkmcnt(10)
	s_add_u32 m0, s28, 0x2000
	v_mfma_f32_32x32x16_bf16 v[68:83], v[100:103], v[144:147], v[68:83]
	global_load_lds_dwordx4 v173, s[8:9]
	ds_read_b128 v[140:143], v180 offset:32768
	v_add_f32_e32 v252, v252, v202
	v_add_f32_e32 v253, v253, v203
	v_cvt_pk_bf16_f32 v194, v200, v201
	v_cvt_pk_bf16_f32 v195, v202, v203
	s_waitcnt lgkmcnt(9)
	v_mfma_f32_32x32x16_bf16 v[20:35], v[104:107], v[220:223], v[20:35]
	ds_read_b128 v[144:147], v180 offset:40960
	v_exp_f32_e32 v204, v204
	v_exp_f32_e32 v205, v205
	v_exp_f32_e32 v206, v206
	s_waitcnt lgkmcnt(8)
	v_mfma_f32_32x32x16_bf16 v[36:51], v[104:107], v[224:227], v[36:51]
	ds_read_b128 v[220:223], v181 offset:32768
	v_exp_f32_e32 v207, v207
	v_add_f32_e32 v252, v252, v204
	v_add_f32_e32 v253, v253, v205
	s_waitcnt lgkmcnt(7)
	v_mfma_f32_32x32x16_bf16 v[52:67], v[104:107], v[232:235], v[52:67]
	ds_read_b128 v[224:227], v181 offset:40960
	v_add_f32_e32 v252, v252, v206
	v_add_f32_e32 v253, v253, v207
	v_exp_f32_e32 v208, v208
	s_waitcnt lgkmcnt(6)
	s_add_u32 m0, s29, 0xf000
	v_mfma_f32_32x32x16_bf16 v[68:83], v[104:107], v[236:239], v[68:83]
	global_load_lds_dwordx4 v175, s[8:9]
	ds_read_b128 v[232:235], v182 offset:32768
	v_exp_f32_e32 v209, v209
	v_cvt_pk_bf16_f32 v204, v204, v205
	v_cvt_pk_bf16_f32 v205, v206, v207
	s_waitcnt lgkmcnt(6)
	v_mfma_f32_32x32x16_bf16 v[84:99], v[132:135], v[116:119], v[2:17]
	ds_read_b128 v[236:239], v182 offset:40960
	v_exp_f32_e32 v210, v210
	v_exp_f32_e32 v211, v211
	v_add_f32_e32 v252, v252, v208
	v_add_f32_e32 v253, v253, v209
	s_waitcnt lgkmcnt(6)
	v_mfma_f32_32x32x16_bf16 v[100:115], v[136:139], v[116:119], v[2:17]
	ds_read_b64_tr_b16 v[132:133], v228 offset:16384
	ds_read_b64_tr_b16 v[134:135], v228 offset:18432
	v_add_f32_e32 v252, v252, v210
	v_add_f32_e32 v253, v253, v211
	v_cvt_pk_bf16_f32 v206, v208, v209
	v_cvt_pk_bf16_f32 v207, v210, v211
	s_waitcnt lgkmcnt(7)
	v_mfma_f32_32x32x16_bf16 v[84:99], v[140:143], v[120:123], v[84:99]
	ds_read_b64_tr_b16 v[136:137], v229 offset:16384
	ds_read_b64_tr_b16 v[138:139], v229 offset:18432
	v_exp_f32_e32 v212, v212
	v_exp_f32_e32 v213, v213
	s_waitcnt lgkmcnt(8)
	v_mfma_f32_32x32x16_bf16 v[100:115], v[144:147], v[120:123], v[100:115]
	ds_read_b64_tr_b16 v[140:141], v230 offset:16384
	ds_read_b64_tr_b16 v[142:143], v230 offset:18432
	v_exp_f32_e32 v214, v214
	v_exp_f32_e32 v215, v215
	v_add_f32_e32 v252, v252, v212
	v_add_f32_e32 v253, v253, v213
	s_waitcnt lgkmcnt(9)
	v_mfma_f32_32x32x16_bf16 v[84:99], v[220:223], v[124:127], v[84:99]
	ds_read_b64_tr_b16 v[144:145], v231 offset:16384
	ds_read_b64_tr_b16 v[146:147], v231 offset:18432
	v_add_f32_e32 v252, v252, v214
	v_add_f32_e32 v253, v253, v215
	v_exp_f32_e32 v216, v216
	s_waitcnt lgkmcnt(10)
	v_mfma_f32_32x32x16_bf16 v[100:115], v[224:227], v[124:127], v[100:115]
	ds_read_b64_tr_b16 v[220:221], v228 offset:20480
	ds_read_b64_tr_b16 v[222:223], v228 offset:22528
	v_exp_f32_e32 v217, v217
	v_cvt_pk_bf16_f32 v208, v212, v213
	v_cvt_pk_bf16_f32 v209, v214, v215
	s_waitcnt lgkmcnt(11)
	v_mfma_f32_32x32x16_bf16 v[84:99], v[232:235], v[128:131], v[84:99]
	ds_read_b64_tr_b16 v[224:225], v229 offset:20480
	ds_read_b64_tr_b16 v[226:227], v229 offset:22528
	v_exp_f32_e32 v218, v218
	v_exp_f32_e32 v219, v219
	v_add_f32_e32 v252, v252, v216
	s_waitcnt lgkmcnt(12)
	v_mfma_f32_32x32x16_bf16 v[100:115], v[236:239], v[128:131], v[100:115]
	ds_read_b64_tr_b16 v[232:233], v230 offset:20480
	ds_read_b64_tr_b16 v[234:235], v230 offset:22528
	v_add_f32_e32 v253, v253, v217
	v_add_f32_e32 v252, v252, v218
	v_add_f32_e32 v253, v253, v219
	v_cvt_pk_bf16_f32 v210, v216, v217
	v_cvt_pk_bf16_f32 v211, v218, v219
	v_max_f32_e32 v251, v252, v253
	v_cmp_nge_f32_e32 vcc, 0x45800000, v251
	s_cbranch_vccnz .LatA_recs_h1

; __device__ __forceinline__ void attn_unit(LAS unsigned char* lds, const bf16_t* Z, bf16_t* A2, const float* tabg, int seq_base, int S, int h, int qb, float lam) {
;     ...
;         {
;             bf16x8 kf[8];
; #pragma unroll
;             for (int ds = 0; ds < 4; ++ds) { kf[2 * ds] = *(const LAS bf16x8*)(Kt + (kfo ^ (unsigned)(ds << 5))); kf[2 * ds + 1] = *(const LAS bf16x8*)(Kt + 32 * 256 + (kfo ^ (unsigned)(ds << 5))); }
;             __builtin_amdgcn_sched_barrier(0);
;             p0 = __builtin_amdgcn_mfma_f32_32x32x16_bf16(kf[0], qf[0], cblk, 0, 0, 0);
;             p1 = __builtin_amdgcn_mfma_f32_32x32x16_bf16(kf[1], qf[0], cblk, 0, 0, 0);
; #pragma unroll
;             for (int ds = 1; ds < 4; ++ds) {
;                 p0 = __builtin_amdgcn_mfma_f32_32x32x16_bf16(kf[2 * ds], qf[ds], p0, 0, 0, 0);
;                 p1 = __builtin_amdgcn_mfma_f32_32x32x16_bf16(kf[2 * ds + 1], qf[ds], p1, 0, 0, 0);
;             }
;         }
;     ...
;         const unsigned vbase = (unsigned)(size_t)Vt + vfo;
;         s16x4 va[8], vb[8];
;         VREADS1(va, 0);
;         if (near) {
;             const LAS float* tp = tab + (kv0 + 4 * hi - (qlo + r32) + 224);
; #pragma unroll
;             for (int r = 0; r < 16; ++r) { p0[r] += tp[(r & 3) + 8 * (r >> 2)]; p1[r] += tp[32 + (r & 3) + 8 * (r >> 2)]; }
;         }
;         float mx = max2f(max16f(p0), max16f(p1));
;         const bool first = (t == 0);
;         if (first || __any(mx > THR)) {
;             { auto rr = __builtin_amdgcn_permlane32_swap(__float_as_uint(mx), __float_as_uint(mx), false, false); mx = max2f(__uint_as_float(rr[0]), __uint_as_float(rr[1])); }
;             const float delta = first ? mx : fmaxf(mx, 0.f);
;             const float alpha = first ? 1.0f : __builtin_amdgcn_exp2f(-delta);
;             mu += delta; ls2 *= alpha;
;             if (!first) {
;                 asm volatile("" ::: "memory");
;                 scr[r32] = alpha;
;                 asm volatile("s_waitcnt lgkmcnt(0)" ::: "memory");
; #pragma unroll
;                 for (int g = 0; g < 4; ++g) { const f32x4 a4 = *(const LAS f32x4*)(scr + 8 * g + 4 * hi);
; #pragma unroll
;                     for (int d = 0; d < 4; ++d) { O[d][4 * g + 0] *= a4[0]; O[d][4 * g + 1] *= a4[1]; O[d][4 * g + 2] *= a4[2]; O[d][4 * g + 3] *= a4[3]; } }
;                 asm volatile("s_waitcnt lgkmcnt(0)" ::: "memory");
;             }
; #pragma unroll
.LatA_evret_h2:
	s_waitcnt lgkmcnt(12)
	v_mfma_f32_32x32x16_bf16 v[20:35], v[188:191], v[132:135], v[20:35]
	ds_read_b64_tr_b16 v[236:237], v231 offset:20480
	ds_read_b64_tr_b16 v[238:239], v231 offset:22528
	v_exp_f32_e32 v84, v84
	v_exp_f32_e32 v85, v85
	s_waitcnt lgkmcnt(12)
	v_mfma_f32_32x32x16_bf16 v[36:51], v[188:191], v[136:139], v[36:51]
	ds_read_b64_tr_b16 v[132:133], v228 offset:24576
	ds_read_b64_tr_b16 v[134:135], v228 offset:26624
	v_exp_f32_e32 v86, v86
	v_exp_f32_e32 v87, v87
	s_waitcnt lgkmcnt(12)
	v_mfma_f32_32x32x16_bf16 v[52:67], v[188:191], v[140:143], v[52:67]
	ds_read_b64_tr_b16 v[136:137], v229 offset:24576
	ds_read_b64_tr_b16 v[138:139], v229 offset:26624
	v_exp_f32_e32 v88, v88
	v_add_f32_e32 v252, v84, v86
	v_add_f32_e32 v253, v85, v87
	v_exp_f32_e32 v89, v89
	s_waitcnt lgkmcnt(12)
	s_add_u32 m0, s28, 0x4000
	v_mfma_f32_32x32x16_bf16 v[68:83], v[188:191], v[144:147], v[68:83]
	global_load_lds_dwordx4 v172, s[8:9]
	ds_read_b64_tr_b16 v[140:141], v230 offset:24576
	ds_read_b64_tr_b16 v[142:143], v230 offset:26624
	v_cvt_pk_bf16_f32 v84, v84, v85
	v_cvt_pk_bf16_f32 v85, v86, v87
	v_exp_f32_e32 v90, v90
	s_waitcnt lgkmcnt(12)
	v_mfma_f32_32x32x16_bf16 v[20:35], v[192:195], v[220:223], v[20:35]
	ds_read_b64_tr_b16 v[144:145], v231 offset:24576
	ds_read_b64_tr_b16 v[146:147], v231 offset:26624
	v_exp_f32_e32 v91, v91
	v_add_f32_e32 v252, v252, v88
	v_add_f32_e32 v253, v253, v89
	v_add_f32_e32 v252, v252, v90
	s_waitcnt lgkmcnt(12)
	v_mfma_f32_32x32x16_bf16 v[36:51], v[192:195], v[224:227], v[36:51]
	ds_read_b64_tr_b16 v[220:221], v228 offset:28672
	ds_read_b64_tr_b16 v[222:223], v228 offset:30720
	v_add_f32_e32 v253, v253, v91
	v_cvt_pk_bf16_f32 v86, v88, v89
	v_cvt_pk_bf16_f32 v87, v90, v91
	v_exp_f32_e32 v92, v92
	s_waitcnt lgkmcnt(12)
	v_mfma_f32_32x32x16_bf16 v[52:67], v[192:195], v[232:235], v[52:67]
	ds_read_b64_tr_b16 v[224:225], v229 offset:28672
	ds_read_b64_tr_b16 v[226:227], v229 offset:30720
	v_exp_f32_e32 v93, v93
	v_exp_f32_e32 v94, v94
	s_waitcnt lgkmcnt(12)
	s_mov_b32 m0, s29
	v_mfma_f32_32x32x16_bf16 v[68:83], v[192:195], v[236:239], v[68:83]
	global_load_lds_dwordx4 v174, s[8:9]
	ds_read_b64_tr_b16 v[232:233], v230 offset:28672
	ds_read_b64_tr_b16 v[234:235], v230 offset:30720
	v_exp_f32_e32 v95, v95
	v_add_f32_e32 v252, v252, v92
	v_add_f32_e32 v253, v253, v93
	v_add_f32_e32 v252, v252, v94
	s_waitcnt lgkmcnt(12)
	v_mfma_f32_32x32x16_bf16 v[20:35], v[204:207], v[132:135], v[20:35]
	ds_read_b64_tr_b16 v[236:237], v231 offset:28672
	ds_read_b64_tr_b16 v[238:239], v231 offset:30720
	v_add_f32_e32 v253, v253, v95
	v_exp_f32_e32 v96, v96
	s_waitcnt lgkmcnt(12)
	v_mfma_f32_32x32x16_bf16 v[36:51], v[204:207], v[136:139], v[36:51]
	ds_read_b128 v[132:135], v164
	v_exp_f32_e32 v97, v97
	v_cvt_pk_bf16_f32 v88, v92, v93
	v_cvt_pk_bf16_f32 v89, v94, v95
	v_exp_f32_e32 v98, v98
	s_waitcnt lgkmcnt(11)
	v_mfma_f32_32x32x16_bf16 v[52:67], v[204:207], v[140:143], v[52:67]
	ds_read_b128 v[136:139], v164 offset:8192
	v_exp_f32_e32 v99, v99
	v_add_f32_e32 v252, v252, v96
	v_add_f32_e32 v253, v253, v97
	s_waitcnt lgkmcnt(10)
	s_add_u32 m0, s28, 0x6000
	v_mfma_f32_32x32x16_bf16 v[68:83], v[204:207], v[144:147], v[68:83]
	global_load_lds_dwordx4 v173, s[8:9]
	ds_read_b128 v[140:143], v165
	v_add_f32_e32 v252, v252, v98
	v_add_f32_e32 v253, v253, v99
	v_cvt_pk_bf16_f32 v90, v96, v97
	v_cvt_pk_bf16_f32 v91, v98, v99
	s_waitcnt lgkmcnt(9)
	v_mfma_f32_32x32x16_bf16 v[20:35], v[208:211], v[220:223], v[20:35]
	ds_read_b128 v[144:147], v165 offset:8192
	v_exp_f32_e32 v100, v100
	v_exp_f32_e32 v101, v101
	v_exp_f32_e32 v102, v102
	s_waitcnt lgkmcnt(8)
	v_mfma_f32_32x32x16_bf16 v[36:51], v[208:211], v[224:227], v[36:51]
	ds_read_b128 v[220:223], v166
	v_exp_f32_e32 v103, v103
	v_add_f32_e32 v252, v252, v100
	v_add_f32_e32 v253, v253, v101
	s_waitcnt lgkmcnt(7)
	v_mfma_f32_32x32x16_bf16 v[52:67], v[208:211], v[232:235], v[52:67]
	ds_read_b128 v[224:227], v166 offset:8192
	v_add_f32_e32 v252, v252, v102
	v_add_f32_e32 v253, v253, v103
	v_exp_f32_e32 v104, v104
	s_waitcnt lgkmcnt(6)
	s_add_u32 m0, s29, 0x2000
	v_mfma_f32_32x32x16_bf16 v[68:83], v[208:211], v[236:239], v[68:83]
	global_load_lds_dwordx4 v175, s[8:9]
	ds_read_b128 v[232:235], v167
	v_exp_f32_e32 v105, v105
	v_cvt_pk_bf16_f32 v100, v100, v101
	v_cvt_pk_bf16_f32 v101, v102, v103
	s_waitcnt lgkmcnt(6)
	v_mfma_f32_32x32x16_bf16 v[188:203], v[132:135], v[116:119], v[2:17]
	ds_read_b128 v[236:239], v167 offset:8192
	v_exp_f32_e32 v106, v106
	v_exp_f32_e32 v107, v107
	v_add_f32_e32 v252, v252, v104
	v_add_f32_e32 v253, v253, v105
	s_waitcnt lgkmcnt(6)
	v_mfma_f32_32x32x16_bf16 v[204:219], v[136:139], v[116:119], v[2:17]
	ds_read_b64_tr_b16 v[132:133], v228 offset:32768
	ds_read_b64_tr_b16 v[134:135], v228 offset:34816
	v_add_f32_e32 v252, v252, v106
	v_add_f32_e32 v253, v253, v107
	v_cvt_pk_bf16_f32 v102, v104, v105
	v_cvt_pk_bf16_f32 v103, v106, v107
	s_waitcnt lgkmcnt(7)
	v_mfma_f32_32x32x16_bf16 v[188:203], v[140:143], v[120:123], v[188:203]
	ds_read_b64_tr_b16 v[136:137], v229 offset:32768
	ds_read_b64_tr_b16 v[138:139], v229 offset:34816
	v_exp_f32_e32 v108, v108
	v_exp_f32_e32 v109, v109
	s_waitcnt lgkmcnt(8)
	v_mfma_f32_32x32x16_bf16 v[204:219], v[144:147], v[120:123], v[204:219]
	ds_read_b64_tr_b16 v[140:141], v230 offset:32768
	ds_read_b64_tr_b16 v[142:143], v230 offset:34816
	v_exp_f32_e32 v110, v110
	v_exp_f32_e32 v111, v111
	v_add_f32_e32 v252, v252, v108
	v_add_f32_e32 v253, v253, v109
	s_waitcnt lgkmcnt(9)
	v_mfma_f32_32x32x16_bf16 v[188:203], v[220:223], v[124:127], v[188:203]
	ds_read_b64_tr_b16 v[144:145], v231 offset:32768
	ds_read_b64_tr_b16 v[146:147], v231 offset:34816
	v_add_f32_e32 v252, v252, v110
	v_add_f32_e32 v253, v253, v111
	v_exp_f32_e32 v112, v112
	s_waitcnt lgkmcnt(10)
	v_mfma_f32_32x32x16_bf16 v[204:219], v[224:227], v[124:127], v[204:219]
	ds_read_b64_tr_b16 v[220:221], v228 offset:36864
	ds_read_b64_tr_b16 v[222:223], v228 offset:38912
	v_exp_f32_e32 v113, v113
	v_cvt_pk_bf16_f32 v104, v108, v109
	v_cvt_pk_bf16_f32 v105, v110, v111
	s_waitcnt lgkmcnt(11)
	v_mfma_f32_32x32x16_bf16 v[188:203], v[232:235], v[128:131], v[188:203]
	ds_read_b64_tr_b16 v[224:225], v229 offset:36864
	ds_read_b64_tr_b16 v[226:227], v229 offset:38912
	v_exp_f32_e32 v114, v114
	v_exp_f32_e32 v115, v115
	v_add_f32_e32 v252, v252, v112
	s_waitcnt lgkmcnt(12)
	v_mfma_f32_32x32x16_bf16 v[204:219], v[236:239], v[128:131], v[204:219]
	ds_read_b64_tr_b16 v[232:233], v230 offset:36864
	ds_read_b64_tr_b16 v[234:235], v230 offset:38912
	v_add_f32_e32 v253, v253, v113
	v_add_f32_e32 v252, v252, v114
	v_add_f32_e32 v253, v253, v115
	v_cvt_pk_bf16_f32 v106, v112, v113
	v_cvt_pk_bf16_f32 v107, v114, v115
	v_max_f32_e32 v251, v252, v253
	v_cmp_nge_f32_e32 vcc, 0x45800000, v251
	s_cbranch_vccnz .LatA_recs_h2

; __device__ __forceinline__ void attn_unit(LAS unsigned char* lds, const bf16_t* Z, bf16_t* A2, const float* tabg, int seq_base, int S, int h, int qb, float lam) {
;     ...
;         {
;             bf16x8 kf[8];
; #pragma unroll
;             for (int ds = 0; ds < 4; ++ds) { kf[2 * ds] = *(const LAS bf16x8*)(Kt + (kfo ^ (unsigned)(ds << 5))); kf[2 * ds + 1] = *(const LAS bf16x8*)(Kt + 32 * 256 + (kfo ^ (unsigned)(ds << 5))); }
;             __builtin_amdgcn_sched_barrier(0);
;             p0 = __builtin_amdgcn_mfma_f32_32x32x16_bf16(kf[0], qf[0], cblk, 0, 0, 0);
;             p1 = __builtin_amdgcn_mfma_f32_32x32x16_bf16(kf[1], qf[0], cblk, 0, 0, 0);
; #pragma unroll
;             for (int ds = 1; ds < 4; ++ds) {
;                 p0 = __builtin_amdgcn_mfma_f32_32x32x16_bf16(kf[2 * ds], qf[ds], p0, 0, 0, 0);
;                 p1 = __builtin_amdgcn_mfma_f32_32x32x16_bf16(kf[2 * ds + 1], qf[ds], p1, 0, 0, 0);
;             }
;         }
;     ...
;         const unsigned vbase = (unsigned)(size_t)Vt + vfo;
;         s16x4 va[8], vb[8];
;         VREADS1(va, 0);
;         if (near) {
;             const LAS float* tp = tab + (kv0 + 4 * hi - (qlo + r32) + 224);
; #pragma unroll
;             for (int r = 0; r < 16; ++r) { p0[r] += tp[(r & 3) + 8 * (r >> 2)]; p1[r] += tp[32 + (r & 3) + 8 * (r >> 2)]; }
;         }
;         float mx = max2f(max16f(p0), max16f(p1));
;         const bool first = (t == 0);
;         if (first || __any(mx > THR)) {
;             { auto rr = __builtin_amdgcn_permlane32_swap(__float_as_uint(mx), __float_as_uint(mx), false, false); mx = max2f(__uint_as_float(rr[0]), __uint_as_float(rr[1])); }
;             const float delta = first ? mx : fmaxf(mx, 0.f);
;             const float alpha = first ? 1.0f : __builtin_amdgcn_exp2f(-delta);
;             mu += delta; ls2 *= alpha;
;             if (!first) {
;                 asm volatile("" ::: "memory");
;                 scr[r32] = alpha;
;                 asm volatile("s_waitcnt lgkmcnt(0)" ::: "memory");
; #pragma unroll
;                 for (int g = 0; g < 4; ++g) { const f32x4 a4 = *(const LAS f32x4*)(scr + 8 * g + 4 * hi);
; #pragma unroll
;                     for (int d = 0; d < 4; ++d) { O[d][4 * g + 0] *= a4[0]; O[d][4 * g + 1] *= a4[1]; O[d][4 * g + 2] *= a4[2]; O[d][4 * g + 3] *= a4[3]; } }
;                 asm volatile("s_waitcnt lgkmcnt(0)" ::: "memory");
;             }
; #pragma unroll
.LatA_evret_h3:
	s_waitcnt lgkmcnt(12)
	v_mfma_f32_32x32x16_bf16 v[20:35], v[84:87], v[132:135], v[20:35]
	ds_read_b64_tr_b16 v[236:237], v231 offset:36864
	ds_read_b64_tr_b16 v[238:239], v231 offset:38912
	v_exp_f32_e32 v188, v188
	v_exp_f32_e32 v189, v189
	s_waitcnt lgkmcnt(12)
	v_mfma_f32_32x32x16_bf16 v[36:51], v[84:87], v[136:139], v[36:51]
	ds_read_b64_tr_b16 v[132:133], v228 offset:40960
	ds_read_b64_tr_b16 v[134:135], v228 offset:43008
	v_exp_f32_e32 v190, v190
	v_exp_f32_e32 v191, v191
	s_waitcnt lgkmcnt(12)
	v_mfma_f32_32x32x16_bf16 v[52:67], v[84:87], v[140:143], v[52:67]
	ds_read_b64_tr_b16 v[136:137], v229 offset:40960
	ds_read_b64_tr_b16 v[138:139], v229 offset:43008
	v_exp_f32_e32 v192, v192
	v_add_f32_e32 v252, v188, v190
	v_add_f32_e32 v253, v189, v191
	v_exp_f32_e32 v193, v193
	s_waitcnt lgkmcnt(12)
	s_add_u32 m0, s28, 0x8000
	v_mfma_f32_32x32x16_bf16 v[68:83], v[84:87], v[144:147], v[68:83]
	global_load_lds_dwordx4 v172, s[8:9]
	ds_read_b64_tr_b16 v[140:141], v230 offset:40960
	ds_read_b64_tr_b16 v[142:143], v230 offset:43008
	v_cvt_pk_bf16_f32 v188, v188, v189
	v_cvt_pk_bf16_f32 v189, v190, v191
	v_exp_f32_e32 v194, v194
	s_waitcnt lgkmcnt(12)
	v_mfma_f32_32x32x16_bf16 v[20:35], v[88:91], v[220:223], v[20:35]
	ds_read_b64_tr_b16 v[144:145], v231 offset:40960
	ds_read_b64_tr_b16 v[146:147], v231 offset:43008
	v_exp_f32_e32 v195, v195
	v_add_f32_e32 v252, v252, v192
	v_add_f32_e32 v253, v253, v193
	v_add_f32_e32 v252, v252, v194
	s_waitcnt lgkmcnt(12)
	v_mfma_f32_32x32x16_bf16 v[36:51], v[88:91], v[224:227], v[36:51]
	ds_read_b64_tr_b16 v[220:221], v228 offset:45056
	ds_read_b64_tr_b16 v[222:223], v228 offset:47104
	v_add_f32_e32 v253, v253, v195
	v_cvt_pk_bf16_f32 v190, v192, v193
	v_cvt_pk_bf16_f32 v191, v194, v195
	v_exp_f32_e32 v196, v196
	s_waitcnt lgkmcnt(12)
	v_mfma_f32_32x32x16_bf16 v[52:67], v[88:91], v[232:235], v[52:67]
	ds_read_b64_tr_b16 v[224:225], v229 offset:45056
	ds_read_b64_tr_b16 v[226:227], v229 offset:47104
	v_exp_f32_e32 v197, v197
	v_exp_f32_e32 v198, v198
	s_waitcnt lgkmcnt(12)
	s_add_u32 m0, s29, 0x4000
	v_mfma_f32_32x32x16_bf16 v[68:83], v[88:91], v[236:239], v[68:83]
	global_load_lds_dwordx4 v174, s[8:9]
	ds_read_b64_tr_b16 v[232:233], v230 offset:45056
	ds_read_b64_tr_b16 v[234:235], v230 offset:47104
	v_exp_f32_e32 v199, v199
	v_add_f32_e32 v252, v252, v196
	v_add_f32_e32 v253, v253, v197
	v_add_f32_e32 v252, v252, v198
	s_waitcnt lgkmcnt(12)
	v_mfma_f32_32x32x16_bf16 v[20:35], v[100:103], v[132:135], v[20:35]
	ds_read_b64_tr_b16 v[236:237], v231 offset:45056
	ds_read_b64_tr_b16 v[238:239], v231 offset:47104
	v_add_f32_e32 v253, v253, v199
	v_exp_f32_e32 v200, v200
	s_waitcnt lgkmcnt(12)
	v_mfma_f32_32x32x16_bf16 v[36:51], v[100:103], v[136:139], v[36:51]
	ds_read_b128 v[132:135], v19
	v_exp_f32_e32 v201, v201
	v_cvt_pk_bf16_f32 v192, v196, v197
	v_cvt_pk_bf16_f32 v193, v198, v199
	v_exp_f32_e32 v202, v202
	s_waitcnt lgkmcnt(11)
	v_mfma_f32_32x32x16_bf16 v[52:67], v[100:103], v[140:143], v[52:67]
	ds_read_b128 v[136:139], v19 offset:8192
	v_exp_f32_e32 v203, v203
	v_add_f32_e32 v252, v252, v200
	v_add_f32_e32 v253, v253, v201
	s_waitcnt lgkmcnt(10)
	s_add_u32 m0, s28, 0xa000
	v_mfma_f32_32x32x16_bf16 v[68:83], v[100:103], v[144:147], v[68:83]
	global_load_lds_dwordx4 v173, s[8:9]
	ds_read_b128 v[140:143], v180
	v_add_f32_e32 v252, v252, v202
	v_add_f32_e32 v253, v253, v203
	v_cvt_pk_bf16_f32 v194, v200, v201
	v_cvt_pk_bf16_f32 v195, v202, v203
	s_waitcnt lgkmcnt(9)
	v_mfma_f32_32x32x16_bf16 v[20:35], v[104:107], v[220:223], v[20:35]
	ds_read_b128 v[144:147], v180 offset:8192
	v_exp_f32_e32 v204, v204
	v_exp_f32_e32 v205, v205
	v_exp_f32_e32 v206, v206
	s_waitcnt lgkmcnt(8)
	v_mfma_f32_32x32x16_bf16 v[36:51], v[104:107], v[224:227], v[36:51]
	ds_read_b128 v[220:223], v181
	v_exp_f32_e32 v207, v207
	v_add_f32_e32 v252, v252, v204
	v_add_f32_e32 v253, v253, v205
	s_waitcnt lgkmcnt(7)
	v_mfma_f32_32x32x16_bf16 v[52:67], v[104:107], v[232:235], v[52:67]
	ds_read_b128 v[224:227], v181 offset:8192
	v_add_f32_e32 v252, v252, v206
	v_add_f32_e32 v253, v253, v207
	v_exp_f32_e32 v208, v208
	s_waitcnt lgkmcnt(6)
	s_add_u32 m0, s29, 0x6000
	v_mfma_f32_32x32x16_bf16 v[68:83], v[104:107], v[236:239], v[68:83]
	global_load_lds_dwordx4 v175, s[8:9]
	ds_read_b128 v[232:235], v182
	v_exp_f32_e32 v209, v209
	v_cvt_pk_bf16_f32 v204, v204, v205
	v_cvt_pk_bf16_f32 v205, v206, v207
	s_waitcnt lgkmcnt(6)
	v_mfma_f32_32x32x16_bf16 v[84:99], v[132:135], v[116:119], v[2:17]
	ds_read_b128 v[236:239], v182 offset:8192
	v_exp_f32_e32 v210, v210
	v_exp_f32_e32 v211, v211
	v_add_f32_e32 v252, v252, v208
	v_add_f32_e32 v253, v253, v209
	s_waitcnt lgkmcnt(6)
	v_mfma_f32_32x32x16_bf16 v[100:115], v[136:139], v[116:119], v[2:17]
	ds_read_b64_tr_b16 v[132:133], v168 offset:0
	ds_read_b64_tr_b16 v[134:135], v168 offset:2048
	v_add_f32_e32 v252, v252, v210
	v_add_f32_e32 v253, v253, v211
	v_cvt_pk_bf16_f32 v206, v208, v209
	v_cvt_pk_bf16_f32 v207, v210, v211
	s_waitcnt lgkmcnt(7)
	v_mfma_f32_32x32x16_bf16 v[84:99], v[140:143], v[120:123], v[84:99]
	ds_read_b64_tr_b16 v[136:137], v169 offset:0
	ds_read_b64_tr_b16 v[138:139], v169 offset:2048
	v_exp_f32_e32 v212, v212
	v_exp_f32_e32 v213, v213
	s_waitcnt lgkmcnt(8)
	v_mfma_f32_32x32x16_bf16 v[100:115], v[144:147], v[120:123], v[100:115]
	ds_read_b64_tr_b16 v[140:141], v170 offset:0
	ds_read_b64_tr_b16 v[142:143], v170 offset:2048
	v_exp_f32_e32 v214, v214
	v_exp_f32_e32 v215, v215
	v_add_f32_e32 v252, v252, v212
	v_add_f32_e32 v253, v253, v213
	s_waitcnt lgkmcnt(9)
	v_mfma_f32_32x32x16_bf16 v[84:99], v[220:223], v[124:127], v[84:99]
	ds_read_b64_tr_b16 v[144:145], v171 offset:0
	ds_read_b64_tr_b16 v[146:147], v171 offset:2048
	v_add_f32_e32 v252, v252, v214
	v_add_f32_e32 v253, v253, v215
	v_exp_f32_e32 v216, v216
	s_waitcnt lgkmcnt(10)
	v_mfma_f32_32x32x16_bf16 v[100:115], v[224:227], v[124:127], v[100:115]
	ds_read_b64_tr_b16 v[220:221], v168 offset:4096
	ds_read_b64_tr_b16 v[222:223], v168 offset:6144
	v_exp_f32_e32 v217, v217
	v_cvt_pk_bf16_f32 v208, v212, v213
	v_cvt_pk_bf16_f32 v209, v214, v215
	s_waitcnt lgkmcnt(11)
	v_mfma_f32_32x32x16_bf16 v[84:99], v[232:235], v[128:131], v[84:99]
	ds_read_b64_tr_b16 v[224:225], v169 offset:4096
	ds_read_b64_tr_b16 v[226:227], v169 offset:6144
	v_exp_f32_e32 v218, v218
	v_exp_f32_e32 v219, v219
	v_add_f32_e32 v252, v252, v216
	s_waitcnt lgkmcnt(12)
	v_mfma_f32_32x32x16_bf16 v[100:115], v[236:239], v[128:131], v[100:115]
	ds_read_b64_tr_b16 v[232:233], v170 offset:4096
	ds_read_b64_tr_b16 v[234:235], v170 offset:6144
	v_add_f32_e32 v253, v253, v217
	v_add_f32_e32 v252, v252, v218
	v_add_f32_e32 v253, v253, v219
	v_cvt_pk_bf16_f32 v210, v216, v217
	v_cvt_pk_bf16_f32 v211, v218, v219
	v_max_f32_e32 v251, v252, v253
	v_cmp_nge_f32_e32 vcc, 0x45800000, v251
	s_cbranch_vccnz .LatA_recs_h3
.LatA_recret_h3:
	v_add_f32_e32 v150, v150, v252
	v_add_f32_e32 v151, v151, v253
	s_add_u32 s8, s8, 0x40000
	s_addc_u32 s9, s9, 0
	s_waitcnt vmcnt(4)
	s_barrier
	s_movk_i32 s36, 30

; __device__ __forceinline__ void attn_unit(LAS unsigned char* lds, const bf16_t* Z, bf16_t* A2, const float* tabg, int seq_base, int S, int h, int qb, float lam) {
;     ...
;         {
;             bf16x8 kf[8];
; #pragma unroll
;             for (int ds = 0; ds < 4; ++ds) { kf[2 * ds] = *(const LAS bf16x8*)(Kt + (kfo ^ (unsigned)(ds << 5))); kf[2 * ds + 1] = *(const LAS bf16x8*)(Kt + 32 * 256 + (kfo ^ (unsigned)(ds << 5))); }
;             __builtin_amdgcn_sched_barrier(0);
;             p0 = __builtin_amdgcn_mfma_f32_32x32x16_bf16(kf[0], qf[0], cblk, 0, 0, 0);
;             p1 = __builtin_amdgcn_mfma_f32_32x32x16_bf16(kf[1], qf[0], cblk, 0, 0, 0);
; #pragma unroll
;             for (int ds = 1; ds < 4; ++ds) {
;                 p0 = __builtin_amdgcn_mfma_f32_32x32x16_bf16(kf[2 * ds], qf[ds], p0, 0, 0, 0);
;                 p1 = __builtin_amdgcn_mfma_f32_32x32x16_bf16(kf[2 * ds + 1], qf[ds], p1, 0, 0, 0);
;             }
;         }
;     ...
;         const unsigned vbase = (unsigned)(size_t)Vt + vfo;
;         s16x4 va[8], vb[8];
;         VREADS1(va, 0);
;         if (near) {
;             const LAS float* tp = tab + (kv0 + 4 * hi - (qlo + r32) + 224);
; #pragma unroll
;             for (int r = 0; r < 16; ++r) { p0[r] += tp[(r & 3) + 8 * (r >> 2)]; p1[r] += tp[32 + (r & 3) + 8 * (r >> 2)]; }
;         }
;         float mx = max2f(max16f(p0), max16f(p1));
;         const bool first = (t == 0);
;         if (first || __any(mx > THR)) {
;             { auto rr = __builtin_amdgcn_permlane32_swap(__float_as_uint(mx), __float_as_uint(mx), false, false); mx = max2f(__uint_as_float(rr[0]), __uint_as_float(rr[1])); }
;             const float delta = first ? mx : fmaxf(mx, 0.f);
;             const float alpha = first ? 1.0f : __builtin_amdgcn_exp2f(-delta);
;             mu += delta; ls2 *= alpha;
;             if (!first) {
;                 asm volatile("" ::: "memory");
;                 scr[r32] = alpha;
;                 asm volatile("s_waitcnt lgkmcnt(0)" ::: "memory");
; #pragma unroll
;                 for (int g = 0; g < 4; ++g) { const f32x4 a4 = *(const LAS f32x4*)(scr + 8 * g + 4 * hi);
; #pragma unroll
;                     for (int d = 0; d < 4; ++d) { O[d][4 * g + 0] *= a4[0]; O[d][4 * g + 1] *= a4[1]; O[d][4 * g + 2] *= a4[2]; O[d][4 * g + 3] *= a4[3]; } }
;                 asm volatile("s_waitcnt lgkmcnt(0)" ::: "memory");
;             }
; #pragma unroll
.LatA_evret_m0:
	s_waitcnt lgkmcnt(12)
	v_mfma_f32_32x32x16_bf16 v[20:35], v[188:191], v[132:135], v[20:35]
	ds_read_b64_tr_b16 v[236:237], v171 offset:4096
	ds_read_b64_tr_b16 v[238:239], v171 offset:6144
	v_exp_f32_e32 v84, v84
	v_exp_f32_e32 v85, v85
	s_waitcnt lgkmcnt(12)
	v_mfma_f32_32x32x16_bf16 v[36:51], v[188:191], v[136:139], v[36:51]
	ds_read_b64_tr_b16 v[132:133], v168 offset:8192
	ds_read_b64_tr_b16 v[134:135], v168 offset:10240
	v_exp_f32_e32 v86, v86
	v_exp_f32_e32 v87, v87
	s_waitcnt lgkmcnt(12)
	v_mfma_f32_32x32x16_bf16 v[52:67], v[188:191], v[140:143], v[52:67]
	ds_read_b64_tr_b16 v[136:137], v169 offset:8192
	ds_read_b64_tr_b16 v[138:139], v169 offset:10240
	v_exp_f32_e32 v88, v88
	v_add_f32_e32 v252, v84, v86
	v_add_f32_e32 v253, v85, v87
	v_exp_f32_e32 v89, v89
	s_waitcnt lgkmcnt(12)
	s_add_u32 m0, s28, 0x1d000
	v_mfma_f32_32x32x16_bf16 v[68:83], v[188:191], v[144:147], v[68:83]
	global_load_lds_dwordx4 v172, s[8:9]
	ds_read_b64_tr_b16 v[140:141], v170 offset:8192
	ds_read_b64_tr_b16 v[142:143], v170 offset:10240
	v_cvt_pk_bf16_f32 v84, v84, v85
	v_cvt_pk_bf16_f32 v85, v86, v87
	v_exp_f32_e32 v90, v90
	s_waitcnt lgkmcnt(12)
	v_mfma_f32_32x32x16_bf16 v[20:35], v[192:195], v[220:223], v[20:35]
	ds_read_b64_tr_b16 v[144:145], v171 offset:8192
	ds_read_b64_tr_b16 v[146:147], v171 offset:10240
	v_exp_f32_e32 v91, v91
	v_add_f32_e32 v252, v252, v88
	v_add_f32_e32 v253, v253, v89
	v_add_f32_e32 v252, v252, v90
	s_waitcnt lgkmcnt(12)
	v_mfma_f32_32x32x16_bf16 v[36:51], v[192:195], v[224:227], v[36:51]
	ds_read_b64_tr_b16 v[220:221], v168 offset:12288
	ds_read_b64_tr_b16 v[222:223], v168 offset:14336
	v_add_f32_e32 v253, v253, v91
	v_cvt_pk_bf16_f32 v86, v88, v89
	v_cvt_pk_bf16_f32 v87, v90, v91
	v_exp_f32_e32 v92, v92
	s_waitcnt lgkmcnt(12)
	v_mfma_f32_32x32x16_bf16 v[52:67], v[192:195], v[232:235], v[52:67]
	ds_read_b64_tr_b16 v[224:225], v169 offset:12288
	ds_read_b64_tr_b16 v[226:227], v169 offset:14336
	v_exp_f32_e32 v93, v93
	v_exp_f32_e32 v94, v94
	s_waitcnt lgkmcnt(12)
	s_add_u32 m0, s29, 0x8000
	v_mfma_f32_32x32x16_bf16 v[68:83], v[192:195], v[236:239], v[68:83]
	global_load_lds_dwordx4 v174, s[8:9]
	ds_read_b64_tr_b16 v[232:233], v170 offset:12288
	ds_read_b64_tr_b16 v[234:235], v170 offset:14336
	v_exp_f32_e32 v95, v95
	v_add_f32_e32 v252, v252, v92
	v_add_f32_e32 v253, v253, v93
	v_add_f32_e32 v252, v252, v94
	s_waitcnt lgkmcnt(12)
	v_mfma_f32_32x32x16_bf16 v[20:35], v[204:207], v[132:135], v[20:35]
	ds_read_b64_tr_b16 v[236:237], v171 offset:12288
	ds_read_b64_tr_b16 v[238:239], v171 offset:14336
	v_add_f32_e32 v253, v253, v95
	v_exp_f32_e32 v96, v96
	s_waitcnt lgkmcnt(12)
	v_mfma_f32_32x32x16_bf16 v[36:51], v[204:207], v[136:139], v[36:51]
	ds_read_b128 v[132:135], v19 offset:16384
	v_exp_f32_e32 v97, v97
	v_cvt_pk_bf16_f32 v88, v92, v93
	v_cvt_pk_bf16_f32 v89, v94, v95
	v_exp_f32_e32 v98, v98
	s_waitcnt lgkmcnt(11)
	v_mfma_f32_32x32x16_bf16 v[52:67], v[204:207], v[140:143], v[52:67]
	ds_read_b128 v[136:139], v19 offset:24576
	v_exp_f32_e32 v99, v99
	v_add_f32_e32 v252, v252, v96
	v_add_f32_e32 v253, v253, v97
	s_waitcnt lgkmcnt(10)
	s_add_u32 m0, s28, 0x1f000
	v_mfma_f32_32x32x16_bf16 v[68:83], v[204:207], v[144:147], v[68:83]
	global_load_lds_dwordx4 v173, s[8:9]
	ds_read_b128 v[140:143], v180 offset:16384
	v_add_f32_e32 v252, v252, v98
	v_add_f32_e32 v253, v253, v99
	v_cvt_pk_bf16_f32 v90, v96, v97
	v_cvt_pk_bf16_f32 v91, v98, v99
	s_waitcnt lgkmcnt(9)
	v_mfma_f32_32x32x16_bf16 v[20:35], v[208:211], v[220:223], v[20:35]
	ds_read_b128 v[144:147], v180 offset:24576
	v_exp_f32_e32 v100, v100
	v_exp_f32_e32 v101, v101
	v_exp_f32_e32 v102, v102
	s_waitcnt lgkmcnt(8)
	v_mfma_f32_32x32x16_bf16 v[36:51], v[208:211], v[224:227], v[36:51]
	ds_read_b128 v[220:223], v181 offset:16384
	v_exp_f32_e32 v103, v103
	v_add_f32_e32 v252, v252, v100
	v_add_f32_e32 v253, v253, v101
	s_waitcnt lgkmcnt(7)
	v_mfma_f32_32x32x16_bf16 v[52:67], v[208:211], v[232:235], v[52:67]
	ds_read_b128 v[224:227], v181 offset:24576
	v_add_f32_e32 v252, v252, v102
	v_add_f32_e32 v253, v253, v103
	v_exp_f32_e32 v104, v104
	s_waitcnt lgkmcnt(6)
	s_add_u32 m0, s29, 0xa000
	v_mfma_f32_32x32x16_bf16 v[68:83], v[208:211], v[236:239], v[68:83]
	global_load_lds_dwordx4 v175, s[8:9]
	ds_read_b128 v[232:235], v182 offset:16384
	v_exp_f32_e32 v105, v105
	v_cvt_pk_bf16_f32 v100, v100, v101
	v_cvt_pk_bf16_f32 v101, v102, v103
	s_waitcnt lgkmcnt(6)
	v_mfma_f32_32x32x16_bf16 v[188:203], v[132:135], v[116:119], v[2:17]
	ds_read_b128 v[236:239], v182 offset:24576
	v_exp_f32_e32 v106, v106
	v_exp_f32_e32 v107, v107
	v_add_f32_e32 v252, v252, v104
	v_add_f32_e32 v253, v253, v105
	s_waitcnt lgkmcnt(6)
	v_mfma_f32_32x32x16_bf16 v[204:219], v[136:139], v[116:119], v[2:17]
	ds_read_b64_tr_b16 v[132:133], v228 offset:0
	ds_read_b64_tr_b16 v[134:135], v228 offset:2048
	v_add_f32_e32 v252, v252, v106
	v_add_f32_e32 v253, v253, v107
	v_cvt_pk_bf16_f32 v102, v104, v105
	v_cvt_pk_bf16_f32 v103, v106, v107
	s_waitcnt lgkmcnt(7)
	v_mfma_f32_32x32x16_bf16 v[188:203], v[140:143], v[120:123], v[188:203]
	ds_read_b64_tr_b16 v[136:137], v229 offset:0
	ds_read_b64_tr_b16 v[138:139], v229 offset:2048
	v_exp_f32_e32 v108, v108
	v_exp_f32_e32 v109, v109
	s_waitcnt lgkmcnt(8)
	v_mfma_f32_32x32x16_bf16 v[204:219], v[144:147], v[120:123], v[204:219]
	ds_read_b64_tr_b16 v[140:141], v230 offset:0
	ds_read_b64_tr_b16 v[142:143], v230 offset:2048
	v_exp_f32_e32 v110, v110
	v_exp_f32_e32 v111, v111
	v_add_f32_e32 v252, v252, v108
	v_add_f32_e32 v253, v253, v109
	s_waitcnt lgkmcnt(9)
	v_mfma_f32_32x32x16_bf16 v[188:203], v[220:223], v[124:127], v[188:203]
	ds_read_b64_tr_b16 v[144:145], v231 offset:0
	ds_read_b64_tr_b16 v[146:147], v231 offset:2048
	v_add_f32_e32 v252, v252, v110
	v_add_f32_e32 v253, v253, v111
	v_exp_f32_e32 v112, v112
	s_waitcnt lgkmcnt(10)
	v_mfma_f32_32x32x16_bf16 v[204:219], v[224:227], v[124:127], v[204:219]
	ds_read_b64_tr_b16 v[220:221], v228 offset:4096
	ds_read_b64_tr_b16 v[222:223], v228 offset:6144
	v_exp_f32_e32 v113, v113
	v_cvt_pk_bf16_f32 v104, v108, v109
	v_cvt_pk_bf16_f32 v105, v110, v111
	s_waitcnt lgkmcnt(11)
	v_mfma_f32_32x32x16_bf16 v[188:203], v[232:235], v[128:131], v[188:203]
	ds_read_b64_tr_b16 v[224:225], v229 offset:4096
	ds_read_b64_tr_b16 v[226:227], v229 offset:6144
	v_exp_f32_e32 v114, v114
	v_exp_f32_e32 v115, v115
	v_add_f32_e32 v252, v252, v112
	s_waitcnt lgkmcnt(12)
	v_mfma_f32_32x32x16_bf16 v[204:219], v[236:239], v[128:131], v[204:219]
	ds_read_b64_tr_b16 v[232:233], v230 offset:4096
	ds_read_b64_tr_b16 v[234:235], v230 offset:6144
	v_add_f32_e32 v253, v253, v113
	v_add_f32_e32 v252, v252, v114
	v_add_f32_e32 v253, v253, v115
	v_cvt_pk_bf16_f32 v106, v112, v113
	v_cvt_pk_bf16_f32 v107, v114, v115
	v_max_f32_e32 v251, v252, v253
	v_cmp_nge_f32_e32 vcc, 0x45800000, v251
	s_cbranch_vccnz .LatA_recs_m0

; #define VREADS1(arr, d_) do { const unsigned ad_ = vbase ^ (unsigned)((d_) << 6); __builtin_amdgcn_sched_barrier(0); \
;         _Pragma("unroll") for (int ks_ = 0; ks_ < 4; ++ks_) { VTR(arr[ks_ * 2], ad_, ks_ * 4096); VTR(arr[ks_ * 2 + 1], ad_, ks_ * 4096 + 2048); } __builtin_amdgcn_sched_barrier(0); } while (0)
; #define PV1(arr, d_) do { _Pragma("unroll") for (int ks_ = 0; ks_ < 4; ++ks_) { const s16x4 lo_ = arr[ks_ * 2], hh_ = arr[ks_ * 2 + 1]; \
;         const bf16x8 bv_ = (bf16x8){lo_[0], lo_[1], lo_[2], lo_[3], hh_[0], hh_[1], hh_[2], hh_[3]}; \
;         O[d_] = __builtin_amdgcn_mfma_f32_32x32x16_bf16(pa[ks_], bv_, O[d_], 0, 0, 0); } __builtin_amdgcn_sched_barrier(0); } while (0)
; #define LGKM0() do { __builtin_amdgcn_sched_barrier(0); asm volatile("s_waitcnt lgkmcnt(0)" ::: "memory"); __builtin_amdgcn_sched_barrier(0); } while (0)
; __device__ __forceinline__ void attn_unit(LAS unsigned char* lds, const bf16_t* Z, bf16_t* A2, const float* tabg, int seq_base, int S, int h, int qb, float lam) {
;     ...
;         for (int r = 0; r < 16; r += 2) { ls2 += (f32x2){p0[r], p0[r + 1]}; ls2 += (f32x2){p1[r], p1[r + 1]}; }
;         bf16x8 pa[4]; pa[0] = pack8(p0, 0); pa[1] = pack8(p0, 8); pa[2] = pack8(p1, 0); pa[3] = pack8(p1, 8);
;         LGKM0(); VREADS1(vb, 1); PV1(va, 0); LGKM0(); VREADS1(va, 2); PV1(vb, 1); LGKM0(); VREADS1(vb, 3); PV1(va, 2); LGKM0(); PV1(vb, 3);
;     ...
;         if (t + 2 < NT) asm volatile("s_waitcnt vmcnt(4) lgkmcnt(0)" ::: "memory"); else asm volatile("s_waitcnt vmcnt(0) lgkmcnt(0)" ::: "memory");
;         __builtin_amdgcn_s_barrier(); asm volatile("" ::: "memory");
;         bc = (bc == NST - 1) ? 0 : bc + 1; bn = (bn == NST - 1) ? 0 : bn + 1;
;     }
.LatA_recret_m3:
	v_add_f32_e32 v150, v150, v252
	v_add_f32_e32 v151, v151, v253
	s_add_u32 s8, s8, 0x40000
	s_addc_u32 s9, s9, 0
	s_waitcnt vmcnt(4)
	s_barrier
	s_sub_u32 s36, s36, 1
	s_cmp_lg_u32 s36, 0
	s_cbranch_scc1 .LatA_loop
	s_sub_u32 s10, s10, 1
	s_cbranch_scc1 .LatA_evs_x4

; __device__ __forceinline__ void attn_unit(LAS unsigned char* lds, const bf16_t* Z, bf16_t* A2, const float* tabg, int seq_base, int S, int h, int qb, float lam) {
;     ...
;         {
;             bf16x8 kf[8];
; #pragma unroll
;             for (int ds = 0; ds < 4; ++ds) { kf[2 * ds] = *(const LAS bf16x8*)(Kt + (kfo ^ (unsigned)(ds << 5))); kf[2 * ds + 1] = *(const LAS bf16x8*)(Kt + 32 * 256 + (kfo ^ (unsigned)(ds << 5))); }
;             __builtin_amdgcn_sched_barrier(0);
;             p0 = __builtin_amdgcn_mfma_f32_32x32x16_bf16(kf[0], qf[0], cblk, 0, 0, 0);
;             p1 = __builtin_amdgcn_mfma_f32_32x32x16_bf16(kf[1], qf[0], cblk, 0, 0, 0);
; #pragma unroll
;             for (int ds = 1; ds < 4; ++ds) {
;                 p0 = __builtin_amdgcn_mfma_f32_32x32x16_bf16(kf[2 * ds], qf[ds], p0, 0, 0, 0);
;                 p1 = __builtin_amdgcn_mfma_f32_32x32x16_bf16(kf[2 * ds + 1], qf[ds], p1, 0, 0, 0);
;             }
;         }
;     ...
;         const unsigned vbase = (unsigned)(size_t)Vt + vfo;
;         s16x4 va[8], vb[8];
;         VREADS1(va, 0);
;         if (near) {
;             const LAS float* tp = tab + (kv0 + 4 * hi - (qlo + r32) + 224);
; #pragma unroll
;             for (int r = 0; r < 16; ++r) { p0[r] += tp[(r & 3) + 8 * (r >> 2)]; p1[r] += tp[32 + (r & 3) + 8 * (r >> 2)]; }
;         }
;         float mx = max2f(max16f(p0), max16f(p1));
;         const bool first = (t == 0);
;         if (first || __any(mx > THR)) {
;             { auto rr = __builtin_amdgcn_permlane32_swap(__float_as_uint(mx), __float_as_uint(mx), false, false); mx = max2f(__uint_as_float(rr[0]), __uint_as_float(rr[1])); }
;             const float delta = first ? mx : fmaxf(mx, 0.f);
;             const float alpha = first ? 1.0f : __builtin_amdgcn_exp2f(-delta);
;             mu += delta; ls2 *= alpha;
;             if (!first) {
;                 asm volatile("" ::: "memory");
;                 scr[r32] = alpha;
;                 asm volatile("s_waitcnt lgkmcnt(0)" ::: "memory");
; #pragma unroll
;                 for (int g = 0; g < 4; ++g) { const f32x4 a4 = *(const LAS f32x4*)(scr + 8 * g + 4 * hi);
; #pragma unroll
;                     for (int d = 0; d < 4; ++d) { O[d][4 * g + 0] *= a4[0]; O[d][4 * g + 1] *= a4[1]; O[d][4 * g + 2] *= a4[2]; O[d][4 * g + 3] *= a4[3]; } }
;                 asm volatile("s_waitcnt lgkmcnt(0)" ::: "memory");
;             }
; #pragma unroll
.LatA_evret_x3:
	s_waitcnt lgkmcnt(12)
	v_mfma_f32_32x32x16_bf16 v[20:35], v[84:87], v[132:135], v[20:35]
	ds_read_b64_tr_b16 v[236:237], v231 offset:4096
	ds_read_b64_tr_b16 v[238:239], v231 offset:6144
	v_exp_f32_e32 v188, v188
	v_exp_f32_e32 v189, v189
	s_waitcnt lgkmcnt(12)
	v_mfma_f32_32x32x16_bf16 v[36:51], v[84:87], v[136:139], v[36:51]
	ds_read_b64_tr_b16 v[132:133], v228 offset:8192
	ds_read_b64_tr_b16 v[134:135], v228 offset:10240
	v_exp_f32_e32 v190, v190
	v_exp_f32_e32 v191, v191
	s_waitcnt lgkmcnt(12)
	v_mfma_f32_32x32x16_bf16 v[52:67], v[84:87], v[140:143], v[52:67]
	ds_read_b64_tr_b16 v[136:137], v229 offset:8192
	ds_read_b64_tr_b16 v[138:139], v229 offset:10240
	v_exp_f32_e32 v192, v192
	v_add_f32_e32 v252, v188, v190
	v_add_f32_e32 v253, v189, v191
	v_exp_f32_e32 v193, v193
	s_waitcnt lgkmcnt(12)
	v_mfma_f32_32x32x16_bf16 v[68:83], v[84:87], v[144:147], v[68:83]
	ds_read_b64_tr_b16 v[140:141], v230 offset:8192
	ds_read_b64_tr_b16 v[142:143], v230 offset:10240
	v_cvt_pk_bf16_f32 v188, v188, v189
	v_cvt_pk_bf16_f32 v189, v190, v191
	v_exp_f32_e32 v194, v194
	s_waitcnt lgkmcnt(12)
	v_mfma_f32_32x32x16_bf16 v[20:35], v[88:91], v[220:223], v[20:35]
	ds_read_b64_tr_b16 v[144:145], v231 offset:8192
	ds_read_b64_tr_b16 v[146:147], v231 offset:10240
	v_exp_f32_e32 v195, v195
	v_add_f32_e32 v252, v252, v192
	v_add_f32_e32 v253, v253, v193
	v_add_f32_e32 v252, v252, v194
	s_waitcnt lgkmcnt(12)
	v_mfma_f32_32x32x16_bf16 v[36:51], v[88:91], v[224:227], v[36:51]
	ds_read_b64_tr_b16 v[220:221], v228 offset:12288
	ds_read_b64_tr_b16 v[222:223], v228 offset:14336
	v_add_f32_e32 v253, v253, v195
	v_cvt_pk_bf16_f32 v190, v192, v193
	v_cvt_pk_bf16_f32 v191, v194, v195
	v_exp_f32_e32 v196, v196
	s_waitcnt lgkmcnt(12)
	v_mfma_f32_32x32x16_bf16 v[52:67], v[88:91], v[232:235], v[52:67]
	ds_read_b64_tr_b16 v[224:225], v229 offset:12288
	ds_read_b64_tr_b16 v[226:227], v229 offset:14336
	v_exp_f32_e32 v197, v197
	v_exp_f32_e32 v198, v198
	s_waitcnt lgkmcnt(12)
	s_add_u32 m0, s29, 0xd000
	v_mfma_f32_32x32x16_bf16 v[68:83], v[88:91], v[236:239], v[68:83]
	global_load_lds_dwordx4 v174, s[8:9]
	ds_read_b64_tr_b16 v[232:233], v230 offset:12288
	ds_read_b64_tr_b16 v[234:235], v230 offset:14336
	v_exp_f32_e32 v199, v199
	v_add_f32_e32 v252, v252, v196
	v_add_f32_e32 v253, v253, v197
	v_add_f32_e32 v252, v252, v198
	s_waitcnt lgkmcnt(12)
	v_mfma_f32_32x32x16_bf16 v[20:35], v[100:103], v[132:135], v[20:35]
	ds_read_b64_tr_b16 v[236:237], v231 offset:12288
	ds_read_b64_tr_b16 v[238:239], v231 offset:14336
	v_add_f32_e32 v253, v253, v199
	v_exp_f32_e32 v200, v200
	s_waitcnt lgkmcnt(12)
	v_mfma_f32_32x32x16_bf16 v[36:51], v[100:103], v[136:139], v[36:51]
	ds_read_b128 v[132:135], v19 offset:32768
	v_exp_f32_e32 v201, v201
	v_cvt_pk_bf16_f32 v192, v196, v197
	v_cvt_pk_bf16_f32 v193, v198, v199
	v_exp_f32_e32 v202, v202
	s_waitcnt lgkmcnt(11)
	v_mfma_f32_32x32x16_bf16 v[52:67], v[100:103], v[140:143], v[52:67]
	ds_read_b128 v[136:139], v19 offset:40960
	v_exp_f32_e32 v203, v203
	v_add_f32_e32 v252, v252, v200
	v_add_f32_e32 v253, v253, v201
	s_waitcnt lgkmcnt(10)
	v_mfma_f32_32x32x16_bf16 v[68:83], v[100:103], v[144:147], v[68:83]
	ds_read_b128 v[140:143], v180 offset:32768
	v_add_f32_e32 v252, v252, v202
	v_add_f32_e32 v253, v253, v203
	v_cvt_pk_bf16_f32 v194, v200, v201
	v_cvt_pk_bf16_f32 v195, v202, v203
	s_waitcnt lgkmcnt(9)
	v_mfma_f32_32x32x16_bf16 v[20:35], v[104:107], v[220:223], v[20:35]
	ds_read_b128 v[144:147], v180 offset:40960
	v_exp_f32_e32 v204, v204
	v_exp_f32_e32 v205, v205
	v_exp_f32_e32 v206, v206
	s_waitcnt lgkmcnt(8)
	v_mfma_f32_32x32x16_bf16 v[36:51], v[104:107], v[224:227], v[36:51]
	ds_read_b128 v[220:223], v181 offset:32768
	v_exp_f32_e32 v207, v207
	v_add_f32_e32 v252, v252, v204
	v_add_f32_e32 v253, v253, v205
	s_waitcnt lgkmcnt(7)
	v_mfma_f32_32x32x16_bf16 v[52:67], v[104:107], v[232:235], v[52:67]
	ds_read_b128 v[224:227], v181 offset:40960
	v_add_f32_e32 v252, v252, v206
	v_add_f32_e32 v253, v253, v207
	v_exp_f32_e32 v208, v208
	s_waitcnt lgkmcnt(6)
	s_add_u32 m0, s29, 0xf000
	v_mfma_f32_32x32x16_bf16 v[68:83], v[104:107], v[236:239], v[68:83]
	global_load_lds_dwordx4 v175, s[8:9]
	ds_read_b128 v[232:235], v182 offset:32768
	v_exp_f32_e32 v209, v209
	v_cvt_pk_bf16_f32 v204, v204, v205
	v_cvt_pk_bf16_f32 v205, v206, v207
	s_waitcnt lgkmcnt(6)
	v_mfma_f32_32x32x16_bf16 v[84:99], v[132:135], v[116:119], v[2:17]
	ds_read_b128 v[236:239], v182 offset:40960
	v_exp_f32_e32 v210, v210
	v_exp_f32_e32 v211, v211
	v_add_f32_e32 v252, v252, v208
	v_add_f32_e32 v253, v253, v209
	s_waitcnt lgkmcnt(6)
	v_mfma_f32_32x32x16_bf16 v[100:115], v[136:139], v[116:119], v[2:17]
	ds_read_b64_tr_b16 v[132:133], v228 offset:16384
	ds_read_b64_tr_b16 v[134:135], v228 offset:18432
	v_add_f32_e32 v252, v252, v210
	v_add_f32_e32 v253, v253, v211
	v_cvt_pk_bf16_f32 v206, v208, v209
	v_cvt_pk_bf16_f32 v207, v210, v211
	s_waitcnt lgkmcnt(7)
	v_mfma_f32_32x32x16_bf16 v[84:99], v[140:143], v[120:123], v[84:99]
	ds_read_b64_tr_b16 v[136:137], v229 offset:16384
	ds_read_b64_tr_b16 v[138:139], v229 offset:18432
	v_exp_f32_e32 v212, v212
	v_exp_f32_e32 v213, v213
	s_waitcnt lgkmcnt(8)
	v_mfma_f32_32x32x16_bf16 v[100:115], v[144:147], v[120:123], v[100:115]
	ds_read_b64_tr_b16 v[140:141], v230 offset:16384
	ds_read_b64_tr_b16 v[142:143], v230 offset:18432
	v_exp_f32_e32 v214, v214
	v_exp_f32_e32 v215, v215
	v_add_f32_e32 v252, v252, v212
	v_add_f32_e32 v253, v253, v213
	s_waitcnt lgkmcnt(9)
	v_mfma_f32_32x32x16_bf16 v[84:99], v[220:223], v[124:127], v[84:99]
	ds_read_b64_tr_b16 v[144:145], v231 offset:16384
	ds_read_b64_tr_b16 v[146:147], v231 offset:18432
	v_add_f32_e32 v252, v252, v214
	v_add_f32_e32 v253, v253, v215
	v_exp_f32_e32 v216, v216
	s_waitcnt lgkmcnt(10)
	v_mfma_f32_32x32x16_bf16 v[100:115], v[224:227], v[124:127], v[100:115]
	ds_read_b64_tr_b16 v[220:221], v228 offset:20480
	ds_read_b64_tr_b16 v[222:223], v228 offset:22528
	v_exp_f32_e32 v217, v217
	v_cvt_pk_bf16_f32 v208, v212, v213
	v_cvt_pk_bf16_f32 v209, v214, v215
	s_waitcnt lgkmcnt(11)
	v_mfma_f32_32x32x16_bf16 v[84:99], v[232:235], v[128:131], v[84:99]
	ds_read_b64_tr_b16 v[224:225], v229 offset:20480
	ds_read_b64_tr_b16 v[226:227], v229 offset:22528
	v_exp_f32_e32 v218, v218
	v_exp_f32_e32 v219, v219
	v_add_f32_e32 v252, v252, v216
	s_waitcnt lgkmcnt(12)
	v_mfma_f32_32x32x16_bf16 v[100:115], v[236:239], v[128:131], v[100:115]
	ds_read_b64_tr_b16 v[232:233], v230 offset:20480
	ds_read_b64_tr_b16 v[234:235], v230 offset:22528
	v_add_f32_e32 v253, v253, v217
	v_add_f32_e32 v252, v252, v218
	v_add_f32_e32 v253, v253, v219
	v_cvt_pk_bf16_f32 v210, v216, v217
	v_cvt_pk_bf16_f32 v211, v218, v219
	v_max_f32_e32 v251, v252, v253
	v_cmp_nge_f32_e32 vcc, 0x45800000, v251
	s_cbranch_vccnz .LatA_recs_x3
; __device__ __forceinline__ void attn_unit(LAS unsigned char* lds, const bf16_t* Z, bf16_t* A2, const float* tabg, int seq_base, int S, int h, int qb, float lam) {
;     ...
;         {
;             bf16x8 kf[8];
; #pragma unroll
;             for (int ds = 0; ds < 4; ++ds) { kf[2 * ds] = *(const LAS bf16x8*)(Kt + (kfo ^ (unsigned)(ds << 5))); kf[2 * ds + 1] = *(const LAS bf16x8*)(Kt + 32 * 256 + (kfo ^ (unsigned)(ds << 5))); }
;             __builtin_amdgcn_sched_barrier(0);
;             p0 = __builtin_amdgcn_mfma_f32_32x32x16_bf16(kf[0], qf[0], cblk, 0, 0, 0);
;             p1 = __builtin_amdgcn_mfma_f32_32x32x16_bf16(kf[1], qf[0], cblk, 0, 0, 0);
; #pragma unroll
;             for (int ds = 1; ds < 4; ++ds) {
;                 p0 = __builtin_amdgcn_mfma_f32_32x32x16_bf16(kf[2 * ds], qf[ds], p0, 0, 0, 0);
;                 p1 = __builtin_amdgcn_mfma_f32_32x32x16_bf16(kf[2 * ds + 1], qf[ds], p1, 0, 0, 0);
;             }
;         }
;     ...
;         const unsigned vbase = (unsigned)(size_t)Vt + vfo;
;         s16x4 va[8], vb[8];
;         VREADS1(va, 0);
;         if (near) {
;             const LAS float* tp = tab + (kv0 + 4 * hi - (qlo + r32) + 224);
; #pragma unroll
;             for (int r = 0; r < 16; ++r) { p0[r] += tp[(r & 3) + 8 * (r >> 2)]; p1[r] += tp[32 + (r & 3) + 8 * (r >> 2)]; }
;         }
;         float mx = max2f(max16f(p0), max16f(p1));
;         const bool first = (t == 0);
;         if (first || __any(mx > THR)) {
;             { auto rr = __builtin_amdgcn_permlane32_swap(__float_as_uint(mx), __float_as_uint(mx), false, false); mx = max2f(__uint_as_float(rr[0]), __uint_as_float(rr[1])); }
;             const float delta = first ? mx : fmaxf(mx, 0.f);
;     ...
;         for (int r = 0; r < 16; r += 2) { ls2 += (f32x2){p0[r], p0[r + 1]}; ls2 += (f32x2){p1[r], p1[r + 1]}; }
;         bf16x8 pa[4]; pa[0] = pack8(p0, 0); pa[1] = pack8(p0, 8); pa[2] = pack8(p1, 0); pa[3] = pack8(p1, 8);
;         LGKM0(); VREADS1(vb, 1); PV1(va, 0); LGKM0(); VREADS1(va, 2); PV1(vb, 1); LGKM0(); VREADS1(vb, 3); PV1(va, 2); LGKM0(); PV1(vb, 3);
;     ...
;         if (t + 2 < NT) asm volatile("s_waitcnt vmcnt(4) lgkmcnt(0)" ::: "memory"); else asm volatile("s_waitcnt vmcnt(0) lgkmcnt(0)" ::: "memory");
;         __builtin_amdgcn_s_barrier(); asm volatile("" ::: "memory");
;         bc = (bc == NST - 1) ? 0 : bc + 1; bn = (bn == NST - 1) ? 0 : bn + 1;
.LatA_recret_x3:
	v_add_f32_e32 v150, v150, v252
	v_add_f32_e32 v151, v151, v253
	s_add_u32 s8, s8, 0x40000
	s_addc_u32 s9, s9, 0
	s_waitcnt vmcnt(2)
	s_barrier
	s_sub_u32 s10, s10, 1
	s_cbranch_scc1 .LatA_evs_x2
.LatA_evret_x2:
	s_waitcnt lgkmcnt(12)
	v_mfma_f32_32x32x16_bf16 v[20:35], v[188:191], v[132:135], v[20:35]
	ds_read_b64_tr_b16 v[236:237], v231 offset:20480
	ds_read_b64_tr_b16 v[238:239], v231 offset:22528
	v_exp_f32_e32 v84, v84
	v_exp_f32_e32 v85, v85
	s_waitcnt lgkmcnt(12)
	v_mfma_f32_32x32x16_bf16 v[36:51], v[188:191], v[136:139], v[36:51]
	ds_read_b64_tr_b16 v[132:133], v228 offset:24576
	ds_read_b64_tr_b16 v[134:135], v228 offset:26624
	v_exp_f32_e32 v86, v86
	v_exp_f32_e32 v87, v87
	s_waitcnt lgkmcnt(12)
	v_mfma_f32_32x32x16_bf16 v[52:67], v[188:191], v[140:143], v[52:67]
	ds_read_b64_tr_b16 v[136:137], v229 offset:24576
	ds_read_b64_tr_b16 v[138:139], v229 offset:26624
	v_exp_f32_e32 v88, v88
	v_add_f32_e32 v252, v84, v86
	v_add_f32_e32 v253, v85, v87
	v_exp_f32_e32 v89, v89
	s_waitcnt lgkmcnt(12)
	v_mfma_f32_32x32x16_bf16 v[68:83], v[188:191], v[144:147], v[68:83]
	ds_read_b64_tr_b16 v[140:141], v230 offset:24576
	ds_read_b64_tr_b16 v[142:143], v230 offset:26624
	v_cvt_pk_bf16_f32 v84, v84, v85
	v_cvt_pk_bf16_f32 v85, v86, v87
	v_exp_f32_e32 v90, v90
	s_waitcnt lgkmcnt(12)
	v_mfma_f32_32x32x16_bf16 v[20:35], v[192:195], v[220:223], v[20:35]
	ds_read_b64_tr_b16 v[144:145], v231 offset:24576
	ds_read_b64_tr_b16 v[146:147], v231 offset:26624
	v_exp_f32_e32 v91, v91
	v_add_f32_e32 v252, v252, v88
	v_add_f32_e32 v253, v253, v89
	v_add_f32_e32 v252, v252, v90
	s_waitcnt lgkmcnt(12)
	v_mfma_f32_32x32x16_bf16 v[36:51], v[192:195], v[224:227], v[36:51]
	ds_read_b64_tr_b16 v[220:221], v228 offset:28672
	ds_read_b64_tr_b16 v[222:223], v228 offset:30720
	v_add_f32_e32 v253, v253, v91
	v_cvt_pk_bf16_f32 v86, v88, v89
	v_cvt_pk_bf16_f32 v87, v90, v91
	v_exp_f32_e32 v92, v92
	s_waitcnt lgkmcnt(12)
	v_mfma_f32_32x32x16_bf16 v[52:67], v[192:195], v[232:235], v[52:67]
	ds_read_b64_tr_b16 v[224:225], v229 offset:28672
	ds_read_b64_tr_b16 v[226:227], v229 offset:30720
	v_exp_f32_e32 v93, v93
	v_exp_f32_e32 v94, v94
	s_waitcnt lgkmcnt(12)
	v_mfma_f32_32x32x16_bf16 v[68:83], v[192:195], v[236:239], v[68:83]
	ds_read_b64_tr_b16 v[232:233], v230 offset:28672
	ds_read_b64_tr_b16 v[234:235], v230 offset:30720
	v_exp_f32_e32 v95, v95
	v_add_f32_e32 v252, v252, v92
	v_add_f32_e32 v253, v253, v93
	v_add_f32_e32 v252, v252, v94
	s_waitcnt lgkmcnt(12)
	v_mfma_f32_32x32x16_bf16 v[20:35], v[204:207], v[132:135], v[20:35]
	ds_read_b64_tr_b16 v[236:237], v231 offset:28672
	ds_read_b64_tr_b16 v[238:239], v231 offset:30720
	v_add_f32_e32 v253, v253, v95
	v_exp_f32_e32 v96, v96
	s_waitcnt lgkmcnt(12)
	v_mfma_f32_32x32x16_bf16 v[36:51], v[204:207], v[136:139], v[36:51]
	ds_read_b128 v[132:135], v164
	v_exp_f32_e32 v97, v97
	v_cvt_pk_bf16_f32 v88, v92, v93
	v_cvt_pk_bf16_f32 v89, v94, v95
	v_exp_f32_e32 v98, v98
	s_waitcnt lgkmcnt(11)
	v_mfma_f32_32x32x16_bf16 v[52:67], v[204:207], v[140:143], v[52:67]
	ds_read_b128 v[136:139], v164 offset:8192
	v_exp_f32_e32 v99, v99
	v_add_f32_e32 v252, v252, v96
	v_add_f32_e32 v253, v253, v97
	s_waitcnt lgkmcnt(10)
	v_mfma_f32_32x32x16_bf16 v[68:83], v[204:207], v[144:147], v[68:83]
	ds_read_b128 v[140:143], v165
	v_add_f32_e32 v252, v252, v98
	v_add_f32_e32 v253, v253, v99
	v_cvt_pk_bf16_f32 v90, v96, v97
	v_cvt_pk_bf16_f32 v91, v98, v99
	s_waitcnt lgkmcnt(9)
	v_mfma_f32_32x32x16_bf16 v[20:35], v[208:211], v[220:223], v[20:35]
	ds_read_b128 v[144:147], v165 offset:8192
	v_exp_f32_e32 v100, v100
	v_exp_f32_e32 v101, v101
	v_exp_f32_e32 v102, v102
	s_waitcnt lgkmcnt(8)
	v_mfma_f32_32x32x16_bf16 v[36:51], v[208:211], v[224:227], v[36:51]
	ds_read_b128 v[220:223], v166
	v_exp_f32_e32 v103, v103
	v_add_f32_e32 v252, v252, v100
	v_add_f32_e32 v253, v253, v101
	s_waitcnt lgkmcnt(7)
	v_mfma_f32_32x32x16_bf16 v[52:67], v[208:211], v[232:235], v[52:67]
	ds_read_b128 v[224:227], v166 offset:8192
	v_add_f32_e32 v252, v252, v102
	v_add_f32_e32 v253, v253, v103
	v_exp_f32_e32 v104, v104
	s_waitcnt lgkmcnt(6)
	v_mfma_f32_32x32x16_bf16 v[68:83], v[208:211], v[236:239], v[68:83]
	ds_read_b128 v[232:235], v167
	v_exp_f32_e32 v105, v105
	v_cvt_pk_bf16_f32 v100, v100, v101
	v_cvt_pk_bf16_f32 v101, v102, v103
	s_waitcnt lgkmcnt(6)
	v_mfma_f32_32x32x16_bf16 v[188:203], v[132:135], v[116:119], v[2:17]
	ds_read_b128 v[236:239], v167 offset:8192
	v_exp_f32_e32 v106, v106
	v_exp_f32_e32 v107, v107
	v_add_f32_e32 v252, v252, v104
	v_add_f32_e32 v253, v253, v105
	s_waitcnt lgkmcnt(6)
	v_mfma_f32_32x32x16_bf16 v[204:219], v[136:139], v[116:119], v[2:17]
	ds_read_b64_tr_b16 v[132:133], v228 offset:32768
	ds_read_b64_tr_b16 v[134:135], v228 offset:34816
	v_add_f32_e32 v252, v252, v106
	v_add_f32_e32 v253, v253, v107
	v_cvt_pk_bf16_f32 v102, v104, v105
	v_cvt_pk_bf16_f32 v103, v106, v107
	s_waitcnt lgkmcnt(7)
	v_mfma_f32_32x32x16_bf16 v[188:203], v[140:143], v[120:123], v[188:203]
	ds_read_b64_tr_b16 v[136:137], v229 offset:32768
	ds_read_b64_tr_b16 v[138:139], v229 offset:34816
	v_exp_f32_e32 v108, v108
	v_exp_f32_e32 v109, v109
	s_waitcnt lgkmcnt(8)
	v_mfma_f32_32x32x16_bf16 v[204:219], v[144:147], v[120:123], v[204:219]
	ds_read_b64_tr_b16 v[140:141], v230 offset:32768
	ds_read_b64_tr_b16 v[142:143], v230 offset:34816
	v_exp_f32_e32 v110, v110
	v_exp_f32_e32 v111, v111
	v_add_f32_e32 v252, v252, v108
	v_add_f32_e32 v253, v253, v109
	s_waitcnt lgkmcnt(9)
	v_mfma_f32_32x32x16_bf16 v[188:203], v[220:223], v[124:127], v[188:203]
	ds_read_b64_tr_b16 v[144:145], v231 offset:32768
	ds_read_b64_tr_b16 v[146:147], v231 offset:34816
	v_add_f32_e32 v252, v252, v110
	v_add_f32_e32 v253, v253, v111
	v_exp_f32_e32 v112, v112
	s_waitcnt lgkmcnt(10)
	v_mfma_f32_32x32x16_bf16 v[204:219], v[224:227], v[124:127], v[204:219]
	ds_read_b64_tr_b16 v[220:221], v228 offset:36864
	ds_read_b64_tr_b16 v[222:223], v228 offset:38912
	v_exp_f32_e32 v113, v113
	v_cvt_pk_bf16_f32 v104, v108, v109
	v_cvt_pk_bf16_f32 v105, v110, v111
	s_waitcnt lgkmcnt(11)
	v_mfma_f32_32x32x16_bf16 v[188:203], v[232:235], v[128:131], v[188:203]
	ds_read_b64_tr_b16 v[224:225], v229 offset:36864
	ds_read_b64_tr_b16 v[226:227], v229 offset:38912
	v_exp_f32_e32 v114, v114
	v_exp_f32_e32 v115, v115
	v_add_f32_e32 v252, v252, v112
	s_waitcnt lgkmcnt(12)
	v_mfma_f32_32x32x16_bf16 v[204:219], v[236:239], v[128:131], v[204:219]
	ds_read_b64_tr_b16 v[232:233], v230 offset:36864
	ds_read_b64_tr_b16 v[234:235], v230 offset:38912
	v_add_f32_e32 v253, v253, v113
	v_add_f32_e32 v252, v252, v114
	v_add_f32_e32 v253, v253, v115
	v_cvt_pk_bf16_f32 v106, v112, v113
	v_cvt_pk_bf16_f32 v107, v114, v115
	v_max_f32_e32 v251, v252, v253
	v_cmp_nge_f32_e32 vcc, 0x45800000, v251
	s_cbranch_vccnz .LatA_recs_x2
; #define VREADS1(arr, d_) do { const unsigned ad_ = vbase ^ (unsigned)((d_) << 6); __builtin_amdgcn_sched_barrier(0); \
;         _Pragma("unroll") for (int ks_ = 0; ks_ < 4; ++ks_) { VTR(arr[ks_ * 2], ad_, ks_ * 4096); VTR(arr[ks_ * 2 + 1], ad_, ks_ * 4096 + 2048); } __builtin_amdgcn_sched_barrier(0); } while (0)
; #define PV1(arr, d_) do { _Pragma("unroll") for (int ks_ = 0; ks_ < 4; ++ks_) { const s16x4 lo_ = arr[ks_ * 2], hh_ = arr[ks_ * 2 + 1]; \
;         const bf16x8 bv_ = (bf16x8){lo_[0], lo_[1], lo_[2], lo_[3], hh_[0], hh_[1], hh_[2], hh_[3]}; \
;         O[d_] = __builtin_amdgcn_mfma_f32_32x32x16_bf16(pa[ks_], bv_, O[d_], 0, 0, 0); } __builtin_amdgcn_sched_barrier(0); } while (0)
; #define LGKM0() do { __builtin_amdgcn_sched_barrier(0); asm volatile("s_waitcnt lgkmcnt(0)" ::: "memory"); __builtin_amdgcn_sched_barrier(0); } while (0)
; __device__ __forceinline__ void attn_unit(LAS unsigned char* lds, const bf16_t* Z, bf16_t* A2, const float* tabg, int seq_base, int S, int h, int qb, float lam) {
;     ...
; #pragma unroll
;         for (int r = 0; r < 16; ++r) { p0[r] = __builtin_amdgcn_exp2f(p0[r]); p1[r] = __builtin_amdgcn_exp2f(p1[r]); }
; #pragma unroll
;         for (int r = 0; r < 16; r += 2) { ls2 += (f32x2){p0[r], p0[r + 1]}; ls2 += (f32x2){p1[r], p1[r + 1]}; }
;         bf16x8 pa[4]; pa[0] = pack8(p0, 0); pa[1] = pack8(p0, 8); pa[2] = pack8(p1, 0); pa[3] = pack8(p1, 8);
;         LGKM0(); VREADS1(vb, 1); PV1(va, 0); LGKM0(); VREADS1(va, 2); PV1(vb, 1); LGKM0(); VREADS1(vb, 3); PV1(va, 2); LGKM0(); PV1(vb, 3);
;     ...
;         if (t + 2 < NT) asm volatile("s_waitcnt vmcnt(4) lgkmcnt(0)" ::: "memory"); else asm volatile("s_waitcnt vmcnt(0) lgkmcnt(0)" ::: "memory");
;         __builtin_amdgcn_s_barrier(); asm volatile("" ::: "memory");
;         bc = (bc == NST - 1) ? 0 : bc + 1; bn = (bn == NST - 1) ? 0 : bn + 1;
.LatA_recret_x2:
	v_add_f32_e32 v150, v150, v252
	v_add_f32_e32 v151, v151, v253
	s_add_u32 s8, s8, 0x40000
	s_addc_u32 s9, s9, 0
	s_waitcnt vmcnt(0)
	s_barrier
	s_sub_u32 s10, s10, 1
	s_cbranch_scc1 .LatA_evs_x1
.LatA_evret_x1:
	s_waitcnt lgkmcnt(12)
	v_mfma_f32_32x32x16_bf16 v[20:35], v[84:87], v[132:135], v[20:35]
	ds_read_b64_tr_b16 v[236:237], v231 offset:36864
	ds_read_b64_tr_b16 v[238:239], v231 offset:38912
	v_exp_f32_e32 v188, v188
	v_exp_f32_e32 v189, v189
	v_exp_f32_e32 v190, v190
	s_waitcnt lgkmcnt(12)
	v_mfma_f32_32x32x16_bf16 v[36:51], v[84:87], v[136:139], v[36:51]
	ds_read_b64_tr_b16 v[132:133], v228 offset:40960
	ds_read_b64_tr_b16 v[134:135], v228 offset:43008
	v_exp_f32_e32 v191, v191
	v_exp_f32_e32 v192, v192
	v_add_f32_e32 v252, v188, v190
	v_add_f32_e32 v253, v189, v191
	v_exp_f32_e32 v193, v193
	s_waitcnt lgkmcnt(12)
	v_mfma_f32_32x32x16_bf16 v[52:67], v[84:87], v[140:143], v[52:67]
	ds_read_b64_tr_b16 v[136:137], v229 offset:40960
	ds_read_b64_tr_b16 v[138:139], v229 offset:43008
	v_cvt_pk_bf16_f32 v188, v188, v189
	v_cvt_pk_bf16_f32 v189, v190, v191
	v_exp_f32_e32 v194, v194
	v_exp_f32_e32 v195, v195
	v_add_f32_e32 v252, v252, v192
	s_waitcnt lgkmcnt(12)
	v_mfma_f32_32x32x16_bf16 v[68:83], v[84:87], v[144:147], v[68:83]
	ds_read_b64_tr_b16 v[140:141], v230 offset:40960
	ds_read_b64_tr_b16 v[142:143], v230 offset:43008
	v_add_f32_e32 v253, v253, v193
	v_add_f32_e32 v252, v252, v194
	v_add_f32_e32 v253, v253, v195
	v_cvt_pk_bf16_f32 v190, v192, v193
	v_cvt_pk_bf16_f32 v191, v194, v195
	v_exp_f32_e32 v196, v196
	s_waitcnt lgkmcnt(12)
	v_mfma_f32_32x32x16_bf16 v[20:35], v[88:91], v[220:223], v[20:35]
	ds_read_b64_tr_b16 v[144:145], v231 offset:40960
	ds_read_b64_tr_b16 v[146:147], v231 offset:43008
	v_exp_f32_e32 v197, v197
	v_exp_f32_e32 v198, v198
	v_exp_f32_e32 v199, v199
	s_waitcnt lgkmcnt(12)
	v_mfma_f32_32x32x16_bf16 v[36:51], v[88:91], v[224:227], v[36:51]
	ds_read_b64_tr_b16 v[220:221], v228 offset:45056
	ds_read_b64_tr_b16 v[222:223], v228 offset:47104
	v_add_f32_e32 v252, v252, v196
	v_add_f32_e32 v253, v253, v197
	v_add_f32_e32 v252, v252, v198
	v_add_f32_e32 v253, v253, v199
	v_exp_f32_e32 v200, v200
	s_waitcnt lgkmcnt(12)
	v_mfma_f32_32x32x16_bf16 v[52:67], v[88:91], v[232:235], v[52:67]
	ds_read_b64_tr_b16 v[224:225], v229 offset:45056
	ds_read_b64_tr_b16 v[226:227], v229 offset:47104
	v_exp_f32_e32 v201, v201
	v_cvt_pk_bf16_f32 v192, v196, v197
	v_cvt_pk_bf16_f32 v193, v198, v199
	v_exp_f32_e32 v202, v202
	v_exp_f32_e32 v203, v203
	s_waitcnt lgkmcnt(12)
	v_mfma_f32_32x32x16_bf16 v[68:83], v[88:91], v[236:239], v[68:83]
	ds_read_b64_tr_b16 v[232:233], v230 offset:45056
	ds_read_b64_tr_b16 v[234:235], v230 offset:47104
	v_add_f32_e32 v252, v252, v200
	v_add_f32_e32 v253, v253, v201
	v_add_f32_e32 v252, v252, v202
	v_add_f32_e32 v253, v253, v203
	v_cvt_pk_bf16_f32 v194, v200, v201
	v_cvt_pk_bf16_f32 v195, v202, v203
	s_waitcnt lgkmcnt(12)
	v_mfma_f32_32x32x16_bf16 v[20:35], v[100:103], v[132:135], v[20:35]
	ds_read_b64_tr_b16 v[236:237], v231 offset:45056
	ds_read_b64_tr_b16 v[238:239], v231 offset:47104
	v_exp_f32_e32 v204, v204
	v_exp_f32_e32 v205, v205
	v_exp_f32_e32 v206, v206
	v_exp_f32_e32 v207, v207
	s_waitcnt lgkmcnt(12)
	v_mfma_f32_32x32x16_bf16 v[36:51], v[100:103], v[136:139], v[36:51]
	ds_read_b64_tr_b16 v[132:133], v168 offset:0
	ds_read_b64_tr_b16 v[134:135], v168 offset:2048
	v_add_f32_e32 v252, v252, v204
	v_add_f32_e32 v253, v253, v205
	v_add_f32_e32 v252, v252, v206
	v_add_f32_e32 v253, v253, v207
	v_exp_f32_e32 v208, v208
	s_waitcnt lgkmcnt(12)
	v_mfma_f32_32x32x16_bf16 v[52:67], v[100:103], v[140:143], v[52:67]
	ds_read_b64_tr_b16 v[136:137], v169 offset:0
	ds_read_b64_tr_b16 v[138:139], v169 offset:2048
	v_exp_f32_e32 v209, v209
	v_cvt_pk_bf16_f32 v204, v204, v205
	v_cvt_pk_bf16_f32 v205, v206, v207
	v_exp_f32_e32 v210, v210
	v_exp_f32_e32 v211, v211
	s_waitcnt lgkmcnt(12)
	v_mfma_f32_32x32x16_bf16 v[68:83], v[100:103], v[144:147], v[68:83]
	ds_read_b64_tr_b16 v[140:141], v170 offset:0
	ds_read_b64_tr_b16 v[142:143], v170 offset:2048
	v_add_f32_e32 v252, v252, v208
	v_add_f32_e32 v253, v253, v209
	v_add_f32_e32 v252, v252, v210
	v_add_f32_e32 v253, v253, v211
	v_cvt_pk_bf16_f32 v206, v208, v209
	v_cvt_pk_bf16_f32 v207, v210, v211
	s_waitcnt lgkmcnt(12)
	v_mfma_f32_32x32x16_bf16 v[20:35], v[104:107], v[220:223], v[20:35]
	ds_read_b64_tr_b16 v[144:145], v171 offset:0
	ds_read_b64_tr_b16 v[146:147], v171 offset:2048
	v_exp_f32_e32 v212, v212
	v_exp_f32_e32 v213, v213
	v_exp_f32_e32 v214, v214
	s_waitcnt lgkmcnt(12)
	v_mfma_f32_32x32x16_bf16 v[36:51], v[104:107], v[224:227], v[36:51]
	ds_read_b64_tr_b16 v[220:221], v168 offset:4096
	ds_read_b64_tr_b16 v[222:223], v168 offset:6144
	v_exp_f32_e32 v215, v215
	v_add_f32_e32 v252, v252, v212
	v_add_f32_e32 v253, v253, v213
	v_add_f32_e32 v252, v252, v214
	v_add_f32_e32 v253, v253, v215
	v_exp_f32_e32 v216, v216
	s_waitcnt lgkmcnt(12)
	v_mfma_f32_32x32x16_bf16 v[52:67], v[104:107], v[232:235], v[52:67]
	ds_read_b64_tr_b16 v[224:225], v169 offset:4096
	ds_read_b64_tr_b16 v[226:227], v169 offset:6144
	v_exp_f32_e32 v217, v217
	v_cvt_pk_bf16_f32 v208, v212, v213
	v_cvt_pk_bf16_f32 v209, v214, v215
	v_exp_f32_e32 v218, v218
	s_waitcnt lgkmcnt(12)
	v_mfma_f32_32x32x16_bf16 v[68:83], v[104:107], v[236:239], v[68:83]
	ds_read_b64_tr_b16 v[232:233], v170 offset:4096
	ds_read_b64_tr_b16 v[234:235], v170 offset:6144
	v_exp_f32_e32 v219, v219
	v_add_f32_e32 v252, v252, v216
	v_add_f32_e32 v253, v253, v217
	v_add_f32_e32 v252, v252, v218
	v_add_f32_e32 v253, v253, v219
	v_cvt_pk_bf16_f32 v210, v216, v217
	v_cvt_pk_bf16_f32 v211, v218, v219
	v_max_f32_e32 v251, v252, v253
	v_cmp_nge_f32_e32 vcc, 0x45800000, v251
	s_cbranch_vccnz .LatA_recs_x1
; #define VREADS1(arr, d_) do { const unsigned ad_ = vbase ^ (unsigned)((d_) << 6); __builtin_amdgcn_sched_barrier(0); \
;         _Pragma("unroll") for (int ks_ = 0; ks_ < 4; ++ks_) { VTR(arr[ks_ * 2], ad_, ks_ * 4096); VTR(arr[ks_ * 2 + 1], ad_, ks_ * 4096 + 2048); } __builtin_amdgcn_sched_barrier(0); } while (0)
; #define PV1(arr, d_) do { _Pragma("unroll") for (int ks_ = 0; ks_ < 4; ++ks_) { const s16x4 lo_ = arr[ks_ * 2], hh_ = arr[ks_ * 2 + 1]; \
;         const bf16x8 bv_ = (bf16x8){lo_[0], lo_[1], lo_[2], lo_[3], hh_[0], hh_[1], hh_[2], hh_[3]}; \
;         O[d_] = __builtin_amdgcn_mfma_f32_32x32x16_bf16(pa[ks_], bv_, O[d_], 0, 0, 0); } __builtin_amdgcn_sched_barrier(0); } while (0)
; #define LGKM0() do { __builtin_amdgcn_sched_barrier(0); asm volatile("s_waitcnt lgkmcnt(0)" ::: "memory"); __builtin_amdgcn_sched_barrier(0); } while (0)
; __device__ __forceinline__ void attn_unit(LAS unsigned char* lds, const bf16_t* Z, bf16_t* A2, const float* tabg, int seq_base, int S, int h, int qb, float lam) {
;     ...
;         for (int r = 0; r < 16; r += 2) { ls2 += (f32x2){p0[r], p0[r + 1]}; ls2 += (f32x2){p1[r], p1[r + 1]}; }
;         bf16x8 pa[4]; pa[0] = pack8(p0, 0); pa[1] = pack8(p0, 8); pa[2] = pack8(p1, 0); pa[3] = pack8(p1, 8);
;         LGKM0(); VREADS1(vb, 1); PV1(va, 0); LGKM0(); VREADS1(va, 2); PV1(vb, 1); LGKM0(); VREADS1(vb, 3); PV1(va, 2); LGKM0(); PV1(vb, 3);
;     ...
;         if (t + 2 < NT) asm volatile("s_waitcnt vmcnt(4) lgkmcnt(0)" ::: "memory"); else asm volatile("s_waitcnt vmcnt(0) lgkmcnt(0)" ::: "memory");
;         __builtin_amdgcn_s_barrier(); asm volatile("" ::: "memory");
;         bc = (bc == NST - 1) ? 0 : bc + 1; bn = (bn == NST - 1) ? 0 : bn + 1;
;     }
;     const float ls = ls2[0] + ls2[1];
.LatA_recret_x1:
	v_add_f32_e32 v150, v150, v252
	v_add_f32_e32 v151, v151, v253
	s_add_u32 s8, s8, 0x40000
	s_addc_u32 s9, s9, 0
	s_waitcnt vmcnt(0)
	s_barrier
	s_waitcnt lgkmcnt(12)
	v_mfma_f32_32x32x16_bf16 v[20:35], v[188:191], v[132:135], v[20:35]
	ds_read_b64_tr_b16 v[236:237], v171 offset:4096
	ds_read_b64_tr_b16 v[238:239], v171 offset:6144
	s_waitcnt lgkmcnt(12)
	v_mfma_f32_32x32x16_bf16 v[36:51], v[188:191], v[136:139], v[36:51]
	ds_read_b64_tr_b16 v[132:133], v168 offset:8192
	ds_read_b64_tr_b16 v[134:135], v168 offset:10240
	s_waitcnt lgkmcnt(12)
	v_mfma_f32_32x32x16_bf16 v[52:67], v[188:191], v[140:143], v[52:67]
	ds_read_b64_tr_b16 v[136:137], v169 offset:8192
	ds_read_b64_tr_b16 v[138:139], v169 offset:10240
	s_waitcnt lgkmcnt(12)
	v_mfma_f32_32x32x16_bf16 v[68:83], v[188:191], v[144:147], v[68:83]
	ds_read_b64_tr_b16 v[140:141], v170 offset:8192
	ds_read_b64_tr_b16 v[142:143], v170 offset:10240
	s_waitcnt lgkmcnt(12)
	v_mfma_f32_32x32x16_bf16 v[20:35], v[192:195], v[220:223], v[20:35]
	ds_read_b64_tr_b16 v[144:145], v171 offset:8192
	ds_read_b64_tr_b16 v[146:147], v171 offset:10240
	s_waitcnt lgkmcnt(12)
	v_mfma_f32_32x32x16_bf16 v[36:51], v[192:195], v[224:227], v[36:51]
	ds_read_b64_tr_b16 v[220:221], v168 offset:12288
	ds_read_b64_tr_b16 v[222:223], v168 offset:14336
	s_waitcnt lgkmcnt(12)
	v_mfma_f32_32x32x16_bf16 v[52:67], v[192:195], v[232:235], v[52:67]
	ds_read_b64_tr_b16 v[224:225], v169 offset:12288
	ds_read_b64_tr_b16 v[226:227], v169 offset:14336
	s_waitcnt lgkmcnt(12)
	v_mfma_f32_32x32x16_bf16 v[68:83], v[192:195], v[236:239], v[68:83]
	ds_read_b64_tr_b16 v[232:233], v170 offset:12288
	ds_read_b64_tr_b16 v[234:235], v170 offset:14336
	s_waitcnt lgkmcnt(12)
	v_mfma_f32_32x32x16_bf16 v[20:35], v[204:207], v[132:135], v[20:35]
	ds_read_b64_tr_b16 v[236:237], v171 offset:12288
	ds_read_b64_tr_b16 v[238:239], v171 offset:14336
	s_waitcnt lgkmcnt(12)
	v_mfma_f32_32x32x16_bf16 v[36:51], v[204:207], v[136:139], v[36:51]
	s_waitcnt lgkmcnt(10)
	v_mfma_f32_32x32x16_bf16 v[52:67], v[204:207], v[140:143], v[52:67]
	s_waitcnt lgkmcnt(8)
	v_mfma_f32_32x32x16_bf16 v[68:83], v[204:207], v[144:147], v[68:83]
	s_waitcnt lgkmcnt(6)
	v_mfma_f32_32x32x16_bf16 v[20:35], v[208:211], v[220:223], v[20:35]
	s_waitcnt lgkmcnt(4)
	v_mfma_f32_32x32x16_bf16 v[36:51], v[208:211], v[224:227], v[36:51]
	s_waitcnt lgkmcnt(2)
	v_mfma_f32_32x32x16_bf16 v[52:67], v[208:211], v[232:235], v[52:67]
	s_waitcnt lgkmcnt(0)
	v_mfma_f32_32x32x16_bf16 v[68:83], v[208:211], v[236:239], v[68:83]
	s_waitcnt lgkmcnt(0)
	s_barrier
	s_mov_b32 m0, s32
	v_mov_b64_e32 v[164:165], 0x200
	v_mov_b64_e32 v[166:167], 0x1ff
	v_mov_b64_e32 v[168:169], 0x5ac
	v_mov_b64_e32 v[170:171], 0x5ab
	v_mov_b64_e32 v[172:173], 0x100
	v_mov_b64_e32 v[174:175], 0xff
	s_nop 15
	s_branch .LatA_done

; #define LAS __attribute__((address_space(3)))
; __device__ __forceinline__ float max2f(float a, float b) { float r; asm("v_max_f32_e32 %0, %1, %2" : "=v"(r) : "v"(a), "v"(b)); return r; }
; __device__ __forceinline__ void attn_unit(LAS unsigned char* lds, const bf16_t* Z, bf16_t* A2, const float* tabg, int seq_base, int S, int h, int qb, float lam) {
;     ...
;         float mx = max2f(max16f(p0), max16f(p1));
;         const bool first = (t == 0);
;         if (first || __any(mx > THR)) {
;             { auto rr = __builtin_amdgcn_permlane32_swap(__float_as_uint(mx), __float_as_uint(mx), false, false); mx = max2f(__uint_as_float(rr[0]), __uint_as_float(rr[1])); }
;             const float delta = first ? mx : fmaxf(mx, 0.f);
;             const float alpha = first ? 1.0f : __builtin_amdgcn_exp2f(-delta);
;             mu += delta; ls2 *= alpha;
;             if (!first) {
;                 asm volatile("" ::: "memory");
;                 scr[r32] = alpha;
;                 asm volatile("s_waitcnt lgkmcnt(0)" ::: "memory");
; #pragma unroll
;                 for (int g = 0; g < 4; ++g) { const f32x4 a4 = *(const LAS f32x4*)(scr + 8 * g + 4 * hi);
; #pragma unroll
;                     for (int d = 0; d < 4; ++d) { O[d][4 * g + 0] *= a4[0]; O[d][4 * g + 1] *= a4[1]; O[d][4 * g + 2] *= a4[2]; O[d][4 * g + 3] *= a4[3]; } }
;                 asm volatile("s_waitcnt lgkmcnt(0)" ::: "memory");
;             }
; #pragma unroll
;             for (int r = 0; r < 16; ++r) { p0[r] -= delta; p1[r] -= delta; }
.LatA_recnn_0:
	v_max3_f32 v251, v84, v85, v86
	v_max3_f32 v252, v87, v88, v89
	v_max3_f32 v251, v251, v90, v91
	v_max3_f32 v252, v252, v92, v93
	v_max3_f32 v251, v251, v94, v95
	v_max3_f32 v252, v252, v96, v97
	v_max3_f32 v251, v251, v98, v99
	v_max3_f32 v252, v252, v100, v101
	v_max3_f32 v251, v251, v102, v103
	v_max3_f32 v252, v252, v104, v105
	v_max3_f32 v251, v251, v106, v107
	v_max3_f32 v252, v252, v108, v109
	v_max3_f32 v251, v251, v110, v111
	v_max3_f32 v252, v252, v112, v113
	v_max3_f32 v251, v251, v114, v115
	v_max_f32_e32 v251, v251, v252
	v_mov_b32_e32 v252, v251
	s_nop 1
	v_permlane32_swap_b32_e32 v251, v252
	v_max_f32_e32 v251, v251, v252
	v_max_f32_e32 v253, 0, v251
	v_exp_f32_e64 v254, -v253
	v_add_f32_e32 v186, v186, v253
	s_nop 0
	v_mul_f32_e32 v150, v150, v254
	v_mul_f32_e32 v151, v151, v254
	ds_write_b32 v184, v254
	s_waitcnt lgkmcnt(0)
	ds_read_b128 v[132:135], v185
	ds_read_b128 v[136:139], v185 offset:32
	ds_read_b128 v[140:143], v185 offset:64
	ds_read_b128 v[144:147], v185 offset:96
	s_waitcnt lgkmcnt(0)
	v_pk_mul_f32 v[20:21], v[20:21], v[132:133]
	v_pk_mul_f32 v[22:23], v[22:23], v[134:135]
	v_pk_mul_f32 v[24:25], v[24:25], v[136:137]
	v_pk_mul_f32 v[26:27], v[26:27], v[138:139]
	v_pk_mul_f32 v[28:29], v[28:29], v[140:141]
	v_pk_mul_f32 v[30:31], v[30:31], v[142:143]
	v_pk_mul_f32 v[32:33], v[32:33], v[144:145]
	v_pk_mul_f32 v[34:35], v[34:35], v[146:147]
	v_pk_mul_f32 v[36:37], v[36:37], v[132:133]
	v_pk_mul_f32 v[38:39], v[38:39], v[134:135]
	v_pk_mul_f32 v[40:41], v[40:41], v[136:137]
	v_pk_mul_f32 v[42:43], v[42:43], v[138:139]
	v_pk_mul_f32 v[44:45], v[44:45], v[140:141]
	v_pk_mul_f32 v[46:47], v[46:47], v[142:143]
	v_pk_mul_f32 v[48:49], v[48:49], v[144:145]
	v_pk_mul_f32 v[50:51], v[50:51], v[146:147]
	v_pk_mul_f32 v[52:53], v[52:53], v[132:133]
	v_pk_mul_f32 v[54:55], v[54:55], v[134:135]
	v_pk_mul_f32 v[56:57], v[56:57], v[136:137]
	v_pk_mul_f32 v[58:59], v[58:59], v[138:139]
	v_pk_mul_f32 v[60:61], v[60:61], v[140:141]
	v_pk_mul_f32 v[62:63], v[62:63], v[142:143]
	v_pk_mul_f32 v[64:65], v[64:65], v[144:145]
	v_pk_mul_f32 v[66:67], v[66:67], v[146:147]
	v_pk_mul_f32 v[68:69], v[68:69], v[132:133]
	v_pk_mul_f32 v[70:71], v[70:71], v[134:135]
	v_pk_mul_f32 v[72:73], v[72:73], v[136:137]
	v_pk_mul_f32 v[74:75], v[74:75], v[138:139]
	v_pk_mul_f32 v[76:77], v[76:77], v[140:141]
	v_pk_mul_f32 v[78:79], v[78:79], v[142:143]
	v_pk_mul_f32 v[80:81], v[80:81], v[144:145]
	v_pk_mul_f32 v[82:83], v[82:83], v[146:147]
	v_mov_b32_e32 v252, v253
	v_pk_add_f32 v[84:85], v[84:85], v[252:253] neg_lo:[0,1] neg_hi:[0,1]
	v_pk_add_f32 v[86:87], v[86:87], v[252:253] neg_lo:[0,1] neg_hi:[0,1]
	v_pk_add_f32 v[88:89], v[88:89], v[252:253] neg_lo:[0,1] neg_hi:[0,1]
	v_pk_add_f32 v[90:91], v[90:91], v[252:253] neg_lo:[0,1] neg_hi:[0,1]
	v_pk_add_f32 v[92:93], v[92:93], v[252:253] neg_lo:[0,1] neg_hi:[0,1]
	v_pk_add_f32 v[94:95], v[94:95], v[252:253] neg_lo:[0,1] neg_hi:[0,1]
	v_pk_add_f32 v[96:97], v[96:97], v[252:253] neg_lo:[0,1] neg_hi:[0,1]
	v_pk_add_f32 v[98:99], v[98:99], v[252:253] neg_lo:[0,1] neg_hi:[0,1]
	v_pk_add_f32 v[100:101], v[100:101], v[252:253] neg_lo:[0,1] neg_hi:[0,1]
	v_pk_add_f32 v[102:103], v[102:103], v[252:253] neg_lo:[0,1] neg_hi:[0,1]
	v_pk_add_f32 v[104:105], v[104:105], v[252:253] neg_lo:[0,1] neg_hi:[0,1]
	v_pk_add_f32 v[106:107], v[106:107], v[252:253] neg_lo:[0,1] neg_hi:[0,1]
	v_pk_add_f32 v[108:109], v[108:109], v[252:253] neg_lo:[0,1] neg_hi:[0,1]
	v_pk_add_f32 v[110:111], v[110:111], v[252:253] neg_lo:[0,1] neg_hi:[0,1]
	v_pk_add_f32 v[112:113], v[112:113], v[252:253] neg_lo:[0,1] neg_hi:[0,1]
	v_pk_add_f32 v[114:115], v[114:115], v[252:253] neg_lo:[0,1] neg_hi:[0,1]
	v_pk_add_f32 v[188:189], v[188:189], v[252:253] neg_lo:[0,1] neg_hi:[0,1]
	v_pk_add_f32 v[190:191], v[190:191], v[252:253] neg_lo:[0,1] neg_hi:[0,1]
	v_pk_add_f32 v[192:193], v[192:193], v[252:253] neg_lo:[0,1] neg_hi:[0,1]
	v_pk_add_f32 v[194:195], v[194:195], v[252:253] neg_lo:[0,1] neg_hi:[0,1]
	v_pk_add_f32 v[196:197], v[196:197], v[252:253] neg_lo:[0,1] neg_hi:[0,1]
	v_pk_add_f32 v[198:199], v[198:199], v[252:253] neg_lo:[0,1] neg_hi:[0,1]
	v_pk_add_f32 v[200:201], v[200:201], v[252:253] neg_lo:[0,1] neg_hi:[0,1]
	v_pk_add_f32 v[202:203], v[202:203], v[252:253] neg_lo:[0,1] neg_hi:[0,1]
; #define VREADS1(arr, d_) do { const unsigned ad_ = vbase ^ (unsigned)((d_) << 6); __builtin_amdgcn_sched_barrier(0); \
;         _Pragma("unroll") for (int ks_ = 0; ks_ < 4; ++ks_) { VTR(arr[ks_ * 2], ad_, ks_ * 4096); VTR(arr[ks_ * 2 + 1], ad_, ks_ * 4096 + 2048); } __builtin_amdgcn_sched_barrier(0); } while (0)
; #define PV1(arr, d_) do { _Pragma("unroll") for (int ks_ = 0; ks_ < 4; ++ks_) { const s16x4 lo_ = arr[ks_ * 2], hh_ = arr[ks_ * 2 + 1]; \
;         const bf16x8 bv_ = (bf16x8){lo_[0], lo_[1], lo_[2], lo_[3], hh_[0], hh_[1], hh_[2], hh_[3]}; \
;         O[d_] = __builtin_amdgcn_mfma_f32_32x32x16_bf16(pa[ks_], bv_, O[d_], 0, 0, 0); } __builtin_amdgcn_sched_barrier(0); } while (0)
; #define LGKM0() do { __builtin_amdgcn_sched_barrier(0); asm volatile("s_waitcnt lgkmcnt(0)" ::: "memory"); __builtin_amdgcn_sched_barrier(0); } while (0)
; __device__ __forceinline__ void attn_unit(LAS unsigned char* lds, const bf16_t* Z, bf16_t* A2, const float* tabg, int seq_base, int S, int h, int qb, float lam) {
;     ...
;         bool near = true; float cc = 0.f;
;         if (kv0 - (qlo + 31) >= 128) { near = false; cc = tabR; } else if (qlo - (kv0 + 63) >= 128) { near = false; cc = tabL; }
;         { const float coff = cc - mu;
;           if (__any(!(coff == coff_cur))) { coff_cur = coff;
; #pragma unroll
;               for (int r = 0; r < 16; ++r) cblk[r] = coff;
;               asm volatile("" : "+v"(cblk)); } }
;     ...
;             for (int r = 0; r < 16; ++r) { p0[r] -= delta; p1[r] -= delta; }
;             asm volatile("" : "+v"(p0), "+v"(p1));
;         }
; #pragma unroll
;         for (int r = 0; r < 16; ++r) { p0[r] = __builtin_amdgcn_exp2f(p0[r]); p1[r] = __builtin_amdgcn_exp2f(p1[r]); }
; #pragma unroll
;         for (int r = 0; r < 16; r += 2) { ls2 += (f32x2){p0[r], p0[r + 1]}; ls2 += (f32x2){p1[r], p1[r + 1]}; }
;         bf16x8 pa[4]; pa[0] = pack8(p0, 0); pa[1] = pack8(p0, 8); pa[2] = pack8(p1, 0); pa[3] = pack8(p1, 8);
;         LGKM0(); VREADS1(vb, 1); PV1(va, 0); LGKM0(); VREADS1(va, 2); PV1(vb, 1); LGKM0(); VREADS1(vb, 3); PV1(va, 2); LGKM0(); PV1(vb, 3);
	v_pk_add_f32 v[204:205], v[204:205], v[252:253] neg_lo:[0,1] neg_hi:[0,1]
	v_pk_add_f32 v[206:207], v[206:207], v[252:253] neg_lo:[0,1] neg_hi:[0,1]
	v_pk_add_f32 v[208:209], v[208:209], v[252:253] neg_lo:[0,1] neg_hi:[0,1]
	v_pk_add_f32 v[210:211], v[210:211], v[252:253] neg_lo:[0,1] neg_hi:[0,1]
	v_pk_add_f32 v[212:213], v[212:213], v[252:253] neg_lo:[0,1] neg_hi:[0,1]
	v_pk_add_f32 v[214:215], v[214:215], v[252:253] neg_lo:[0,1] neg_hi:[0,1]
	v_pk_add_f32 v[216:217], v[216:217], v[252:253] neg_lo:[0,1] neg_hi:[0,1]
	v_pk_add_f32 v[218:219], v[218:219], v[252:253] neg_lo:[0,1] neg_hi:[0,1]
	v_exp_f32_e32 v84, v84
	v_exp_f32_e32 v85, v85
	v_exp_f32_e32 v86, v86
	v_exp_f32_e32 v87, v87
	v_exp_f32_e32 v88, v88
	v_add_f32_e32 v252, v84, v86
	v_add_f32_e32 v253, v85, v87
	v_exp_f32_e32 v89, v89
	v_cvt_pk_bf16_f32 v84, v84, v85
	v_cvt_pk_bf16_f32 v85, v86, v87
	v_exp_f32_e32 v90, v90
	v_exp_f32_e32 v91, v91
	v_add_f32_e32 v252, v252, v88
	v_add_f32_e32 v253, v253, v89
	v_add_f32_e32 v252, v252, v90
	v_add_f32_e32 v253, v253, v91
	v_cvt_pk_bf16_f32 v86, v88, v89
	v_cvt_pk_bf16_f32 v87, v90, v91
	v_exp_f32_e32 v92, v92
	v_exp_f32_e32 v93, v93
	v_exp_f32_e32 v94, v94
	v_exp_f32_e32 v95, v95
	v_add_f32_e32 v252, v252, v92
	v_add_f32_e32 v253, v253, v93
	v_add_f32_e32 v252, v252, v94
	v_add_f32_e32 v253, v253, v95
	v_exp_f32_e32 v96, v96
	v_exp_f32_e32 v97, v97
	v_cvt_pk_bf16_f32 v88, v92, v93
	v_cvt_pk_bf16_f32 v89, v94, v95
	v_exp_f32_e32 v98, v98
	v_exp_f32_e32 v99, v99
	v_add_f32_e32 v252, v252, v96
	v_add_f32_e32 v253, v253, v97
	v_add_f32_e32 v252, v252, v98
	v_add_f32_e32 v253, v253, v99
	v_cvt_pk_bf16_f32 v90, v96, v97
	v_cvt_pk_bf16_f32 v91, v98, v99
	v_exp_f32_e32 v100, v100
	v_exp_f32_e32 v101, v101
	v_exp_f32_e32 v102, v102
	v_exp_f32_e32 v103, v103
	v_add_f32_e32 v252, v252, v100
	v_add_f32_e32 v253, v253, v101
	v_add_f32_e32 v252, v252, v102
	v_add_f32_e32 v253, v253, v103
	v_exp_f32_e32 v104, v104
	v_exp_f32_e32 v105, v105
	v_cvt_pk_bf16_f32 v100, v100, v101
	v_cvt_pk_bf16_f32 v101, v102, v103
	v_exp_f32_e32 v106, v106
	v_exp_f32_e32 v107, v107
	v_add_f32_e32 v252, v252, v104
	v_add_f32_e32 v253, v253, v105
	v_add_f32_e32 v252, v252, v106
	v_add_f32_e32 v253, v253, v107
	v_cvt_pk_bf16_f32 v102, v104, v105
	v_cvt_pk_bf16_f32 v103, v106, v107
	v_exp_f32_e32 v108, v108
	v_exp_f32_e32 v109, v109
	v_exp_f32_e32 v110, v110
	v_exp_f32_e32 v111, v111
	v_add_f32_e32 v252, v252, v108
	v_add_f32_e32 v253, v253, v109
	v_add_f32_e32 v252, v252, v110
	v_add_f32_e32 v253, v253, v111
	v_exp_f32_e32 v112, v112
	v_exp_f32_e32 v113, v113
	v_cvt_pk_bf16_f32 v104, v108, v109
	v_cvt_pk_bf16_f32 v105, v110, v111
	v_exp_f32_e32 v114, v114
	v_exp_f32_e32 v115, v115
	v_add_f32_e32 v252, v252, v112
	v_add_f32_e32 v253, v253, v113
	v_add_f32_e32 v252, v252, v114
	v_add_f32_e32 v253, v253, v115
	v_cvt_pk_bf16_f32 v106, v112, v113
	v_cvt_pk_bf16_f32 v107, v114, v115
	s_mov_b32 s37, s43
	s_mov_b32 s35, s37
	v_mov_b32_e32 v251, 0
	s_cmp_eq_u32 s37, 1
	s_cselect_b64 vcc, -1, 0
	v_cndmask_b32_e32 v251, v251, v177, vcc
	s_cmp_eq_u32 s37, 2
	s_cselect_b64 vcc, -1, 0
	v_cndmask_b32_e32 v251, v251, v178, vcc
	v_sub_f32_e32 v2, v251, v186
	v_mov_b32_e32 v3, v2
	v_mov_b64_e32 v[4:5], v[2:3]
	v_mov_b64_e32 v[6:7], v[2:3]
	v_mov_b64_e32 v[8:9], v[2:3]
	v_mov_b64_e32 v[10:11], v[2:3]
	v_mov_b64_e32 v[12:13], v[2:3]
	v_mov_b64_e32 v[14:15], v[2:3]
	v_mov_b64_e32 v[16:17], v[2:3]
	ds_read_b64_tr_b16 v[132:133], v228 offset:0
	ds_read_b64_tr_b16 v[134:135], v228 offset:2048
	ds_read_b64_tr_b16 v[136:137], v229 offset:0
	ds_read_b64_tr_b16 v[138:139], v229 offset:2048
	ds_read_b64_tr_b16 v[140:141], v230 offset:0
	ds_read_b64_tr_b16 v[142:143], v230 offset:2048
	ds_read_b64_tr_b16 v[144:145], v231 offset:0
	ds_read_b64_tr_b16 v[146:147], v231 offset:2048
	ds_read_b64_tr_b16 v[220:221], v228 offset:4096
	ds_read_b64_tr_b16 v[222:223], v228 offset:6144
	ds_read_b64_tr_b16 v[224:225], v229 offset:4096
	ds_read_b64_tr_b16 v[226:227], v229 offset:6144
	ds_read_b64_tr_b16 v[232:233], v230 offset:4096
	ds_read_b64_tr_b16 v[234:235], v230 offset:6144
	s_nop 1
	s_cmp_eq_u32 s42, 0
	s_cbranch_scc1 .LatA_recret_h0
	s_cmp_eq_u32 s42, 1
	s_cbranch_scc1 .LatA_recret_m0
	s_branch .LatA_recret_x4

; #define LAS __attribute__((address_space(3)))
; __device__ __forceinline__ float max2f(float a, float b) { float r; asm("v_max_f32_e32 %0, %1, %2" : "=v"(r) : "v"(a), "v"(b)); return r; }
; __device__ __forceinline__ void attn_unit(LAS unsigned char* lds, const bf16_t* Z, bf16_t* A2, const float* tabg, int seq_base, int S, int h, int qb, float lam) {
;     ...
;         float mx = max2f(max16f(p0), max16f(p1));
;         const bool first = (t == 0);
;         if (first || __any(mx > THR)) {
;             { auto rr = __builtin_amdgcn_permlane32_swap(__float_as_uint(mx), __float_as_uint(mx), false, false); mx = max2f(__uint_as_float(rr[0]), __uint_as_float(rr[1])); }
;             const float delta = first ? mx : fmaxf(mx, 0.f);
;             const float alpha = first ? 1.0f : __builtin_amdgcn_exp2f(-delta);
;             mu += delta; ls2 *= alpha;
;             if (!first) {
;                 asm volatile("" ::: "memory");
;                 scr[r32] = alpha;
;                 asm volatile("s_waitcnt lgkmcnt(0)" ::: "memory");
; #pragma unroll
;                 for (int g = 0; g < 4; ++g) { const f32x4 a4 = *(const LAS f32x4*)(scr + 8 * g + 4 * hi);
; #pragma unroll
;                     for (int d = 0; d < 4; ++d) { O[d][4 * g + 0] *= a4[0]; O[d][4 * g + 1] *= a4[1]; O[d][4 * g + 2] *= a4[2]; O[d][4 * g + 3] *= a4[3]; } }
;                 asm volatile("s_waitcnt lgkmcnt(0)" ::: "memory");
;             }
; #pragma unroll
;             for (int r = 0; r < 16; ++r) { p0[r] -= delta; p1[r] -= delta; }
.LatA_recnn_1:
	v_max3_f32 v251, v188, v189, v190
	v_max3_f32 v252, v191, v192, v193
	v_max3_f32 v251, v251, v194, v195
	v_max3_f32 v252, v252, v196, v197
	v_max3_f32 v251, v251, v198, v199
	v_max3_f32 v252, v252, v200, v201
	v_max3_f32 v251, v251, v202, v203
	v_max3_f32 v252, v252, v204, v205
	v_max3_f32 v251, v251, v206, v207
	v_max3_f32 v252, v252, v208, v209
	v_max3_f32 v251, v251, v210, v211
	v_max3_f32 v252, v252, v212, v213
	v_max3_f32 v251, v251, v214, v215
	v_max3_f32 v252, v252, v216, v217
	v_max3_f32 v251, v251, v218, v219
	v_max_f32_e32 v251, v251, v252
	v_mov_b32_e32 v252, v251
	s_nop 1
	v_permlane32_swap_b32_e32 v251, v252
	v_max_f32_e32 v251, v251, v252
	v_max_f32_e32 v253, 0, v251
	v_exp_f32_e64 v254, -v253
	v_add_f32_e32 v186, v186, v253
	s_nop 0
	v_mul_f32_e32 v150, v150, v254
	v_mul_f32_e32 v151, v151, v254
	ds_write_b32 v184, v254
	s_waitcnt lgkmcnt(0)
	ds_read_b128 v[132:135], v185
	ds_read_b128 v[136:139], v185 offset:32
	ds_read_b128 v[140:143], v185 offset:64
	ds_read_b128 v[144:147], v185 offset:96
	s_waitcnt lgkmcnt(0)
	v_pk_mul_f32 v[20:21], v[20:21], v[132:133]
	v_pk_mul_f32 v[22:23], v[22:23], v[134:135]
	v_pk_mul_f32 v[24:25], v[24:25], v[136:137]
	v_pk_mul_f32 v[26:27], v[26:27], v[138:139]
	v_pk_mul_f32 v[28:29], v[28:29], v[140:141]
	v_pk_mul_f32 v[30:31], v[30:31], v[142:143]
	v_pk_mul_f32 v[32:33], v[32:33], v[144:145]
	v_pk_mul_f32 v[34:35], v[34:35], v[146:147]
	v_pk_mul_f32 v[36:37], v[36:37], v[132:133]
	v_pk_mul_f32 v[38:39], v[38:39], v[134:135]
	v_pk_mul_f32 v[40:41], v[40:41], v[136:137]
	v_pk_mul_f32 v[42:43], v[42:43], v[138:139]
	v_pk_mul_f32 v[44:45], v[44:45], v[140:141]
	v_pk_mul_f32 v[46:47], v[46:47], v[142:143]
	v_pk_mul_f32 v[48:49], v[48:49], v[144:145]
	v_pk_mul_f32 v[50:51], v[50:51], v[146:147]
	v_pk_mul_f32 v[52:53], v[52:53], v[132:133]
	v_pk_mul_f32 v[54:55], v[54:55], v[134:135]
	v_pk_mul_f32 v[56:57], v[56:57], v[136:137]
	v_pk_mul_f32 v[58:59], v[58:59], v[138:139]
	v_pk_mul_f32 v[60:61], v[60:61], v[140:141]
	v_pk_mul_f32 v[62:63], v[62:63], v[142:143]
	v_pk_mul_f32 v[64:65], v[64:65], v[144:145]
	v_pk_mul_f32 v[66:67], v[66:67], v[146:147]
	v_pk_mul_f32 v[68:69], v[68:69], v[132:133]
	v_pk_mul_f32 v[70:71], v[70:71], v[134:135]
	v_pk_mul_f32 v[72:73], v[72:73], v[136:137]
	v_pk_mul_f32 v[74:75], v[74:75], v[138:139]
	v_pk_mul_f32 v[76:77], v[76:77], v[140:141]
	v_pk_mul_f32 v[78:79], v[78:79], v[142:143]
	v_pk_mul_f32 v[80:81], v[80:81], v[144:145]
	v_pk_mul_f32 v[82:83], v[82:83], v[146:147]
	v_mov_b32_e32 v252, v253
	v_pk_add_f32 v[188:189], v[188:189], v[252:253] neg_lo:[0,1] neg_hi:[0,1]
	v_pk_add_f32 v[190:191], v[190:191], v[252:253] neg_lo:[0,1] neg_hi:[0,1]
	v_pk_add_f32 v[192:193], v[192:193], v[252:253] neg_lo:[0,1] neg_hi:[0,1]
	v_pk_add_f32 v[194:195], v[194:195], v[252:253] neg_lo:[0,1] neg_hi:[0,1]
	v_pk_add_f32 v[196:197], v[196:197], v[252:253] neg_lo:[0,1] neg_hi:[0,1]
	v_pk_add_f32 v[198:199], v[198:199], v[252:253] neg_lo:[0,1] neg_hi:[0,1]
	v_pk_add_f32 v[200:201], v[200:201], v[252:253] neg_lo:[0,1] neg_hi:[0,1]
	v_pk_add_f32 v[202:203], v[202:203], v[252:253] neg_lo:[0,1] neg_hi:[0,1]
	v_pk_add_f32 v[204:205], v[204:205], v[252:253] neg_lo:[0,1] neg_hi:[0,1]
	v_pk_add_f32 v[206:207], v[206:207], v[252:253] neg_lo:[0,1] neg_hi:[0,1]
	v_pk_add_f32 v[208:209], v[208:209], v[252:253] neg_lo:[0,1] neg_hi:[0,1]
	v_pk_add_f32 v[210:211], v[210:211], v[252:253] neg_lo:[0,1] neg_hi:[0,1]
	v_pk_add_f32 v[212:213], v[212:213], v[252:253] neg_lo:[0,1] neg_hi:[0,1]
	v_pk_add_f32 v[214:215], v[214:215], v[252:253] neg_lo:[0,1] neg_hi:[0,1]
	v_pk_add_f32 v[216:217], v[216:217], v[252:253] neg_lo:[0,1] neg_hi:[0,1]
	v_pk_add_f32 v[218:219], v[218:219], v[252:253] neg_lo:[0,1] neg_hi:[0,1]
	v_pk_add_f32 v[84:85], v[84:85], v[252:253] neg_lo:[0,1] neg_hi:[0,1]
	v_pk_add_f32 v[86:87], v[86:87], v[252:253] neg_lo:[0,1] neg_hi:[0,1]
	v_pk_add_f32 v[88:89], v[88:89], v[252:253] neg_lo:[0,1] neg_hi:[0,1]
	v_pk_add_f32 v[90:91], v[90:91], v[252:253] neg_lo:[0,1] neg_hi:[0,1]
	v_pk_add_f32 v[92:93], v[92:93], v[252:253] neg_lo:[0,1] neg_hi:[0,1]
	v_pk_add_f32 v[94:95], v[94:95], v[252:253] neg_lo:[0,1] neg_hi:[0,1]
	v_pk_add_f32 v[96:97], v[96:97], v[252:253] neg_lo:[0,1] neg_hi:[0,1]
	v_pk_add_f32 v[98:99], v[98:99], v[252:253] neg_lo:[0,1] neg_hi:[0,1]
; #define VREADS1(arr, d_) do { const unsigned ad_ = vbase ^ (unsigned)((d_) << 6); __builtin_amdgcn_sched_barrier(0); \
;         _Pragma("unroll") for (int ks_ = 0; ks_ < 4; ++ks_) { VTR(arr[ks_ * 2], ad_, ks_ * 4096); VTR(arr[ks_ * 2 + 1], ad_, ks_ * 4096 + 2048); } __builtin_amdgcn_sched_barrier(0); } while (0)
; #define PV1(arr, d_) do { _Pragma("unroll") for (int ks_ = 0; ks_ < 4; ++ks_) { const s16x4 lo_ = arr[ks_ * 2], hh_ = arr[ks_ * 2 + 1]; \
;         const bf16x8 bv_ = (bf16x8){lo_[0], lo_[1], lo_[2], lo_[3], hh_[0], hh_[1], hh_[2], hh_[3]}; \
;         O[d_] = __builtin_amdgcn_mfma_f32_32x32x16_bf16(pa[ks_], bv_, O[d_], 0, 0, 0); } __builtin_amdgcn_sched_barrier(0); } while (0)
; #define LGKM0() do { __builtin_amdgcn_sched_barrier(0); asm volatile("s_waitcnt lgkmcnt(0)" ::: "memory"); __builtin_amdgcn_sched_barrier(0); } while (0)
; __device__ __forceinline__ void attn_unit(LAS unsigned char* lds, const bf16_t* Z, bf16_t* A2, const float* tabg, int seq_base, int S, int h, int qb, float lam) {
;     ...
;         bool near = true; float cc = 0.f;
;         if (kv0 - (qlo + 31) >= 128) { near = false; cc = tabR; } else if (qlo - (kv0 + 63) >= 128) { near = false; cc = tabL; }
;         { const float coff = cc - mu;
;           if (__any(!(coff == coff_cur))) { coff_cur = coff;
; #pragma unroll
;               for (int r = 0; r < 16; ++r) cblk[r] = coff;
;               asm volatile("" : "+v"(cblk)); } }
;     ...
;             for (int r = 0; r < 16; ++r) { p0[r] -= delta; p1[r] -= delta; }
;             asm volatile("" : "+v"(p0), "+v"(p1));
;         }
; #pragma unroll
;         for (int r = 0; r < 16; ++r) { p0[r] = __builtin_amdgcn_exp2f(p0[r]); p1[r] = __builtin_amdgcn_exp2f(p1[r]); }
; #pragma unroll
;         for (int r = 0; r < 16; r += 2) { ls2 += (f32x2){p0[r], p0[r + 1]}; ls2 += (f32x2){p1[r], p1[r + 1]}; }
;         bf16x8 pa[4]; pa[0] = pack8(p0, 0); pa[1] = pack8(p0, 8); pa[2] = pack8(p1, 0); pa[3] = pack8(p1, 8);
;         LGKM0(); VREADS1(vb, 1); PV1(va, 0); LGKM0(); VREADS1(va, 2); PV1(vb, 1); LGKM0(); VREADS1(vb, 3); PV1(va, 2); LGKM0(); PV1(vb, 3);
	v_pk_add_f32 v[100:101], v[100:101], v[252:253] neg_lo:[0,1] neg_hi:[0,1]
	v_pk_add_f32 v[102:103], v[102:103], v[252:253] neg_lo:[0,1] neg_hi:[0,1]
	v_pk_add_f32 v[104:105], v[104:105], v[252:253] neg_lo:[0,1] neg_hi:[0,1]
	v_pk_add_f32 v[106:107], v[106:107], v[252:253] neg_lo:[0,1] neg_hi:[0,1]
	v_pk_add_f32 v[108:109], v[108:109], v[252:253] neg_lo:[0,1] neg_hi:[0,1]
	v_pk_add_f32 v[110:111], v[110:111], v[252:253] neg_lo:[0,1] neg_hi:[0,1]
	v_pk_add_f32 v[112:113], v[112:113], v[252:253] neg_lo:[0,1] neg_hi:[0,1]
	v_pk_add_f32 v[114:115], v[114:115], v[252:253] neg_lo:[0,1] neg_hi:[0,1]
	v_exp_f32_e32 v188, v188
	v_exp_f32_e32 v189, v189
	v_exp_f32_e32 v190, v190
	v_exp_f32_e32 v191, v191
	v_exp_f32_e32 v192, v192
	v_add_f32_e32 v252, v188, v190
	v_add_f32_e32 v253, v189, v191
	v_exp_f32_e32 v193, v193
	v_cvt_pk_bf16_f32 v188, v188, v189
	v_cvt_pk_bf16_f32 v189, v190, v191
	v_exp_f32_e32 v194, v194
	v_exp_f32_e32 v195, v195
	v_add_f32_e32 v252, v252, v192
	v_add_f32_e32 v253, v253, v193
	v_add_f32_e32 v252, v252, v194
	v_add_f32_e32 v253, v253, v195
	v_cvt_pk_bf16_f32 v190, v192, v193
	v_cvt_pk_bf16_f32 v191, v194, v195
	v_exp_f32_e32 v196, v196
	v_exp_f32_e32 v197, v197
	v_exp_f32_e32 v198, v198
	v_exp_f32_e32 v199, v199
	v_add_f32_e32 v252, v252, v196
	v_add_f32_e32 v253, v253, v197
	v_add_f32_e32 v252, v252, v198
	v_add_f32_e32 v253, v253, v199
	v_exp_f32_e32 v200, v200
	v_exp_f32_e32 v201, v201
	v_cvt_pk_bf16_f32 v192, v196, v197
	v_cvt_pk_bf16_f32 v193, v198, v199
	v_exp_f32_e32 v202, v202
	v_exp_f32_e32 v203, v203
	v_add_f32_e32 v252, v252, v200
	v_add_f32_e32 v253, v253, v201
	v_add_f32_e32 v252, v252, v202
	v_add_f32_e32 v253, v253, v203
	v_cvt_pk_bf16_f32 v194, v200, v201
	v_cvt_pk_bf16_f32 v195, v202, v203
	v_exp_f32_e32 v204, v204
	v_exp_f32_e32 v205, v205
	v_exp_f32_e32 v206, v206
	v_exp_f32_e32 v207, v207
	v_add_f32_e32 v252, v252, v204
	v_add_f32_e32 v253, v253, v205
	v_add_f32_e32 v252, v252, v206
	v_add_f32_e32 v253, v253, v207
	v_exp_f32_e32 v208, v208
	v_exp_f32_e32 v209, v209
	v_cvt_pk_bf16_f32 v204, v204, v205
	v_cvt_pk_bf16_f32 v205, v206, v207
	v_exp_f32_e32 v210, v210
	v_exp_f32_e32 v211, v211
	v_add_f32_e32 v252, v252, v208
	v_add_f32_e32 v253, v253, v209
	v_add_f32_e32 v252, v252, v210
	v_add_f32_e32 v253, v253, v211
	v_cvt_pk_bf16_f32 v206, v208, v209
	v_cvt_pk_bf16_f32 v207, v210, v211
	v_exp_f32_e32 v212, v212
	v_exp_f32_e32 v213, v213
	v_exp_f32_e32 v214, v214
	v_exp_f32_e32 v215, v215
	v_add_f32_e32 v252, v252, v212
	v_add_f32_e32 v253, v253, v213
	v_add_f32_e32 v252, v252, v214
	v_add_f32_e32 v253, v253, v215
	v_exp_f32_e32 v216, v216
	v_exp_f32_e32 v217, v217
	v_cvt_pk_bf16_f32 v208, v212, v213
	v_cvt_pk_bf16_f32 v209, v214, v215
	v_exp_f32_e32 v218, v218
	v_exp_f32_e32 v219, v219
	v_add_f32_e32 v252, v252, v216
	v_add_f32_e32 v253, v253, v217
	v_add_f32_e32 v252, v252, v218
	v_add_f32_e32 v253, v253, v219
	v_cvt_pk_bf16_f32 v210, v216, v217
	v_cvt_pk_bf16_f32 v211, v218, v219
	s_mov_b32 s37, s43
	s_mov_b32 s35, s37
	v_mov_b32_e32 v251, 0
	s_cmp_eq_u32 s37, 1
	s_cselect_b64 vcc, -1, 0
	v_cndmask_b32_e32 v251, v251, v177, vcc
	s_cmp_eq_u32 s37, 2
	s_cselect_b64 vcc, -1, 0
	v_cndmask_b32_e32 v251, v251, v178, vcc
	v_sub_f32_e32 v2, v251, v186
	v_mov_b32_e32 v3, v2
	v_mov_b64_e32 v[4:5], v[2:3]
	v_mov_b64_e32 v[6:7], v[2:3]
	v_mov_b64_e32 v[8:9], v[2:3]
	v_mov_b64_e32 v[10:11], v[2:3]
	v_mov_b64_e32 v[12:13], v[2:3]
	v_mov_b64_e32 v[14:15], v[2:3]
	v_mov_b64_e32 v[16:17], v[2:3]
	ds_read_b64_tr_b16 v[132:133], v228 offset:16384
	ds_read_b64_tr_b16 v[134:135], v228 offset:18432
	ds_read_b64_tr_b16 v[136:137], v229 offset:16384
	ds_read_b64_tr_b16 v[138:139], v229 offset:18432
	ds_read_b64_tr_b16 v[140:141], v230 offset:16384
	ds_read_b64_tr_b16 v[142:143], v230 offset:18432
	ds_read_b64_tr_b16 v[144:145], v231 offset:16384
	ds_read_b64_tr_b16 v[146:147], v231 offset:18432
	ds_read_b64_tr_b16 v[220:221], v228 offset:20480
	ds_read_b64_tr_b16 v[222:223], v228 offset:22528
	ds_read_b64_tr_b16 v[224:225], v229 offset:20480
	ds_read_b64_tr_b16 v[226:227], v229 offset:22528
	ds_read_b64_tr_b16 v[232:233], v230 offset:20480
	ds_read_b64_tr_b16 v[234:235], v230 offset:22528
	s_nop 1
	s_cmp_eq_u32 s42, 0
	s_cbranch_scc1 .LatA_recret_h1
	s_cmp_eq_u32 s42, 1
	s_cbranch_scc1 .LatA_recret_m1
	s_branch .LatA_recret_x3

; #define LAS __attribute__((address_space(3)))
; __device__ __forceinline__ float max2f(float a, float b) { float r; asm("v_max_f32_e32 %0, %1, %2" : "=v"(r) : "v"(a), "v"(b)); return r; }
; __device__ __forceinline__ void attn_unit(LAS unsigned char* lds, const bf16_t* Z, bf16_t* A2, const float* tabg, int seq_base, int S, int h, int qb, float lam) {
;     ...
;         float mx = max2f(max16f(p0), max16f(p1));
;         const bool first = (t == 0);
;         if (first || __any(mx > THR)) {
;             { auto rr = __builtin_amdgcn_permlane32_swap(__float_as_uint(mx), __float_as_uint(mx), false, false); mx = max2f(__uint_as_float(rr[0]), __uint_as_float(rr[1])); }
;             const float delta = first ? mx : fmaxf(mx, 0.f);
;             const float alpha = first ? 1.0f : __builtin_amdgcn_exp2f(-delta);
;             mu += delta; ls2 *= alpha;
;             if (!first) {
;                 asm volatile("" ::: "memory");
;                 scr[r32] = alpha;
;                 asm volatile("s_waitcnt lgkmcnt(0)" ::: "memory");
; #pragma unroll
;                 for (int g = 0; g < 4; ++g) { const f32x4 a4 = *(const LAS f32x4*)(scr + 8 * g + 4 * hi);
; #pragma unroll
;                     for (int d = 0; d < 4; ++d) { O[d][4 * g + 0] *= a4[0]; O[d][4 * g + 1] *= a4[1]; O[d][4 * g + 2] *= a4[2]; O[d][4 * g + 3] *= a4[3]; } }
;                 asm volatile("s_waitcnt lgkmcnt(0)" ::: "memory");
;             }
; #pragma unroll
;             for (int r = 0; r < 16; ++r) { p0[r] -= delta; p1[r] -= delta; }
.LatA_recnn_2:
	v_max3_f32 v251, v84, v85, v86
	v_max3_f32 v252, v87, v88, v89
	v_max3_f32 v251, v251, v90, v91
	v_max3_f32 v252, v252, v92, v93
	v_max3_f32 v251, v251, v94, v95
	v_max3_f32 v252, v252, v96, v97
	v_max3_f32 v251, v251, v98, v99
	v_max3_f32 v252, v252, v100, v101
	v_max3_f32 v251, v251, v102, v103
	v_max3_f32 v252, v252, v104, v105
	v_max3_f32 v251, v251, v106, v107
	v_max3_f32 v252, v252, v108, v109
	v_max3_f32 v251, v251, v110, v111
	v_max3_f32 v252, v252, v112, v113
	v_max3_f32 v251, v251, v114, v115
	v_max_f32_e32 v251, v251, v252
	v_mov_b32_e32 v252, v251
	s_nop 1
	v_permlane32_swap_b32_e32 v251, v252
	v_max_f32_e32 v251, v251, v252
	v_max_f32_e32 v253, 0, v251
	v_exp_f32_e64 v254, -v253
	v_add_f32_e32 v186, v186, v253
	s_nop 0
	v_mul_f32_e32 v150, v150, v254
	v_mul_f32_e32 v151, v151, v254
	ds_write_b32 v184, v254
	s_waitcnt lgkmcnt(0)
	ds_read_b128 v[132:135], v185
	ds_read_b128 v[136:139], v185 offset:32
	ds_read_b128 v[140:143], v185 offset:64
	ds_read_b128 v[144:147], v185 offset:96
	s_waitcnt lgkmcnt(0)
	v_pk_mul_f32 v[20:21], v[20:21], v[132:133]
	v_pk_mul_f32 v[22:23], v[22:23], v[134:135]
	v_pk_mul_f32 v[24:25], v[24:25], v[136:137]
	v_pk_mul_f32 v[26:27], v[26:27], v[138:139]
	v_pk_mul_f32 v[28:29], v[28:29], v[140:141]
	v_pk_mul_f32 v[30:31], v[30:31], v[142:143]
	v_pk_mul_f32 v[32:33], v[32:33], v[144:145]
	v_pk_mul_f32 v[34:35], v[34:35], v[146:147]
	v_pk_mul_f32 v[36:37], v[36:37], v[132:133]
	v_pk_mul_f32 v[38:39], v[38:39], v[134:135]
	v_pk_mul_f32 v[40:41], v[40:41], v[136:137]
	v_pk_mul_f32 v[42:43], v[42:43], v[138:139]
	v_pk_mul_f32 v[44:45], v[44:45], v[140:141]
	v_pk_mul_f32 v[46:47], v[46:47], v[142:143]
	v_pk_mul_f32 v[48:49], v[48:49], v[144:145]
	v_pk_mul_f32 v[50:51], v[50:51], v[146:147]
	v_pk_mul_f32 v[52:53], v[52:53], v[132:133]
	v_pk_mul_f32 v[54:55], v[54:55], v[134:135]
	v_pk_mul_f32 v[56:57], v[56:57], v[136:137]
	v_pk_mul_f32 v[58:59], v[58:59], v[138:139]
	v_pk_mul_f32 v[60:61], v[60:61], v[140:141]
	v_pk_mul_f32 v[62:63], v[62:63], v[142:143]
	v_pk_mul_f32 v[64:65], v[64:65], v[144:145]
	v_pk_mul_f32 v[66:67], v[66:67], v[146:147]
	v_pk_mul_f32 v[68:69], v[68:69], v[132:133]
	v_pk_mul_f32 v[70:71], v[70:71], v[134:135]
	v_pk_mul_f32 v[72:73], v[72:73], v[136:137]
	v_pk_mul_f32 v[74:75], v[74:75], v[138:139]
	v_pk_mul_f32 v[76:77], v[76:77], v[140:141]
	v_pk_mul_f32 v[78:79], v[78:79], v[142:143]
	v_pk_mul_f32 v[80:81], v[80:81], v[144:145]
	v_pk_mul_f32 v[82:83], v[82:83], v[146:147]
	v_mov_b32_e32 v252, v253
	v_pk_add_f32 v[84:85], v[84:85], v[252:253] neg_lo:[0,1] neg_hi:[0,1]
	v_pk_add_f32 v[86:87], v[86:87], v[252:253] neg_lo:[0,1] neg_hi:[0,1]
	v_pk_add_f32 v[88:89], v[88:89], v[252:253] neg_lo:[0,1] neg_hi:[0,1]
	v_pk_add_f32 v[90:91], v[90:91], v[252:253] neg_lo:[0,1] neg_hi:[0,1]
	v_pk_add_f32 v[92:93], v[92:93], v[252:253] neg_lo:[0,1] neg_hi:[0,1]
	v_pk_add_f32 v[94:95], v[94:95], v[252:253] neg_lo:[0,1] neg_hi:[0,1]
	v_pk_add_f32 v[96:97], v[96:97], v[252:253] neg_lo:[0,1] neg_hi:[0,1]
	v_pk_add_f32 v[98:99], v[98:99], v[252:253] neg_lo:[0,1] neg_hi:[0,1]
	v_pk_add_f32 v[100:101], v[100:101], v[252:253] neg_lo:[0,1] neg_hi:[0,1]
	v_pk_add_f32 v[102:103], v[102:103], v[252:253] neg_lo:[0,1] neg_hi:[0,1]
	v_pk_add_f32 v[104:105], v[104:105], v[252:253] neg_lo:[0,1] neg_hi:[0,1]
	v_pk_add_f32 v[106:107], v[106:107], v[252:253] neg_lo:[0,1] neg_hi:[0,1]
	v_pk_add_f32 v[108:109], v[108:109], v[252:253] neg_lo:[0,1] neg_hi:[0,1]
	v_pk_add_f32 v[110:111], v[110:111], v[252:253] neg_lo:[0,1] neg_hi:[0,1]
	v_pk_add_f32 v[112:113], v[112:113], v[252:253] neg_lo:[0,1] neg_hi:[0,1]
	v_pk_add_f32 v[114:115], v[114:115], v[252:253] neg_lo:[0,1] neg_hi:[0,1]
	v_pk_add_f32 v[188:189], v[188:189], v[252:253] neg_lo:[0,1] neg_hi:[0,1]
	v_pk_add_f32 v[190:191], v[190:191], v[252:253] neg_lo:[0,1] neg_hi:[0,1]
	v_pk_add_f32 v[192:193], v[192:193], v[252:253] neg_lo:[0,1] neg_hi:[0,1]
	v_pk_add_f32 v[194:195], v[194:195], v[252:253] neg_lo:[0,1] neg_hi:[0,1]
	v_pk_add_f32 v[196:197], v[196:197], v[252:253] neg_lo:[0,1] neg_hi:[0,1]
	v_pk_add_f32 v[198:199], v[198:199], v[252:253] neg_lo:[0,1] neg_hi:[0,1]
	v_pk_add_f32 v[200:201], v[200:201], v[252:253] neg_lo:[0,1] neg_hi:[0,1]
	v_pk_add_f32 v[202:203], v[202:203], v[252:253] neg_lo:[0,1] neg_hi:[0,1]
; #define VREADS1(arr, d_) do { const unsigned ad_ = vbase ^ (unsigned)((d_) << 6); __builtin_amdgcn_sched_barrier(0); \
;         _Pragma("unroll") for (int ks_ = 0; ks_ < 4; ++ks_) { VTR(arr[ks_ * 2], ad_, ks_ * 4096); VTR(arr[ks_ * 2 + 1], ad_, ks_ * 4096 + 2048); } __builtin_amdgcn_sched_barrier(0); } while (0)
; #define PV1(arr, d_) do { _Pragma("unroll") for (int ks_ = 0; ks_ < 4; ++ks_) { const s16x4 lo_ = arr[ks_ * 2], hh_ = arr[ks_ * 2 + 1]; \
;         const bf16x8 bv_ = (bf16x8){lo_[0], lo_[1], lo_[2], lo_[3], hh_[0], hh_[1], hh_[2], hh_[3]}; \
;         O[d_] = __builtin_amdgcn_mfma_f32_32x32x16_bf16(pa[ks_], bv_, O[d_], 0, 0, 0); } __builtin_amdgcn_sched_barrier(0); } while (0)
; #define LGKM0() do { __builtin_amdgcn_sched_barrier(0); asm volatile("s_waitcnt lgkmcnt(0)" ::: "memory"); __builtin_amdgcn_sched_barrier(0); } while (0)
; __device__ __forceinline__ void attn_unit(LAS unsigned char* lds, const bf16_t* Z, bf16_t* A2, const float* tabg, int seq_base, int S, int h, int qb, float lam) {
;     ...
;         bool near = true; float cc = 0.f;
;         if (kv0 - (qlo + 31) >= 128) { near = false; cc = tabR; } else if (qlo - (kv0 + 63) >= 128) { near = false; cc = tabL; }
;         { const float coff = cc - mu;
;           if (__any(!(coff == coff_cur))) { coff_cur = coff;
; #pragma unroll
;               for (int r = 0; r < 16; ++r) cblk[r] = coff;
;               asm volatile("" : "+v"(cblk)); } }
;     ...
;             for (int r = 0; r < 16; ++r) { p0[r] -= delta; p1[r] -= delta; }
;             asm volatile("" : "+v"(p0), "+v"(p1));
;         }
; #pragma unroll
;         for (int r = 0; r < 16; ++r) { p0[r] = __builtin_amdgcn_exp2f(p0[r]); p1[r] = __builtin_amdgcn_exp2f(p1[r]); }
; #pragma unroll
;         for (int r = 0; r < 16; r += 2) { ls2 += (f32x2){p0[r], p0[r + 1]}; ls2 += (f32x2){p1[r], p1[r + 1]}; }
;         bf16x8 pa[4]; pa[0] = pack8(p0, 0); pa[1] = pack8(p0, 8); pa[2] = pack8(p1, 0); pa[3] = pack8(p1, 8);
;         LGKM0(); VREADS1(vb, 1); PV1(va, 0); LGKM0(); VREADS1(va, 2); PV1(vb, 1); LGKM0(); VREADS1(vb, 3); PV1(va, 2); LGKM0(); PV1(vb, 3);
	v_pk_add_f32 v[204:205], v[204:205], v[252:253] neg_lo:[0,1] neg_hi:[0,1]
	v_pk_add_f32 v[206:207], v[206:207], v[252:253] neg_lo:[0,1] neg_hi:[0,1]
	v_pk_add_f32 v[208:209], v[208:209], v[252:253] neg_lo:[0,1] neg_hi:[0,1]
	v_pk_add_f32 v[210:211], v[210:211], v[252:253] neg_lo:[0,1] neg_hi:[0,1]
	v_pk_add_f32 v[212:213], v[212:213], v[252:253] neg_lo:[0,1] neg_hi:[0,1]
	v_pk_add_f32 v[214:215], v[214:215], v[252:253] neg_lo:[0,1] neg_hi:[0,1]
	v_pk_add_f32 v[216:217], v[216:217], v[252:253] neg_lo:[0,1] neg_hi:[0,1]
	v_pk_add_f32 v[218:219], v[218:219], v[252:253] neg_lo:[0,1] neg_hi:[0,1]
	v_exp_f32_e32 v84, v84
	v_exp_f32_e32 v85, v85
	v_exp_f32_e32 v86, v86
	v_exp_f32_e32 v87, v87
	v_exp_f32_e32 v88, v88
	v_add_f32_e32 v252, v84, v86
	v_add_f32_e32 v253, v85, v87
	v_exp_f32_e32 v89, v89
	v_cvt_pk_bf16_f32 v84, v84, v85
	v_cvt_pk_bf16_f32 v85, v86, v87
	v_exp_f32_e32 v90, v90
	v_exp_f32_e32 v91, v91
	v_add_f32_e32 v252, v252, v88
	v_add_f32_e32 v253, v253, v89
	v_add_f32_e32 v252, v252, v90
	v_add_f32_e32 v253, v253, v91
	v_cvt_pk_bf16_f32 v86, v88, v89
	v_cvt_pk_bf16_f32 v87, v90, v91
	v_exp_f32_e32 v92, v92
	v_exp_f32_e32 v93, v93
	v_exp_f32_e32 v94, v94
	v_exp_f32_e32 v95, v95
	v_add_f32_e32 v252, v252, v92
	v_add_f32_e32 v253, v253, v93
	v_add_f32_e32 v252, v252, v94
	v_add_f32_e32 v253, v253, v95
	v_exp_f32_e32 v96, v96
	v_exp_f32_e32 v97, v97
	v_cvt_pk_bf16_f32 v88, v92, v93
	v_cvt_pk_bf16_f32 v89, v94, v95
	v_exp_f32_e32 v98, v98
	v_exp_f32_e32 v99, v99
	v_add_f32_e32 v252, v252, v96
	v_add_f32_e32 v253, v253, v97
	v_add_f32_e32 v252, v252, v98
	v_add_f32_e32 v253, v253, v99
	v_cvt_pk_bf16_f32 v90, v96, v97
	v_cvt_pk_bf16_f32 v91, v98, v99
	v_exp_f32_e32 v100, v100
	v_exp_f32_e32 v101, v101
	v_exp_f32_e32 v102, v102
	v_exp_f32_e32 v103, v103
	v_add_f32_e32 v252, v252, v100
	v_add_f32_e32 v253, v253, v101
	v_add_f32_e32 v252, v252, v102
	v_add_f32_e32 v253, v253, v103
	v_exp_f32_e32 v104, v104
	v_exp_f32_e32 v105, v105
	v_cvt_pk_bf16_f32 v100, v100, v101
	v_cvt_pk_bf16_f32 v101, v102, v103
	v_exp_f32_e32 v106, v106
	v_exp_f32_e32 v107, v107
	v_add_f32_e32 v252, v252, v104
	v_add_f32_e32 v253, v253, v105
	v_add_f32_e32 v252, v252, v106
	v_add_f32_e32 v253, v253, v107
	v_cvt_pk_bf16_f32 v102, v104, v105
	v_cvt_pk_bf16_f32 v103, v106, v107
	v_exp_f32_e32 v108, v108
	v_exp_f32_e32 v109, v109
	v_exp_f32_e32 v110, v110
	v_exp_f32_e32 v111, v111
	v_add_f32_e32 v252, v252, v108
	v_add_f32_e32 v253, v253, v109
	v_add_f32_e32 v252, v252, v110
	v_add_f32_e32 v253, v253, v111
	v_exp_f32_e32 v112, v112
	v_exp_f32_e32 v113, v113
	v_cvt_pk_bf16_f32 v104, v108, v109
	v_cvt_pk_bf16_f32 v105, v110, v111
	v_exp_f32_e32 v114, v114
	v_exp_f32_e32 v115, v115
	v_add_f32_e32 v252, v252, v112
	v_add_f32_e32 v253, v253, v113
	v_add_f32_e32 v252, v252, v114
	v_add_f32_e32 v253, v253, v115
	v_cvt_pk_bf16_f32 v106, v112, v113
	v_cvt_pk_bf16_f32 v107, v114, v115
	s_mov_b32 s37, s43
	s_mov_b32 s35, s37
	v_mov_b32_e32 v251, 0
	s_cmp_eq_u32 s37, 1
	s_cselect_b64 vcc, -1, 0
	v_cndmask_b32_e32 v251, v251, v177, vcc
	s_cmp_eq_u32 s37, 2
	s_cselect_b64 vcc, -1, 0
	v_cndmask_b32_e32 v251, v251, v178, vcc
	v_sub_f32_e32 v2, v251, v186
	v_mov_b32_e32 v3, v2
	v_mov_b64_e32 v[4:5], v[2:3]
	v_mov_b64_e32 v[6:7], v[2:3]
	v_mov_b64_e32 v[8:9], v[2:3]
	v_mov_b64_e32 v[10:11], v[2:3]
	v_mov_b64_e32 v[12:13], v[2:3]
	v_mov_b64_e32 v[14:15], v[2:3]
	v_mov_b64_e32 v[16:17], v[2:3]
	ds_read_b64_tr_b16 v[132:133], v228 offset:32768
	ds_read_b64_tr_b16 v[134:135], v228 offset:34816
	ds_read_b64_tr_b16 v[136:137], v229 offset:32768
	ds_read_b64_tr_b16 v[138:139], v229 offset:34816
	ds_read_b64_tr_b16 v[140:141], v230 offset:32768
	ds_read_b64_tr_b16 v[142:143], v230 offset:34816
	ds_read_b64_tr_b16 v[144:145], v231 offset:32768
	ds_read_b64_tr_b16 v[146:147], v231 offset:34816
	ds_read_b64_tr_b16 v[220:221], v228 offset:36864
	ds_read_b64_tr_b16 v[222:223], v228 offset:38912
	ds_read_b64_tr_b16 v[224:225], v229 offset:36864
	ds_read_b64_tr_b16 v[226:227], v229 offset:38912
	ds_read_b64_tr_b16 v[232:233], v230 offset:36864
	ds_read_b64_tr_b16 v[234:235], v230 offset:38912
	s_nop 1
	s_cmp_eq_u32 s42, 0
	s_cbranch_scc1 .LatA_recret_h2
	s_cmp_eq_u32 s42, 1
	s_cbranch_scc1 .LatA_recret_m2
	s_branch .LatA_recret_x2

; #define LAS __attribute__((address_space(3)))
; __device__ __forceinline__ float max2f(float a, float b) { float r; asm("v_max_f32_e32 %0, %1, %2" : "=v"(r) : "v"(a), "v"(b)); return r; }
; __device__ __forceinline__ void attn_unit(LAS unsigned char* lds, const bf16_t* Z, bf16_t* A2, const float* tabg, int seq_base, int S, int h, int qb, float lam) {
;     ...
;         float mx = max2f(max16f(p0), max16f(p1));
;         const bool first = (t == 0);
;         if (first || __any(mx > THR)) {
;             { auto rr = __builtin_amdgcn_permlane32_swap(__float_as_uint(mx), __float_as_uint(mx), false, false); mx = max2f(__uint_as_float(rr[0]), __uint_as_float(rr[1])); }
;             const float delta = first ? mx : fmaxf(mx, 0.f);
;             const float alpha = first ? 1.0f : __builtin_amdgcn_exp2f(-delta);
;             mu += delta; ls2 *= alpha;
;             if (!first) {
;                 asm volatile("" ::: "memory");
;                 scr[r32] = alpha;
;                 asm volatile("s_waitcnt lgkmcnt(0)" ::: "memory");
; #pragma unroll
;                 for (int g = 0; g < 4; ++g) { const f32x4 a4 = *(const LAS f32x4*)(scr + 8 * g + 4 * hi);
; #pragma unroll
;                     for (int d = 0; d < 4; ++d) { O[d][4 * g + 0] *= a4[0]; O[d][4 * g + 1] *= a4[1]; O[d][4 * g + 2] *= a4[2]; O[d][4 * g + 3] *= a4[3]; } }
;                 asm volatile("s_waitcnt lgkmcnt(0)" ::: "memory");
;             }
; #pragma unroll
;             for (int r = 0; r < 16; ++r) { p0[r] -= delta; p1[r] -= delta; }
.LatA_recnn_3:
	v_max3_f32 v251, v188, v189, v190
	v_max3_f32 v252, v191, v192, v193
	v_max3_f32 v251, v251, v194, v195
	v_max3_f32 v252, v252, v196, v197
	v_max3_f32 v251, v251, v198, v199
	v_max3_f32 v252, v252, v200, v201
	v_max3_f32 v251, v251, v202, v203
	v_max3_f32 v252, v252, v204, v205
	v_max3_f32 v251, v251, v206, v207
	v_max3_f32 v252, v252, v208, v209
	v_max3_f32 v251, v251, v210, v211
	v_max3_f32 v252, v252, v212, v213
	v_max3_f32 v251, v251, v214, v215
	v_max3_f32 v252, v252, v216, v217
	v_max3_f32 v251, v251, v218, v219
	v_max_f32_e32 v251, v251, v252
	v_mov_b32_e32 v252, v251
	s_nop 1
	v_permlane32_swap_b32_e32 v251, v252
	v_max_f32_e32 v251, v251, v252
	v_max_f32_e32 v253, 0, v251
	v_exp_f32_e64 v254, -v253
	v_add_f32_e32 v186, v186, v253
	s_nop 0
	v_mul_f32_e32 v150, v150, v254
	v_mul_f32_e32 v151, v151, v254
	ds_write_b32 v184, v254
	s_waitcnt lgkmcnt(0)
	ds_read_b128 v[132:135], v185
	ds_read_b128 v[136:139], v185 offset:32
	ds_read_b128 v[140:143], v185 offset:64
	ds_read_b128 v[144:147], v185 offset:96
	s_waitcnt lgkmcnt(0)
	v_pk_mul_f32 v[20:21], v[20:21], v[132:133]
	v_pk_mul_f32 v[22:23], v[22:23], v[134:135]
	v_pk_mul_f32 v[24:25], v[24:25], v[136:137]
	v_pk_mul_f32 v[26:27], v[26:27], v[138:139]
	v_pk_mul_f32 v[28:29], v[28:29], v[140:141]
	v_pk_mul_f32 v[30:31], v[30:31], v[142:143]
	v_pk_mul_f32 v[32:33], v[32:33], v[144:145]
	v_pk_mul_f32 v[34:35], v[34:35], v[146:147]
	v_pk_mul_f32 v[36:37], v[36:37], v[132:133]
	v_pk_mul_f32 v[38:39], v[38:39], v[134:135]
	v_pk_mul_f32 v[40:41], v[40:41], v[136:137]
	v_pk_mul_f32 v[42:43], v[42:43], v[138:139]
	v_pk_mul_f32 v[44:45], v[44:45], v[140:141]
	v_pk_mul_f32 v[46:47], v[46:47], v[142:143]
	v_pk_mul_f32 v[48:49], v[48:49], v[144:145]
	v_pk_mul_f32 v[50:51], v[50:51], v[146:147]
	v_pk_mul_f32 v[52:53], v[52:53], v[132:133]
	v_pk_mul_f32 v[54:55], v[54:55], v[134:135]
	v_pk_mul_f32 v[56:57], v[56:57], v[136:137]
	v_pk_mul_f32 v[58:59], v[58:59], v[138:139]
	v_pk_mul_f32 v[60:61], v[60:61], v[140:141]
	v_pk_mul_f32 v[62:63], v[62:63], v[142:143]
	v_pk_mul_f32 v[64:65], v[64:65], v[144:145]
	v_pk_mul_f32 v[66:67], v[66:67], v[146:147]
	v_pk_mul_f32 v[68:69], v[68:69], v[132:133]
	v_pk_mul_f32 v[70:71], v[70:71], v[134:135]
	v_pk_mul_f32 v[72:73], v[72:73], v[136:137]
	v_pk_mul_f32 v[74:75], v[74:75], v[138:139]
	v_pk_mul_f32 v[76:77], v[76:77], v[140:141]
	v_pk_mul_f32 v[78:79], v[78:79], v[142:143]
	v_pk_mul_f32 v[80:81], v[80:81], v[144:145]
	v_pk_mul_f32 v[82:83], v[82:83], v[146:147]
	v_mov_b32_e32 v252, v253
	v_pk_add_f32 v[188:189], v[188:189], v[252:253] neg_lo:[0,1] neg_hi:[0,1]
	v_pk_add_f32 v[190:191], v[190:191], v[252:253] neg_lo:[0,1] neg_hi:[0,1]
	v_pk_add_f32 v[192:193], v[192:193], v[252:253] neg_lo:[0,1] neg_hi:[0,1]
	v_pk_add_f32 v[194:195], v[194:195], v[252:253] neg_lo:[0,1] neg_hi:[0,1]
	v_pk_add_f32 v[196:197], v[196:197], v[252:253] neg_lo:[0,1] neg_hi:[0,1]
	v_pk_add_f32 v[198:199], v[198:199], v[252:253] neg_lo:[0,1] neg_hi:[0,1]
	v_pk_add_f32 v[200:201], v[200:201], v[252:253] neg_lo:[0,1] neg_hi:[0,1]
	v_pk_add_f32 v[202:203], v[202:203], v[252:253] neg_lo:[0,1] neg_hi:[0,1]
	v_pk_add_f32 v[204:205], v[204:205], v[252:253] neg_lo:[0,1] neg_hi:[0,1]
	v_pk_add_f32 v[206:207], v[206:207], v[252:253] neg_lo:[0,1] neg_hi:[0,1]
	v_pk_add_f32 v[208:209], v[208:209], v[252:253] neg_lo:[0,1] neg_hi:[0,1]
	v_pk_add_f32 v[210:211], v[210:211], v[252:253] neg_lo:[0,1] neg_hi:[0,1]
	v_pk_add_f32 v[212:213], v[212:213], v[252:253] neg_lo:[0,1] neg_hi:[0,1]
	v_pk_add_f32 v[214:215], v[214:215], v[252:253] neg_lo:[0,1] neg_hi:[0,1]
	v_pk_add_f32 v[216:217], v[216:217], v[252:253] neg_lo:[0,1] neg_hi:[0,1]
	v_pk_add_f32 v[218:219], v[218:219], v[252:253] neg_lo:[0,1] neg_hi:[0,1]
	v_pk_add_f32 v[84:85], v[84:85], v[252:253] neg_lo:[0,1] neg_hi:[0,1]
	v_pk_add_f32 v[86:87], v[86:87], v[252:253] neg_lo:[0,1] neg_hi:[0,1]
	v_pk_add_f32 v[88:89], v[88:89], v[252:253] neg_lo:[0,1] neg_hi:[0,1]
	v_pk_add_f32 v[90:91], v[90:91], v[252:253] neg_lo:[0,1] neg_hi:[0,1]
	v_pk_add_f32 v[92:93], v[92:93], v[252:253] neg_lo:[0,1] neg_hi:[0,1]
	v_pk_add_f32 v[94:95], v[94:95], v[252:253] neg_lo:[0,1] neg_hi:[0,1]
	v_pk_add_f32 v[96:97], v[96:97], v[252:253] neg_lo:[0,1] neg_hi:[0,1]
	v_pk_add_f32 v[98:99], v[98:99], v[252:253] neg_lo:[0,1] neg_hi:[0,1]
; #define VREADS1(arr, d_) do { const unsigned ad_ = vbase ^ (unsigned)((d_) << 6); __builtin_amdgcn_sched_barrier(0); \
;         _Pragma("unroll") for (int ks_ = 0; ks_ < 4; ++ks_) { VTR(arr[ks_ * 2], ad_, ks_ * 4096); VTR(arr[ks_ * 2 + 1], ad_, ks_ * 4096 + 2048); } __builtin_amdgcn_sched_barrier(0); } while (0)
; #define PV1(arr, d_) do { _Pragma("unroll") for (int ks_ = 0; ks_ < 4; ++ks_) { const s16x4 lo_ = arr[ks_ * 2], hh_ = arr[ks_ * 2 + 1]; \
;         const bf16x8 bv_ = (bf16x8){lo_[0], lo_[1], lo_[2], lo_[3], hh_[0], hh_[1], hh_[2], hh_[3]}; \
;         O[d_] = __builtin_amdgcn_mfma_f32_32x32x16_bf16(pa[ks_], bv_, O[d_], 0, 0, 0); } __builtin_amdgcn_sched_barrier(0); } while (0)
; #define LGKM0() do { __builtin_amdgcn_sched_barrier(0); asm volatile("s_waitcnt lgkmcnt(0)" ::: "memory"); __builtin_amdgcn_sched_barrier(0); } while (0)
; __device__ __forceinline__ void attn_unit(LAS unsigned char* lds, const bf16_t* Z, bf16_t* A2, const float* tabg, int seq_base, int S, int h, int qb, float lam) {
;     ...
;         bool near = true; float cc = 0.f;
;         if (kv0 - (qlo + 31) >= 128) { near = false; cc = tabR; } else if (qlo - (kv0 + 63) >= 128) { near = false; cc = tabL; }
;         { const float coff = cc - mu;
;           if (__any(!(coff == coff_cur))) { coff_cur = coff;
; #pragma unroll
;               for (int r = 0; r < 16; ++r) cblk[r] = coff;
;               asm volatile("" : "+v"(cblk)); } }
;     ...
;             for (int r = 0; r < 16; ++r) { p0[r] -= delta; p1[r] -= delta; }
;             asm volatile("" : "+v"(p0), "+v"(p1));
;         }
; #pragma unroll
;         for (int r = 0; r < 16; ++r) { p0[r] = __builtin_amdgcn_exp2f(p0[r]); p1[r] = __builtin_amdgcn_exp2f(p1[r]); }
; #pragma unroll
;         for (int r = 0; r < 16; r += 2) { ls2 += (f32x2){p0[r], p0[r + 1]}; ls2 += (f32x2){p1[r], p1[r + 1]}; }
;         bf16x8 pa[4]; pa[0] = pack8(p0, 0); pa[1] = pack8(p0, 8); pa[2] = pack8(p1, 0); pa[3] = pack8(p1, 8);
;         LGKM0(); VREADS1(vb, 1); PV1(va, 0); LGKM0(); VREADS1(va, 2); PV1(vb, 1); LGKM0(); VREADS1(vb, 3); PV1(va, 2); LGKM0(); PV1(vb, 3);
	v_pk_add_f32 v[100:101], v[100:101], v[252:253] neg_lo:[0,1] neg_hi:[0,1]
	v_pk_add_f32 v[102:103], v[102:103], v[252:253] neg_lo:[0,1] neg_hi:[0,1]
	v_pk_add_f32 v[104:105], v[104:105], v[252:253] neg_lo:[0,1] neg_hi:[0,1]
	v_pk_add_f32 v[106:107], v[106:107], v[252:253] neg_lo:[0,1] neg_hi:[0,1]
	v_pk_add_f32 v[108:109], v[108:109], v[252:253] neg_lo:[0,1] neg_hi:[0,1]
	v_pk_add_f32 v[110:111], v[110:111], v[252:253] neg_lo:[0,1] neg_hi:[0,1]
	v_pk_add_f32 v[112:113], v[112:113], v[252:253] neg_lo:[0,1] neg_hi:[0,1]
	v_pk_add_f32 v[114:115], v[114:115], v[252:253] neg_lo:[0,1] neg_hi:[0,1]
	v_exp_f32_e32 v188, v188
	v_exp_f32_e32 v189, v189
	v_exp_f32_e32 v190, v190
	v_exp_f32_e32 v191, v191
	v_exp_f32_e32 v192, v192
	v_add_f32_e32 v252, v188, v190
	v_add_f32_e32 v253, v189, v191
	v_exp_f32_e32 v193, v193
	v_cvt_pk_bf16_f32 v188, v188, v189
	v_cvt_pk_bf16_f32 v189, v190, v191
	v_exp_f32_e32 v194, v194
	v_exp_f32_e32 v195, v195
	v_add_f32_e32 v252, v252, v192
	v_add_f32_e32 v253, v253, v193
	v_add_f32_e32 v252, v252, v194
	v_add_f32_e32 v253, v253, v195
	v_cvt_pk_bf16_f32 v190, v192, v193
	v_cvt_pk_bf16_f32 v191, v194, v195
	v_exp_f32_e32 v196, v196
	v_exp_f32_e32 v197, v197
	v_exp_f32_e32 v198, v198
	v_exp_f32_e32 v199, v199
	v_add_f32_e32 v252, v252, v196
	v_add_f32_e32 v253, v253, v197
	v_add_f32_e32 v252, v252, v198
	v_add_f32_e32 v253, v253, v199
	v_exp_f32_e32 v200, v200
	v_exp_f32_e32 v201, v201
	v_cvt_pk_bf16_f32 v192, v196, v197
	v_cvt_pk_bf16_f32 v193, v198, v199
	v_exp_f32_e32 v202, v202
	v_exp_f32_e32 v203, v203
	v_add_f32_e32 v252, v252, v200
	v_add_f32_e32 v253, v253, v201
	v_add_f32_e32 v252, v252, v202
	v_add_f32_e32 v253, v253, v203
	v_cvt_pk_bf16_f32 v194, v200, v201
	v_cvt_pk_bf16_f32 v195, v202, v203
	v_exp_f32_e32 v204, v204
	v_exp_f32_e32 v205, v205
	v_exp_f32_e32 v206, v206
	v_exp_f32_e32 v207, v207
	v_add_f32_e32 v252, v252, v204
	v_add_f32_e32 v253, v253, v205
	v_add_f32_e32 v252, v252, v206
	v_add_f32_e32 v253, v253, v207
	v_exp_f32_e32 v208, v208
	v_exp_f32_e32 v209, v209
	v_cvt_pk_bf16_f32 v204, v204, v205
	v_cvt_pk_bf16_f32 v205, v206, v207
	v_exp_f32_e32 v210, v210
	v_exp_f32_e32 v211, v211
	v_add_f32_e32 v252, v252, v208
	v_add_f32_e32 v253, v253, v209
	v_add_f32_e32 v252, v252, v210
	v_add_f32_e32 v253, v253, v211
	v_cvt_pk_bf16_f32 v206, v208, v209
	v_cvt_pk_bf16_f32 v207, v210, v211
	v_exp_f32_e32 v212, v212
	v_exp_f32_e32 v213, v213
	v_exp_f32_e32 v214, v214
	v_exp_f32_e32 v215, v215
	v_add_f32_e32 v252, v252, v212
	v_add_f32_e32 v253, v253, v213
	v_add_f32_e32 v252, v252, v214
	v_add_f32_e32 v253, v253, v215
	v_exp_f32_e32 v216, v216
	v_exp_f32_e32 v217, v217
	v_cvt_pk_bf16_f32 v208, v212, v213
	v_cvt_pk_bf16_f32 v209, v214, v215
	v_exp_f32_e32 v218, v218
	v_exp_f32_e32 v219, v219
	v_add_f32_e32 v252, v252, v216
	v_add_f32_e32 v253, v253, v217
	v_add_f32_e32 v252, v252, v218
	v_add_f32_e32 v253, v253, v219
	v_cvt_pk_bf16_f32 v210, v216, v217
	v_cvt_pk_bf16_f32 v211, v218, v219
	s_mov_b32 s37, s43
	s_mov_b32 s35, s37
	v_mov_b32_e32 v251, 0
	s_cmp_eq_u32 s37, 1
	s_cselect_b64 vcc, -1, 0
	v_cndmask_b32_e32 v251, v251, v177, vcc
	s_cmp_eq_u32 s37, 2
	s_cselect_b64 vcc, -1, 0
	v_cndmask_b32_e32 v251, v251, v178, vcc
	v_sub_f32_e32 v2, v251, v186
	v_mov_b32_e32 v3, v2
	v_mov_b64_e32 v[4:5], v[2:3]
	v_mov_b64_e32 v[6:7], v[2:3]
	v_mov_b64_e32 v[8:9], v[2:3]
	v_mov_b64_e32 v[10:11], v[2:3]
	v_mov_b64_e32 v[12:13], v[2:3]
	v_mov_b64_e32 v[14:15], v[2:3]
	v_mov_b64_e32 v[16:17], v[2:3]
	ds_read_b64_tr_b16 v[132:133], v168 offset:0
	ds_read_b64_tr_b16 v[134:135], v168 offset:2048
	ds_read_b64_tr_b16 v[136:137], v169 offset:0
	ds_read_b64_tr_b16 v[138:139], v169 offset:2048
	ds_read_b64_tr_b16 v[140:141], v170 offset:0
	ds_read_b64_tr_b16 v[142:143], v170 offset:2048
	ds_read_b64_tr_b16 v[144:145], v171 offset:0
	ds_read_b64_tr_b16 v[146:147], v171 offset:2048
	ds_read_b64_tr_b16 v[220:221], v168 offset:4096
	ds_read_b64_tr_b16 v[222:223], v168 offset:6144
	ds_read_b64_tr_b16 v[224:225], v169 offset:4096
	ds_read_b64_tr_b16 v[226:227], v169 offset:6144
	ds_read_b64_tr_b16 v[232:233], v170 offset:4096
	ds_read_b64_tr_b16 v[234:235], v170 offset:6144
	s_nop 1
	s_cmp_eq_u32 s42, 0
	s_cbranch_scc1 .LatA_recret_h3
	s_cmp_eq_u32 s42, 1
	s_cbranch_scc1 .LatA_recret_m3
	s_branch .LatA_recret_x1

; #define LAS __attribute__((address_space(3)))
; __device__ __forceinline__ void attn_unit(LAS unsigned char* lds, const bf16_t* Z, bf16_t* A2, const float* tabg, int seq_base, int S, int h, int qb, float lam) {
;     ...
;         if (kv0 - (qlo + 31) >= 128) { near = false; cc = tabR; } else if (qlo - (kv0 + 63) >= 128) { near = false; cc = tabL; }
;         { const float coff = cc - mu;
;           if (__any(!(coff == coff_cur))) { coff_cur = coff;
; #pragma unroll
;               for (int r = 0; r < 16; ++r) cblk[r] = coff;
;               asm volatile("" : "+v"(cblk)); } }
;         f32x16 p0, p1;
;         {
;             bf16x8 kf[8];
; #pragma unroll
;     ...
;         float mx = max2f(max16f(p0), max16f(p1));
;         const bool first = (t == 0);
;         if (first || __any(mx > THR)) {
;             { auto rr = __builtin_amdgcn_permlane32_swap(__float_as_uint(mx), __float_as_uint(mx), false, false); mx = max2f(__uint_as_float(rr[0]), __uint_as_float(rr[1])); }
;             const float delta = first ? mx : fmaxf(mx, 0.f);
;             const float alpha = first ? 1.0f : __builtin_amdgcn_exp2f(-delta);
;             mu += delta; ls2 *= alpha;
;             if (!first) {
;                 asm volatile("" ::: "memory");
;                 scr[r32] = alpha;
;                 asm volatile("s_waitcnt lgkmcnt(0)" ::: "memory");
; #pragma unroll
;                 for (int g = 0; g < 4; ++g) { const f32x4 a4 = *(const LAS f32x4*)(scr + 8 * g + 4 * hi);
; #pragma unroll
;                     for (int d = 0; d < 4; ++d) { O[d][4 * g + 0] *= a4[0]; O[d][4 * g + 1] *= a4[1]; O[d][4 * g + 2] *= a4[2]; O[d][4 * g + 3] *= a4[3]; } }
;                 asm volatile("s_waitcnt lgkmcnt(0)" ::: "memory");
;             }
; #pragma unroll
;             for (int r = 0; r < 16; ++r) { p0[r] -= delta; p1[r] -= delta; }
;             asm volatile("" : "+v"(p0), "+v"(p1));
;         }
; #pragma unroll
;         for (int r = 0; r < 16; ++r) { p0[r] = __builtin_amdgcn_exp2f(p0[r]); p1[r] = __builtin_amdgcn_exp2f(p1[r]); }
; #pragma unroll
;         for (int r = 0; r < 16; r += 2) { ls2 += (f32x2){p0[r], p0[r + 1]}; ls2 += (f32x2){p1[r], p1[r + 1]}; }
;         bf16x8 pa[4]; pa[0] = pack8(p0, 0); pa[1] = pack8(p0, 8); pa[2] = pack8(p1, 0); pa[3] = pack8(p1, 8);
.LatB_p0_nonear:
	v_max3_f32 v251, v84, v85, v86
	v_max3_f32 v252, v87, v88, v89
	v_max3_f32 v251, v251, v90, v91
	v_max3_f32 v252, v252, v92, v93
	v_max3_f32 v251, v251, v94, v95
	v_max3_f32 v252, v252, v96, v97
	v_max3_f32 v251, v251, v98, v99
	v_max3_f32 v252, v252, v100, v101
	v_max3_f32 v251, v251, v102, v103
	v_max3_f32 v252, v252, v104, v105
	v_max3_f32 v251, v251, v106, v107
	v_max3_f32 v252, v252, v108, v109
	v_max3_f32 v251, v251, v110, v111
	v_max3_f32 v252, v252, v112, v113
	v_max3_f32 v251, v251, v114, v115
	v_max_f32_e32 v251, v251, v252
	v_mov_b32_e32 v252, v251
	s_nop 1
	v_permlane32_swap_b32_e32 v251, v252
	v_max_f32_e32 v186, v251, v252
	v_sub_f32_e32 v84, v84, v186
	v_sub_f32_e32 v85, v85, v186
	v_sub_f32_e32 v86, v86, v186
	v_sub_f32_e32 v87, v87, v186
	v_sub_f32_e32 v88, v88, v186
	v_sub_f32_e32 v89, v89, v186
	v_sub_f32_e32 v90, v90, v186
	v_sub_f32_e32 v91, v91, v186
	v_sub_f32_e32 v92, v92, v186
	v_sub_f32_e32 v93, v93, v186
	v_sub_f32_e32 v94, v94, v186
	v_sub_f32_e32 v95, v95, v186
	v_sub_f32_e32 v96, v96, v186
	v_sub_f32_e32 v97, v97, v186
	v_sub_f32_e32 v98, v98, v186
	v_sub_f32_e32 v99, v99, v186
	v_sub_f32_e32 v100, v100, v186
	v_sub_f32_e32 v101, v101, v186
	v_sub_f32_e32 v102, v102, v186
	v_sub_f32_e32 v103, v103, v186
	v_sub_f32_e32 v104, v104, v186
	v_sub_f32_e32 v105, v105, v186
	v_sub_f32_e32 v106, v106, v186
	v_sub_f32_e32 v107, v107, v186
	v_sub_f32_e32 v108, v108, v186
	v_sub_f32_e32 v109, v109, v186
	v_sub_f32_e32 v110, v110, v186
	v_sub_f32_e32 v111, v111, v186
	v_sub_f32_e32 v112, v112, v186
	v_sub_f32_e32 v113, v113, v186
	v_sub_f32_e32 v114, v114, v186
	v_sub_f32_e32 v115, v115, v186
	s_add_u32 s29, s5, 64
	s_cmp_lt_u32 s29, s11
	s_cselect_b32 s24, 1, 0
	s_cmp_gt_u32 s29, s31
	s_cselect_b32 s30, 2, 0
	s_or_b32 s24, s24, s30
	s_mov_b32 s35, s24
	v_mov_b32_e32 v251, 0
	s_cmp_eq_u32 s24, 1
	s_cselect_b64 vcc, -1, 0
	v_cndmask_b32_e32 v251, v251, v177, vcc
	s_cmp_eq_u32 s24, 2
	s_cselect_b64 vcc, -1, 0
	v_cndmask_b32_e32 v251, v251, v178, vcc
	v_sub_f32_e32 v2, v251, v186
	v_mov_b32_e32 v3, v2
	v_mov_b64_e32 v[4:5], v[2:3]
	v_mov_b64_e32 v[6:7], v[2:3]
	v_mov_b64_e32 v[8:9], v[2:3]
	v_mov_b64_e32 v[10:11], v[2:3]
	v_mov_b64_e32 v[12:13], v[2:3]
	v_mov_b64_e32 v[14:15], v[2:3]
	v_mov_b64_e32 v[16:17], v[2:3]
	s_waitcnt vmcnt(0)
	s_barrier
	ds_read_b128 v[132:135], v19 offset:16384
	ds_read_b128 v[136:139], v19 offset:24576
	ds_read_b128 v[140:143], v180 offset:16384
	ds_read_b128 v[144:147], v180 offset:24576
	ds_read_b128 v[220:223], v181 offset:16384
	ds_read_b128 v[224:227], v181 offset:24576
	ds_read_b128 v[232:235], v182 offset:16384
	s_waitcnt lgkmcnt(6)
	s_add_u32 m0, s25, 0x1d000
	v_mfma_f32_32x32x16_bf16 v[188:203], v[132:135], v[116:119], v[2:17]
	global_load_lds_dwordx4 v172, s[8:9]
	ds_read_b128 v[236:239], v182 offset:24576
	v_exp_f32_e32 v84, v84
	v_exp_f32_e32 v85, v85
	v_exp_f32_e32 v86, v86
	v_exp_f32_e32 v87, v87
	v_exp_f32_e32 v88, v88
	v_add_f32_e32 v252, v84, v86
	v_add_f32_e32 v253, v85, v87
	v_exp_f32_e32 v89, v89
	s_waitcnt lgkmcnt(6)
	s_add_u32 m0, s27, 0x8000
	v_mfma_f32_32x32x16_bf16 v[204:219], v[136:139], v[116:119], v[2:17]
	global_load_lds_dwordx4 v174, s[8:9]
	ds_read_b64_tr_b16 v[132:133], v228 offset:0
	ds_read_b64_tr_b16 v[134:135], v228 offset:2048
	v_cvt_pk_bf16_f32 v84, v84, v85
	v_cvt_pk_bf16_f32 v85, v86, v87
	v_exp_f32_e32 v90, v90
	v_exp_f32_e32 v91, v91
	v_add_f32_e32 v252, v252, v88
	v_add_f32_e32 v253, v253, v89
	v_add_f32_e32 v252, v252, v90
	v_add_f32_e32 v253, v253, v91
	v_cvt_pk_bf16_f32 v86, v88, v89
	v_cvt_pk_bf16_f32 v87, v90, v91
	v_exp_f32_e32 v92, v92
	s_waitcnt lgkmcnt(7)
	s_add_u32 m0, s25, 0x1f000
	v_mfma_f32_32x32x16_bf16 v[188:203], v[140:143], v[120:123], v[188:203]
	global_load_lds_dwordx4 v173, s[8:9]
	ds_read_b64_tr_b16 v[136:137], v229 offset:0
	ds_read_b64_tr_b16 v[138:139], v229 offset:2048
	v_exp_f32_e32 v93, v93
	v_exp_f32_e32 v94, v94
	v_exp_f32_e32 v95, v95
	v_add_f32_e32 v252, v252, v92
	v_add_f32_e32 v253, v253, v93
	v_add_f32_e32 v252, v252, v94
	v_add_f32_e32 v253, v253, v95
	v_exp_f32_e32 v96, v96
	s_waitcnt lgkmcnt(8)
	s_add_u32 m0, s27, 0xa000
	v_mfma_f32_32x32x16_bf16 v[204:219], v[144:147], v[120:123], v[204:219]
	global_load_lds_dwordx4 v175, s[8:9]
	ds_read_b64_tr_b16 v[140:141], v230 offset:0
	ds_read_b64_tr_b16 v[142:143], v230 offset:2048
	v_exp_f32_e32 v97, v97
	v_cvt_pk_bf16_f32 v88, v92, v93
	v_cvt_pk_bf16_f32 v89, v94, v95
	v_exp_f32_e32 v98, v98
	v_exp_f32_e32 v99, v99
	v_add_f32_e32 v252, v252, v96
	v_add_f32_e32 v253, v253, v97
	v_add_f32_e32 v252, v252, v98
	v_add_f32_e32 v253, v253, v99
	v_cvt_pk_bf16_f32 v90, v96, v97
	v_cvt_pk_bf16_f32 v91, v98, v99
	s_waitcnt lgkmcnt(9)
	v_mfma_f32_32x32x16_bf16 v[188:203], v[220:223], v[124:127], v[188:203]
	ds_read_b64_tr_b16 v[144:145], v231 offset:0
	ds_read_b64_tr_b16 v[146:147], v231 offset:2048
	v_exp_f32_e32 v100, v100
	v_exp_f32_e32 v101, v101
	v_exp_f32_e32 v102, v102
	v_exp_f32_e32 v103, v103
	v_add_f32_e32 v252, v252, v100
	v_add_f32_e32 v253, v253, v101
	v_add_f32_e32 v252, v252, v102
	v_add_f32_e32 v253, v253, v103
	v_exp_f32_e32 v104, v104
	s_waitcnt lgkmcnt(10)
	v_mfma_f32_32x32x16_bf16 v[204:219], v[224:227], v[124:127], v[204:219]
	ds_read_b64_tr_b16 v[220:221], v228 offset:4096
	ds_read_b64_tr_b16 v[222:223], v228 offset:6144
	v_exp_f32_e32 v105, v105
	v_cvt_pk_bf16_f32 v100, v100, v101
	v_cvt_pk_bf16_f32 v101, v102, v103
	v_exp_f32_e32 v106, v106
	v_exp_f32_e32 v107, v107
	v_add_f32_e32 v252, v252, v104
	v_add_f32_e32 v253, v253, v105
	v_add_f32_e32 v252, v252, v106
	v_add_f32_e32 v253, v253, v107
	v_cvt_pk_bf16_f32 v102, v104, v105
	v_cvt_pk_bf16_f32 v103, v106, v107
	s_waitcnt lgkmcnt(11)
	v_mfma_f32_32x32x16_bf16 v[188:203], v[232:235], v[128:131], v[188:203]
	ds_read_b64_tr_b16 v[224:225], v229 offset:4096
	ds_read_b64_tr_b16 v[226:227], v229 offset:6144
	v_exp_f32_e32 v108, v108
	v_exp_f32_e32 v109, v109
	v_exp_f32_e32 v110, v110
	v_exp_f32_e32 v111, v111
	v_add_f32_e32 v252, v252, v108
	v_add_f32_e32 v253, v253, v109
	v_add_f32_e32 v252, v252, v110
	v_add_f32_e32 v253, v253, v111
	v_exp_f32_e32 v112, v112
	s_waitcnt lgkmcnt(12)
	v_mfma_f32_32x32x16_bf16 v[204:219], v[236:239], v[128:131], v[204:219]
	ds_read_b64_tr_b16 v[232:233], v230 offset:4096
	ds_read_b64_tr_b16 v[234:235], v230 offset:6144
	v_exp_f32_e32 v113, v113
	v_cvt_pk_bf16_f32 v104, v108, v109
	v_cvt_pk_bf16_f32 v105, v110, v111
	v_exp_f32_e32 v114, v114
	v_exp_f32_e32 v115, v115
	v_add_f32_e32 v252, v252, v112
	v_add_f32_e32 v253, v253, v113
	v_add_f32_e32 v252, v252, v114
	v_add_f32_e32 v253, v253, v115
	v_cvt_pk_bf16_f32 v106, v112, v113
	v_cvt_pk_bf16_f32 v107, v114, v115
	v_max_f32_e32 v251, v252, v253
	v_cmp_nge_f32_e32 vcc, 0x45800000, v251
	s_cbranch_vccnz .LatB_recs_h0

; #define LAS __attribute__((address_space(3)))
; #define VREADS1(arr, d_) do { const unsigned ad_ = vbase ^ (unsigned)((d_) << 6); __builtin_amdgcn_sched_barrier(0); \
;         _Pragma("unroll") for (int ks_ = 0; ks_ < 4; ++ks_) { VTR(arr[ks_ * 2], ad_, ks_ * 4096); VTR(arr[ks_ * 2 + 1], ad_, ks_ * 4096 + 2048); } __builtin_amdgcn_sched_barrier(0); } while (0)
; #define PV1(arr, d_) do { _Pragma("unroll") for (int ks_ = 0; ks_ < 4; ++ks_) { const s16x4 lo_ = arr[ks_ * 2], hh_ = arr[ks_ * 2 + 1]; \
;         const bf16x8 bv_ = (bf16x8){lo_[0], lo_[1], lo_[2], lo_[3], hh_[0], hh_[1], hh_[2], hh_[3]}; \
;         O[d_] = __builtin_amdgcn_mfma_f32_32x32x16_bf16(pa[ks_], bv_, O[d_], 0, 0, 0); } __builtin_amdgcn_sched_barrier(0); } while (0)
; #define LGKM0() do { __builtin_amdgcn_sched_barrier(0); asm volatile("s_waitcnt lgkmcnt(0)" ::: "memory"); __builtin_amdgcn_sched_barrier(0); } while (0)
; __device__ __forceinline__ void attn_unit(LAS unsigned char* lds, const bf16_t* Z, bf16_t* A2, const float* tabg, int seq_base, int S, int h, int qb, float lam) {
;     ...
;             for (int ds = 0; ds < 4; ++ds) { kf[2 * ds] = *(const LAS bf16x8*)(Kt + (kfo ^ (unsigned)(ds << 5))); kf[2 * ds + 1] = *(const LAS bf16x8*)(Kt + 32 * 256 + (kfo ^ (unsigned)(ds << 5))); }
;             __builtin_amdgcn_sched_barrier(0);
;             p0 = __builtin_amdgcn_mfma_f32_32x32x16_bf16(kf[0], qf[0], cblk, 0, 0, 0);
;             p1 = __builtin_amdgcn_mfma_f32_32x32x16_bf16(kf[1], qf[0], cblk, 0, 0, 0);
; #pragma unroll
;             for (int ds = 1; ds < 4; ++ds) {
;                 p0 = __builtin_amdgcn_mfma_f32_32x32x16_bf16(kf[2 * ds], qf[ds], p0, 0, 0, 0);
;                 p1 = __builtin_amdgcn_mfma_f32_32x32x16_bf16(kf[2 * ds + 1], qf[ds], p1, 0, 0, 0);
;             }
;     ...
; #pragma unroll
;         for (int r = 0; r < 16; ++r) { p0[r] = __builtin_amdgcn_exp2f(p0[r]); p1[r] = __builtin_amdgcn_exp2f(p1[r]); }
; #pragma unroll
;         for (int r = 0; r < 16; r += 2) { ls2 += (f32x2){p0[r], p0[r + 1]}; ls2 += (f32x2){p1[r], p1[r + 1]}; }
;         bf16x8 pa[4]; pa[0] = pack8(p0, 0); pa[1] = pack8(p0, 8); pa[2] = pack8(p1, 0); pa[3] = pack8(p1, 8);
;         LGKM0(); VREADS1(vb, 1); PV1(va, 0); LGKM0(); VREADS1(va, 2); PV1(vb, 1); LGKM0(); VREADS1(vb, 3); PV1(va, 2); LGKM0(); PV1(vb, 3);
.LatB_evret_h1:
	s_waitcnt lgkmcnt(12)
	v_mfma_f32_32x32x16_bf16 v[20:35], v[84:87], v[132:135], v[20:35]
	ds_read_b64_tr_b16 v[236:237], v231 offset:4096
	ds_read_b64_tr_b16 v[238:239], v231 offset:6144
	v_exp_f32_e32 v188, v188
	v_exp_f32_e32 v189, v189
	s_waitcnt lgkmcnt(12)
	v_mfma_f32_32x32x16_bf16 v[36:51], v[84:87], v[136:139], v[36:51]
	ds_read_b64_tr_b16 v[132:133], v228 offset:8192
	ds_read_b64_tr_b16 v[134:135], v228 offset:10240
	v_exp_f32_e32 v190, v190
	v_exp_f32_e32 v191, v191
	s_waitcnt lgkmcnt(12)
	v_mfma_f32_32x32x16_bf16 v[52:67], v[84:87], v[140:143], v[52:67]
	ds_read_b64_tr_b16 v[136:137], v229 offset:8192
	ds_read_b64_tr_b16 v[138:139], v229 offset:10240
	v_exp_f32_e32 v192, v192
	v_add_f32_e32 v252, v188, v190
	v_add_f32_e32 v253, v189, v191
	v_exp_f32_e32 v193, v193
	s_waitcnt lgkmcnt(12)
	s_mov_b32 m0, s25
	v_mfma_f32_32x32x16_bf16 v[68:83], v[84:87], v[144:147], v[68:83]
	global_load_lds_dwordx4 v172, s[8:9]
	ds_read_b64_tr_b16 v[140:141], v230 offset:8192
	ds_read_b64_tr_b16 v[142:143], v230 offset:10240
	v_cvt_pk_bf16_f32 v188, v188, v189
	v_cvt_pk_bf16_f32 v189, v190, v191
	v_exp_f32_e32 v194, v194
	s_waitcnt lgkmcnt(12)
	v_mfma_f32_32x32x16_bf16 v[20:35], v[88:91], v[220:223], v[20:35]
	ds_read_b64_tr_b16 v[144:145], v231 offset:8192
	ds_read_b64_tr_b16 v[146:147], v231 offset:10240
	v_exp_f32_e32 v195, v195
	v_add_f32_e32 v252, v252, v192
	v_add_f32_e32 v253, v253, v193
	v_add_f32_e32 v252, v252, v194
	s_waitcnt lgkmcnt(12)
	v_mfma_f32_32x32x16_bf16 v[36:51], v[88:91], v[224:227], v[36:51]
	ds_read_b64_tr_b16 v[220:221], v228 offset:12288
	ds_read_b64_tr_b16 v[222:223], v228 offset:14336
	v_add_f32_e32 v253, v253, v195
	v_cvt_pk_bf16_f32 v190, v192, v193
	v_cvt_pk_bf16_f32 v191, v194, v195
	v_exp_f32_e32 v196, v196
	s_waitcnt lgkmcnt(12)
	v_mfma_f32_32x32x16_bf16 v[52:67], v[88:91], v[232:235], v[52:67]
	ds_read_b64_tr_b16 v[224:225], v229 offset:12288
	ds_read_b64_tr_b16 v[226:227], v229 offset:14336
	v_exp_f32_e32 v197, v197
	v_exp_f32_e32 v198, v198
	s_waitcnt lgkmcnt(12)
	s_add_u32 m0, s27, 0xd000
	v_mfma_f32_32x32x16_bf16 v[68:83], v[88:91], v[236:239], v[68:83]
	global_load_lds_dwordx4 v174, s[8:9]
	ds_read_b64_tr_b16 v[232:233], v230 offset:12288
	ds_read_b64_tr_b16 v[234:235], v230 offset:14336
	v_exp_f32_e32 v199, v199
	v_add_f32_e32 v252, v252, v196
	v_add_f32_e32 v253, v253, v197
	v_add_f32_e32 v252, v252, v198
	s_waitcnt lgkmcnt(12)
	v_mfma_f32_32x32x16_bf16 v[20:35], v[100:103], v[132:135], v[20:35]
	ds_read_b64_tr_b16 v[236:237], v231 offset:12288
	ds_read_b64_tr_b16 v[238:239], v231 offset:14336
	v_add_f32_e32 v253, v253, v199
	v_exp_f32_e32 v200, v200
	s_waitcnt lgkmcnt(12)
	v_mfma_f32_32x32x16_bf16 v[36:51], v[100:103], v[136:139], v[36:51]
	ds_read_b128 v[132:135], v19 offset:32768
	v_exp_f32_e32 v201, v201
	v_cvt_pk_bf16_f32 v192, v196, v197
	v_cvt_pk_bf16_f32 v193, v198, v199
	v_exp_f32_e32 v202, v202
	s_waitcnt lgkmcnt(11)
	v_mfma_f32_32x32x16_bf16 v[52:67], v[100:103], v[140:143], v[52:67]
	ds_read_b128 v[136:139], v19 offset:40960
	v_exp_f32_e32 v203, v203
	v_add_f32_e32 v252, v252, v200
	v_add_f32_e32 v253, v253, v201
	s_waitcnt lgkmcnt(10)
	s_add_u32 m0, s25, 0x2000
	v_mfma_f32_32x32x16_bf16 v[68:83], v[100:103], v[144:147], v[68:83]
	global_load_lds_dwordx4 v173, s[8:9]
	ds_read_b128 v[140:143], v180 offset:32768
	v_add_f32_e32 v252, v252, v202
	v_add_f32_e32 v253, v253, v203
	v_cvt_pk_bf16_f32 v194, v200, v201
	v_cvt_pk_bf16_f32 v195, v202, v203
	s_waitcnt lgkmcnt(9)
	v_mfma_f32_32x32x16_bf16 v[20:35], v[104:107], v[220:223], v[20:35]
	ds_read_b128 v[144:147], v180 offset:40960
	v_exp_f32_e32 v204, v204
	v_exp_f32_e32 v205, v205
	v_exp_f32_e32 v206, v206
	s_waitcnt lgkmcnt(8)
	v_mfma_f32_32x32x16_bf16 v[36:51], v[104:107], v[224:227], v[36:51]
	ds_read_b128 v[220:223], v181 offset:32768
	v_exp_f32_e32 v207, v207
	v_add_f32_e32 v252, v252, v204
	v_add_f32_e32 v253, v253, v205
	s_waitcnt lgkmcnt(7)
	v_mfma_f32_32x32x16_bf16 v[52:67], v[104:107], v[232:235], v[52:67]
	ds_read_b128 v[224:227], v181 offset:40960
	v_add_f32_e32 v252, v252, v206
	v_add_f32_e32 v253, v253, v207
	v_exp_f32_e32 v208, v208
	s_waitcnt lgkmcnt(6)
	s_add_u32 m0, s27, 0xf000
	v_mfma_f32_32x32x16_bf16 v[68:83], v[104:107], v[236:239], v[68:83]
	global_load_lds_dwordx4 v175, s[8:9]
	ds_read_b128 v[232:235], v182 offset:32768
	v_exp_f32_e32 v209, v209
	v_cvt_pk_bf16_f32 v204, v204, v205
	v_cvt_pk_bf16_f32 v205, v206, v207
	s_waitcnt lgkmcnt(6)
	v_mfma_f32_32x32x16_bf16 v[84:99], v[132:135], v[116:119], v[2:17]
	ds_read_b128 v[236:239], v182 offset:40960
	v_exp_f32_e32 v210, v210
	v_exp_f32_e32 v211, v211
	v_add_f32_e32 v252, v252, v208
	v_add_f32_e32 v253, v253, v209
	s_waitcnt lgkmcnt(6)
	v_mfma_f32_32x32x16_bf16 v[100:115], v[136:139], v[116:119], v[2:17]
	ds_read_b64_tr_b16 v[132:133], v228 offset:16384
	ds_read_b64_tr_b16 v[134:135], v228 offset:18432
	v_add_f32_e32 v252, v252, v210
	v_add_f32_e32 v253, v253, v211
	v_cvt_pk_bf16_f32 v206, v208, v209
	v_cvt_pk_bf16_f32 v207, v210, v211
	s_waitcnt lgkmcnt(7)
	v_mfma_f32_32x32x16_bf16 v[84:99], v[140:143], v[120:123], v[84:99]
	ds_read_b64_tr_b16 v[136:137], v229 offset:16384
	ds_read_b64_tr_b16 v[138:139], v229 offset:18432
	v_exp_f32_e32 v212, v212
	v_exp_f32_e32 v213, v213
	s_waitcnt lgkmcnt(8)
	v_mfma_f32_32x32x16_bf16 v[100:115], v[144:147], v[120:123], v[100:115]
	ds_read_b64_tr_b16 v[140:141], v230 offset:16384
	ds_read_b64_tr_b16 v[142:143], v230 offset:18432
	v_exp_f32_e32 v214, v214
	v_exp_f32_e32 v215, v215
	v_add_f32_e32 v252, v252, v212
	v_add_f32_e32 v253, v253, v213
	s_waitcnt lgkmcnt(9)
	v_mfma_f32_32x32x16_bf16 v[84:99], v[220:223], v[124:127], v[84:99]
	ds_read_b64_tr_b16 v[144:145], v231 offset:16384
	ds_read_b64_tr_b16 v[146:147], v231 offset:18432
	v_add_f32_e32 v252, v252, v214
	v_add_f32_e32 v253, v253, v215
	v_exp_f32_e32 v216, v216
	s_waitcnt lgkmcnt(10)
	v_mfma_f32_32x32x16_bf16 v[100:115], v[224:227], v[124:127], v[100:115]
	ds_read_b64_tr_b16 v[220:221], v228 offset:20480
	ds_read_b64_tr_b16 v[222:223], v228 offset:22528
	v_exp_f32_e32 v217, v217
	v_cvt_pk_bf16_f32 v208, v212, v213
	v_cvt_pk_bf16_f32 v209, v214, v215
	s_waitcnt lgkmcnt(11)
	v_mfma_f32_32x32x16_bf16 v[84:99], v[232:235], v[128:131], v[84:99]
	ds_read_b64_tr_b16 v[224:225], v229 offset:20480
	ds_read_b64_tr_b16 v[226:227], v229 offset:22528
	v_exp_f32_e32 v218, v218
	v_exp_f32_e32 v219, v219
	v_add_f32_e32 v252, v252, v216
	s_waitcnt lgkmcnt(12)
	v_mfma_f32_32x32x16_bf16 v[100:115], v[236:239], v[128:131], v[100:115]
	ds_read_b64_tr_b16 v[232:233], v230 offset:20480
	ds_read_b64_tr_b16 v[234:235], v230 offset:22528
	v_add_f32_e32 v253, v253, v217
	v_add_f32_e32 v252, v252, v218
	v_add_f32_e32 v253, v253, v219
	v_cvt_pk_bf16_f32 v210, v216, v217
	v_cvt_pk_bf16_f32 v211, v218, v219
	v_max_f32_e32 v251, v252, v253
	v_cmp_nge_f32_e32 vcc, 0x45800000, v251
	s_cbranch_vccnz .LatB_recs_h1

; #define LAS __attribute__((address_space(3)))
; #define VREADS1(arr, d_) do { const unsigned ad_ = vbase ^ (unsigned)((d_) << 6); __builtin_amdgcn_sched_barrier(0); \
;         _Pragma("unroll") for (int ks_ = 0; ks_ < 4; ++ks_) { VTR(arr[ks_ * 2], ad_, ks_ * 4096); VTR(arr[ks_ * 2 + 1], ad_, ks_ * 4096 + 2048); } __builtin_amdgcn_sched_barrier(0); } while (0)
; #define PV1(arr, d_) do { _Pragma("unroll") for (int ks_ = 0; ks_ < 4; ++ks_) { const s16x4 lo_ = arr[ks_ * 2], hh_ = arr[ks_ * 2 + 1]; \
;         const bf16x8 bv_ = (bf16x8){lo_[0], lo_[1], lo_[2], lo_[3], hh_[0], hh_[1], hh_[2], hh_[3]}; \
;         O[d_] = __builtin_amdgcn_mfma_f32_32x32x16_bf16(pa[ks_], bv_, O[d_], 0, 0, 0); } __builtin_amdgcn_sched_barrier(0); } while (0)
; #define LGKM0() do { __builtin_amdgcn_sched_barrier(0); asm volatile("s_waitcnt lgkmcnt(0)" ::: "memory"); __builtin_amdgcn_sched_barrier(0); } while (0)
; __device__ __forceinline__ void attn_unit(LAS unsigned char* lds, const bf16_t* Z, bf16_t* A2, const float* tabg, int seq_base, int S, int h, int qb, float lam) {
;     ...
;             for (int ds = 0; ds < 4; ++ds) { kf[2 * ds] = *(const LAS bf16x8*)(Kt + (kfo ^ (unsigned)(ds << 5))); kf[2 * ds + 1] = *(const LAS bf16x8*)(Kt + 32 * 256 + (kfo ^ (unsigned)(ds << 5))); }
;             __builtin_amdgcn_sched_barrier(0);
;             p0 = __builtin_amdgcn_mfma_f32_32x32x16_bf16(kf[0], qf[0], cblk, 0, 0, 0);
;             p1 = __builtin_amdgcn_mfma_f32_32x32x16_bf16(kf[1], qf[0], cblk, 0, 0, 0);
; #pragma unroll
;             for (int ds = 1; ds < 4; ++ds) {
;                 p0 = __builtin_amdgcn_mfma_f32_32x32x16_bf16(kf[2 * ds], qf[ds], p0, 0, 0, 0);
;                 p1 = __builtin_amdgcn_mfma_f32_32x32x16_bf16(kf[2 * ds + 1], qf[ds], p1, 0, 0, 0);
;             }
;     ...
; #pragma unroll
;         for (int r = 0; r < 16; ++r) { p0[r] = __builtin_amdgcn_exp2f(p0[r]); p1[r] = __builtin_amdgcn_exp2f(p1[r]); }
; #pragma unroll
;         for (int r = 0; r < 16; r += 2) { ls2 += (f32x2){p0[r], p0[r + 1]}; ls2 += (f32x2){p1[r], p1[r + 1]}; }
;         bf16x8 pa[4]; pa[0] = pack8(p0, 0); pa[1] = pack8(p0, 8); pa[2] = pack8(p1, 0); pa[3] = pack8(p1, 8);
;         LGKM0(); VREADS1(vb, 1); PV1(va, 0); LGKM0(); VREADS1(va, 2); PV1(vb, 1); LGKM0(); VREADS1(vb, 3); PV1(va, 2); LGKM0(); PV1(vb, 3);
.LatB_evret_h2:
	s_waitcnt lgkmcnt(12)
	v_mfma_f32_32x32x16_bf16 v[20:35], v[188:191], v[132:135], v[20:35]
	ds_read_b64_tr_b16 v[236:237], v231 offset:20480
	ds_read_b64_tr_b16 v[238:239], v231 offset:22528
	v_exp_f32_e32 v84, v84
	v_exp_f32_e32 v85, v85
	s_waitcnt lgkmcnt(12)
	v_mfma_f32_32x32x16_bf16 v[36:51], v[188:191], v[136:139], v[36:51]
	ds_read_b64_tr_b16 v[132:133], v228 offset:24576
	ds_read_b64_tr_b16 v[134:135], v228 offset:26624
	v_exp_f32_e32 v86, v86
	v_exp_f32_e32 v87, v87
	s_waitcnt lgkmcnt(12)
	v_mfma_f32_32x32x16_bf16 v[52:67], v[188:191], v[140:143], v[52:67]
	ds_read_b64_tr_b16 v[136:137], v229 offset:24576
	ds_read_b64_tr_b16 v[138:139], v229 offset:26624
	v_exp_f32_e32 v88, v88
	v_add_f32_e32 v252, v84, v86
	v_add_f32_e32 v253, v85, v87
	v_exp_f32_e32 v89, v89
	s_waitcnt lgkmcnt(12)
	s_add_u32 m0, s25, 0x4000
	v_mfma_f32_32x32x16_bf16 v[68:83], v[188:191], v[144:147], v[68:83]
	global_load_lds_dwordx4 v172, s[8:9]
	ds_read_b64_tr_b16 v[140:141], v230 offset:24576
	ds_read_b64_tr_b16 v[142:143], v230 offset:26624
	v_cvt_pk_bf16_f32 v84, v84, v85
	v_cvt_pk_bf16_f32 v85, v86, v87
	v_exp_f32_e32 v90, v90
	s_waitcnt lgkmcnt(12)
	v_mfma_f32_32x32x16_bf16 v[20:35], v[192:195], v[220:223], v[20:35]
	ds_read_b64_tr_b16 v[144:145], v231 offset:24576
	ds_read_b64_tr_b16 v[146:147], v231 offset:26624
	v_exp_f32_e32 v91, v91
	v_add_f32_e32 v252, v252, v88
	v_add_f32_e32 v253, v253, v89
	v_add_f32_e32 v252, v252, v90
	s_waitcnt lgkmcnt(12)
	v_mfma_f32_32x32x16_bf16 v[36:51], v[192:195], v[224:227], v[36:51]
	ds_read_b64_tr_b16 v[220:221], v228 offset:28672
	ds_read_b64_tr_b16 v[222:223], v228 offset:30720
	v_add_f32_e32 v253, v253, v91
	v_cvt_pk_bf16_f32 v86, v88, v89
	v_cvt_pk_bf16_f32 v87, v90, v91
	v_exp_f32_e32 v92, v92
	s_waitcnt lgkmcnt(12)
	v_mfma_f32_32x32x16_bf16 v[52:67], v[192:195], v[232:235], v[52:67]
	ds_read_b64_tr_b16 v[224:225], v229 offset:28672
	ds_read_b64_tr_b16 v[226:227], v229 offset:30720
	v_exp_f32_e32 v93, v93
	v_exp_f32_e32 v94, v94
	s_waitcnt lgkmcnt(12)
	s_mov_b32 m0, s27
	v_mfma_f32_32x32x16_bf16 v[68:83], v[192:195], v[236:239], v[68:83]
	global_load_lds_dwordx4 v174, s[8:9]
	ds_read_b64_tr_b16 v[232:233], v230 offset:28672
	ds_read_b64_tr_b16 v[234:235], v230 offset:30720
	v_exp_f32_e32 v95, v95
	v_add_f32_e32 v252, v252, v92
	v_add_f32_e32 v253, v253, v93
	v_add_f32_e32 v252, v252, v94
	s_waitcnt lgkmcnt(12)
	v_mfma_f32_32x32x16_bf16 v[20:35], v[204:207], v[132:135], v[20:35]
	ds_read_b64_tr_b16 v[236:237], v231 offset:28672
	ds_read_b64_tr_b16 v[238:239], v231 offset:30720
	v_add_f32_e32 v253, v253, v95
	v_exp_f32_e32 v96, v96
	s_waitcnt lgkmcnt(12)
	v_mfma_f32_32x32x16_bf16 v[36:51], v[204:207], v[136:139], v[36:51]
	ds_read_b128 v[132:135], v164
	v_exp_f32_e32 v97, v97
	v_cvt_pk_bf16_f32 v88, v92, v93
	v_cvt_pk_bf16_f32 v89, v94, v95
	v_exp_f32_e32 v98, v98
	s_waitcnt lgkmcnt(11)
	v_mfma_f32_32x32x16_bf16 v[52:67], v[204:207], v[140:143], v[52:67]
	ds_read_b128 v[136:139], v164 offset:8192
	v_exp_f32_e32 v99, v99
	v_add_f32_e32 v252, v252, v96
	v_add_f32_e32 v253, v253, v97
	s_waitcnt lgkmcnt(10)
	s_add_u32 m0, s25, 0x6000
	v_mfma_f32_32x32x16_bf16 v[68:83], v[204:207], v[144:147], v[68:83]
	global_load_lds_dwordx4 v173, s[8:9]
	ds_read_b128 v[140:143], v165
	v_add_f32_e32 v252, v252, v98
	v_add_f32_e32 v253, v253, v99
	v_cvt_pk_bf16_f32 v90, v96, v97
	v_cvt_pk_bf16_f32 v91, v98, v99
	s_waitcnt lgkmcnt(9)
	v_mfma_f32_32x32x16_bf16 v[20:35], v[208:211], v[220:223], v[20:35]
	ds_read_b128 v[144:147], v165 offset:8192
	v_exp_f32_e32 v100, v100
	v_exp_f32_e32 v101, v101
	v_exp_f32_e32 v102, v102
	s_waitcnt lgkmcnt(8)
	v_mfma_f32_32x32x16_bf16 v[36:51], v[208:211], v[224:227], v[36:51]
	ds_read_b128 v[220:223], v166
	v_exp_f32_e32 v103, v103
	v_add_f32_e32 v252, v252, v100
	v_add_f32_e32 v253, v253, v101
	s_waitcnt lgkmcnt(7)
	v_mfma_f32_32x32x16_bf16 v[52:67], v[208:211], v[232:235], v[52:67]
	ds_read_b128 v[224:227], v166 offset:8192
	v_add_f32_e32 v252, v252, v102
	v_add_f32_e32 v253, v253, v103
	v_exp_f32_e32 v104, v104
	s_waitcnt lgkmcnt(6)
	s_add_u32 m0, s27, 0x2000
	v_mfma_f32_32x32x16_bf16 v[68:83], v[208:211], v[236:239], v[68:83]
	global_load_lds_dwordx4 v175, s[8:9]
	ds_read_b128 v[232:235], v167
	v_exp_f32_e32 v105, v105
	v_cvt_pk_bf16_f32 v100, v100, v101
	v_cvt_pk_bf16_f32 v101, v102, v103
	s_waitcnt lgkmcnt(6)
	v_mfma_f32_32x32x16_bf16 v[188:203], v[132:135], v[116:119], v[2:17]
	ds_read_b128 v[236:239], v167 offset:8192
	v_exp_f32_e32 v106, v106
	v_exp_f32_e32 v107, v107
	v_add_f32_e32 v252, v252, v104
	v_add_f32_e32 v253, v253, v105
	s_waitcnt lgkmcnt(6)
	v_mfma_f32_32x32x16_bf16 v[204:219], v[136:139], v[116:119], v[2:17]
	ds_read_b64_tr_b16 v[132:133], v228 offset:32768
	ds_read_b64_tr_b16 v[134:135], v228 offset:34816
	v_add_f32_e32 v252, v252, v106
	v_add_f32_e32 v253, v253, v107
	v_cvt_pk_bf16_f32 v102, v104, v105
	v_cvt_pk_bf16_f32 v103, v106, v107
	s_waitcnt lgkmcnt(7)
	v_mfma_f32_32x32x16_bf16 v[188:203], v[140:143], v[120:123], v[188:203]
	ds_read_b64_tr_b16 v[136:137], v229 offset:32768
	ds_read_b64_tr_b16 v[138:139], v229 offset:34816
	v_exp_f32_e32 v108, v108
	v_exp_f32_e32 v109, v109
	s_waitcnt lgkmcnt(8)
	v_mfma_f32_32x32x16_bf16 v[204:219], v[144:147], v[120:123], v[204:219]
	ds_read_b64_tr_b16 v[140:141], v230 offset:32768
	ds_read_b64_tr_b16 v[142:143], v230 offset:34816
	v_exp_f32_e32 v110, v110
	v_exp_f32_e32 v111, v111
	v_add_f32_e32 v252, v252, v108
	v_add_f32_e32 v253, v253, v109
	s_waitcnt lgkmcnt(9)
	v_mfma_f32_32x32x16_bf16 v[188:203], v[220:223], v[124:127], v[188:203]
	ds_read_b64_tr_b16 v[144:145], v231 offset:32768
	ds_read_b64_tr_b16 v[146:147], v231 offset:34816
	v_add_f32_e32 v252, v252, v110
	v_add_f32_e32 v253, v253, v111
	v_exp_f32_e32 v112, v112
	s_waitcnt lgkmcnt(10)
	v_mfma_f32_32x32x16_bf16 v[204:219], v[224:227], v[124:127], v[204:219]
	ds_read_b64_tr_b16 v[220:221], v228 offset:36864
	ds_read_b64_tr_b16 v[222:223], v228 offset:38912
	v_exp_f32_e32 v113, v113
	v_cvt_pk_bf16_f32 v104, v108, v109
	v_cvt_pk_bf16_f32 v105, v110, v111
	s_waitcnt lgkmcnt(11)
	v_mfma_f32_32x32x16_bf16 v[188:203], v[232:235], v[128:131], v[188:203]
	ds_read_b64_tr_b16 v[224:225], v229 offset:36864
	ds_read_b64_tr_b16 v[226:227], v229 offset:38912
	v_exp_f32_e32 v114, v114
	v_exp_f32_e32 v115, v115
	v_add_f32_e32 v252, v252, v112
	s_waitcnt lgkmcnt(12)
	v_mfma_f32_32x32x16_bf16 v[204:219], v[236:239], v[128:131], v[204:219]
	ds_read_b64_tr_b16 v[232:233], v230 offset:36864
	ds_read_b64_tr_b16 v[234:235], v230 offset:38912
	v_add_f32_e32 v253, v253, v113
	v_add_f32_e32 v252, v252, v114
	v_add_f32_e32 v253, v253, v115
	v_cvt_pk_bf16_f32 v106, v112, v113
	v_cvt_pk_bf16_f32 v107, v114, v115
	v_max_f32_e32 v251, v252, v253
	v_cmp_nge_f32_e32 vcc, 0x45800000, v251
	s_cbranch_vccnz .LatB_recs_h2

; #define VREADS1(arr, d_) do { const unsigned ad_ = vbase ^ (unsigned)((d_) << 6); __builtin_amdgcn_sched_barrier(0); \
;         _Pragma("unroll") for (int ks_ = 0; ks_ < 4; ++ks_) { VTR(arr[ks_ * 2], ad_, ks_ * 4096); VTR(arr[ks_ * 2 + 1], ad_, ks_ * 4096 + 2048); } __builtin_amdgcn_sched_barrier(0); } while (0)
; #define PV1(arr, d_) do { _Pragma("unroll") for (int ks_ = 0; ks_ < 4; ++ks_) { const s16x4 lo_ = arr[ks_ * 2], hh_ = arr[ks_ * 2 + 1]; \
;         const bf16x8 bv_ = (bf16x8){lo_[0], lo_[1], lo_[2], lo_[3], hh_[0], hh_[1], hh_[2], hh_[3]}; \
;         O[d_] = __builtin_amdgcn_mfma_f32_32x32x16_bf16(pa[ks_], bv_, O[d_], 0, 0, 0); } __builtin_amdgcn_sched_barrier(0); } while (0)
; #define LGKM0() do { __builtin_amdgcn_sched_barrier(0); asm volatile("s_waitcnt lgkmcnt(0)" ::: "memory"); __builtin_amdgcn_sched_barrier(0); } while (0)
; __device__ __forceinline__ void attn_unit(LAS unsigned char* lds, const bf16_t* Z, bf16_t* A2, const float* tabg, int seq_base, int S, int h, int qb, float lam) {
;     ...
; #pragma unroll
;         for (int r = 0; r < 16; ++r) { p0[r] = __builtin_amdgcn_exp2f(p0[r]); p1[r] = __builtin_amdgcn_exp2f(p1[r]); }
; #pragma unroll
;         for (int r = 0; r < 16; r += 2) { ls2 += (f32x2){p0[r], p0[r + 1]}; ls2 += (f32x2){p1[r], p1[r + 1]}; }
;         bf16x8 pa[4]; pa[0] = pack8(p0, 0); pa[1] = pack8(p0, 8); pa[2] = pack8(p1, 0); pa[3] = pack8(p1, 8);
;         LGKM0(); VREADS1(vb, 1); PV1(va, 0); LGKM0(); VREADS1(va, 2); PV1(vb, 1); LGKM0(); VREADS1(vb, 3); PV1(va, 2); LGKM0(); PV1(vb, 3);
;     ...
;         if (t + 2 < NT) asm volatile("s_waitcnt vmcnt(4) lgkmcnt(0)" ::: "memory"); else asm volatile("s_waitcnt vmcnt(0) lgkmcnt(0)" ::: "memory");
;         __builtin_amdgcn_s_barrier(); asm volatile("" ::: "memory");
;         bc = (bc == NST - 1) ? 0 : bc + 1; bn = (bn == NST - 1) ? 0 : bn + 1;
;     }
;     const float ls = ls2[0] + ls2[1];
.LatB_evret_h3:
	s_waitcnt lgkmcnt(12)
	v_mfma_f32_32x32x16_bf16 v[20:35], v[84:87], v[132:135], v[20:35]
	ds_read_b64_tr_b16 v[236:237], v231 offset:36864
	ds_read_b64_tr_b16 v[238:239], v231 offset:38912
	v_exp_f32_e32 v188, v188
	v_exp_f32_e32 v189, v189
	s_waitcnt lgkmcnt(12)
	v_mfma_f32_32x32x16_bf16 v[36:51], v[84:87], v[136:139], v[36:51]
	ds_read_b64_tr_b16 v[132:133], v228 offset:40960
	ds_read_b64_tr_b16 v[134:135], v228 offset:43008
	v_exp_f32_e32 v190, v190
	v_exp_f32_e32 v191, v191
	s_waitcnt lgkmcnt(12)
	v_mfma_f32_32x32x16_bf16 v[52:67], v[84:87], v[140:143], v[52:67]
	ds_read_b64_tr_b16 v[136:137], v229 offset:40960
	ds_read_b64_tr_b16 v[138:139], v229 offset:43008
	v_exp_f32_e32 v192, v192
	v_add_f32_e32 v252, v188, v190
	v_add_f32_e32 v253, v189, v191
	v_exp_f32_e32 v193, v193
	s_waitcnt lgkmcnt(12)
	s_add_u32 m0, s25, 0x8000
	v_mfma_f32_32x32x16_bf16 v[68:83], v[84:87], v[144:147], v[68:83]
	global_load_lds_dwordx4 v172, s[8:9]
	ds_read_b64_tr_b16 v[140:141], v230 offset:40960
	ds_read_b64_tr_b16 v[142:143], v230 offset:43008
	v_cvt_pk_bf16_f32 v188, v188, v189
	v_cvt_pk_bf16_f32 v189, v190, v191
	v_exp_f32_e32 v194, v194
	s_waitcnt lgkmcnt(12)
	v_mfma_f32_32x32x16_bf16 v[20:35], v[88:91], v[220:223], v[20:35]
	ds_read_b64_tr_b16 v[144:145], v231 offset:40960
	ds_read_b64_tr_b16 v[146:147], v231 offset:43008
	v_exp_f32_e32 v195, v195
	v_add_f32_e32 v252, v252, v192
	v_add_f32_e32 v253, v253, v193
	v_add_f32_e32 v252, v252, v194
	s_waitcnt lgkmcnt(12)
	v_mfma_f32_32x32x16_bf16 v[36:51], v[88:91], v[224:227], v[36:51]
	ds_read_b64_tr_b16 v[220:221], v228 offset:45056
	ds_read_b64_tr_b16 v[222:223], v228 offset:47104
	v_add_f32_e32 v253, v253, v195
	v_cvt_pk_bf16_f32 v190, v192, v193
	v_cvt_pk_bf16_f32 v191, v194, v195
	v_exp_f32_e32 v196, v196
	s_waitcnt lgkmcnt(12)
	v_mfma_f32_32x32x16_bf16 v[52:67], v[88:91], v[232:235], v[52:67]
	ds_read_b64_tr_b16 v[224:225], v229 offset:45056
	ds_read_b64_tr_b16 v[226:227], v229 offset:47104
	v_exp_f32_e32 v197, v197
	v_exp_f32_e32 v198, v198
	s_waitcnt lgkmcnt(12)
	s_add_u32 m0, s27, 0x4000
	v_mfma_f32_32x32x16_bf16 v[68:83], v[88:91], v[236:239], v[68:83]
	global_load_lds_dwordx4 v174, s[8:9]
	ds_read_b64_tr_b16 v[232:233], v230 offset:45056
	ds_read_b64_tr_b16 v[234:235], v230 offset:47104
	v_exp_f32_e32 v199, v199
	v_add_f32_e32 v252, v252, v196
	v_add_f32_e32 v253, v253, v197
	v_add_f32_e32 v252, v252, v198
	s_waitcnt lgkmcnt(12)
	v_mfma_f32_32x32x16_bf16 v[20:35], v[100:103], v[132:135], v[20:35]
	ds_read_b64_tr_b16 v[236:237], v231 offset:45056
	ds_read_b64_tr_b16 v[238:239], v231 offset:47104
	v_add_f32_e32 v253, v253, v199
	v_exp_f32_e32 v200, v200
	s_waitcnt lgkmcnt(12)
	v_mfma_f32_32x32x16_bf16 v[36:51], v[100:103], v[136:139], v[36:51]
	ds_read_b128 v[132:135], v19
	v_exp_f32_e32 v201, v201
	v_cvt_pk_bf16_f32 v192, v196, v197
	v_cvt_pk_bf16_f32 v193, v198, v199
	v_exp_f32_e32 v202, v202
	s_waitcnt lgkmcnt(11)
	v_mfma_f32_32x32x16_bf16 v[52:67], v[100:103], v[140:143], v[52:67]
	ds_read_b128 v[136:139], v19 offset:8192
	v_exp_f32_e32 v203, v203
	v_add_f32_e32 v252, v252, v200
	v_add_f32_e32 v253, v253, v201
	s_waitcnt lgkmcnt(10)
	s_add_u32 m0, s25, 0xa000
	v_mfma_f32_32x32x16_bf16 v[68:83], v[100:103], v[144:147], v[68:83]
	global_load_lds_dwordx4 v173, s[8:9]
	ds_read_b128 v[140:143], v180
	v_add_f32_e32 v252, v252, v202
	v_add_f32_e32 v253, v253, v203
	v_cvt_pk_bf16_f32 v194, v200, v201
	v_cvt_pk_bf16_f32 v195, v202, v203
	s_waitcnt lgkmcnt(9)
	v_mfma_f32_32x32x16_bf16 v[20:35], v[104:107], v[220:223], v[20:35]
	ds_read_b128 v[144:147], v180 offset:8192
	v_exp_f32_e32 v204, v204
	v_exp_f32_e32 v205, v205
	v_exp_f32_e32 v206, v206
	s_waitcnt lgkmcnt(8)
	v_mfma_f32_32x32x16_bf16 v[36:51], v[104:107], v[224:227], v[36:51]
	ds_read_b128 v[220:223], v181
	v_exp_f32_e32 v207, v207
	v_add_f32_e32 v252, v252, v204
	v_add_f32_e32 v253, v253, v205
	s_waitcnt lgkmcnt(7)
	v_mfma_f32_32x32x16_bf16 v[52:67], v[104:107], v[232:235], v[52:67]
	ds_read_b128 v[224:227], v181 offset:8192
	v_add_f32_e32 v252, v252, v206
	v_add_f32_e32 v253, v253, v207
	v_exp_f32_e32 v208, v208
	s_waitcnt lgkmcnt(6)
	s_add_u32 m0, s27, 0x6000
	v_mfma_f32_32x32x16_bf16 v[68:83], v[104:107], v[236:239], v[68:83]
	global_load_lds_dwordx4 v175, s[8:9]
	ds_read_b128 v[232:235], v182
	v_exp_f32_e32 v209, v209
	v_cvt_pk_bf16_f32 v204, v204, v205
	v_cvt_pk_bf16_f32 v205, v206, v207
	s_waitcnt lgkmcnt(6)
	v_mfma_f32_32x32x16_bf16 v[84:99], v[132:135], v[116:119], v[2:17]
	ds_read_b128 v[236:239], v182 offset:8192
	v_exp_f32_e32 v210, v210
	v_exp_f32_e32 v211, v211
	v_add_f32_e32 v252, v252, v208
	v_add_f32_e32 v253, v253, v209
	s_waitcnt lgkmcnt(6)
	v_mfma_f32_32x32x16_bf16 v[100:115], v[136:139], v[116:119], v[2:17]
	ds_read_b64_tr_b16 v[132:133], v168 offset:0
	ds_read_b64_tr_b16 v[134:135], v168 offset:2048
	v_add_f32_e32 v252, v252, v210
	v_add_f32_e32 v253, v253, v211
	v_cvt_pk_bf16_f32 v206, v208, v209
	v_cvt_pk_bf16_f32 v207, v210, v211
	s_waitcnt lgkmcnt(7)
	v_mfma_f32_32x32x16_bf16 v[84:99], v[140:143], v[120:123], v[84:99]
	ds_read_b64_tr_b16 v[136:137], v169 offset:0
	ds_read_b64_tr_b16 v[138:139], v169 offset:2048
	v_exp_f32_e32 v212, v212
	v_exp_f32_e32 v213, v213
	s_waitcnt lgkmcnt(8)
	v_mfma_f32_32x32x16_bf16 v[100:115], v[144:147], v[120:123], v[100:115]
	ds_read_b64_tr_b16 v[140:141], v170 offset:0
	ds_read_b64_tr_b16 v[142:143], v170 offset:2048
	v_exp_f32_e32 v214, v214
	v_exp_f32_e32 v215, v215
	v_add_f32_e32 v252, v252, v212
	v_add_f32_e32 v253, v253, v213
	s_waitcnt lgkmcnt(9)
	v_mfma_f32_32x32x16_bf16 v[84:99], v[220:223], v[124:127], v[84:99]
	ds_read_b64_tr_b16 v[144:145], v171 offset:0
	ds_read_b64_tr_b16 v[146:147], v171 offset:2048
	v_add_f32_e32 v252, v252, v214
	v_add_f32_e32 v253, v253, v215
	v_exp_f32_e32 v216, v216
	s_waitcnt lgkmcnt(10)
	v_mfma_f32_32x32x16_bf16 v[100:115], v[224:227], v[124:127], v[100:115]
	ds_read_b64_tr_b16 v[220:221], v168 offset:4096
	ds_read_b64_tr_b16 v[222:223], v168 offset:6144
	v_exp_f32_e32 v217, v217
	v_cvt_pk_bf16_f32 v208, v212, v213
	v_cvt_pk_bf16_f32 v209, v214, v215
	s_waitcnt lgkmcnt(11)
	v_mfma_f32_32x32x16_bf16 v[84:99], v[232:235], v[128:131], v[84:99]
	ds_read_b64_tr_b16 v[224:225], v169 offset:4096
	ds_read_b64_tr_b16 v[226:227], v169 offset:6144
	v_exp_f32_e32 v218, v218
	v_exp_f32_e32 v219, v219
	v_add_f32_e32 v252, v252, v216
	s_waitcnt lgkmcnt(12)
	v_mfma_f32_32x32x16_bf16 v[100:115], v[236:239], v[128:131], v[100:115]
	ds_read_b64_tr_b16 v[232:233], v170 offset:4096
	ds_read_b64_tr_b16 v[234:235], v170 offset:6144
	v_add_f32_e32 v253, v253, v217
	v_add_f32_e32 v252, v252, v218
	v_add_f32_e32 v253, v253, v219
	v_cvt_pk_bf16_f32 v210, v216, v217
	v_cvt_pk_bf16_f32 v211, v218, v219
	v_max_f32_e32 v251, v252, v253
	v_cmp_nge_f32_e32 vcc, 0x45800000, v251
	s_cbranch_vccnz .LatB_recs_h3
.LatB_recret_h3:
	v_add_f32_e32 v150, v150, v252
	v_add_f32_e32 v151, v151, v253
	s_add_u32 s8, s8, 0x40000
	s_addc_u32 s9, s9, 0
	s_waitcnt vmcnt(4)
	s_barrier
	s_movk_i32 s36, 62

; #define LAS __attribute__((address_space(3)))
; #define VREADS1(arr, d_) do { const unsigned ad_ = vbase ^ (unsigned)((d_) << 6); __builtin_amdgcn_sched_barrier(0); \
;         _Pragma("unroll") for (int ks_ = 0; ks_ < 4; ++ks_) { VTR(arr[ks_ * 2], ad_, ks_ * 4096); VTR(arr[ks_ * 2 + 1], ad_, ks_ * 4096 + 2048); } __builtin_amdgcn_sched_barrier(0); } while (0)
; #define PV1(arr, d_) do { _Pragma("unroll") for (int ks_ = 0; ks_ < 4; ++ks_) { const s16x4 lo_ = arr[ks_ * 2], hh_ = arr[ks_ * 2 + 1]; \
;         const bf16x8 bv_ = (bf16x8){lo_[0], lo_[1], lo_[2], lo_[3], hh_[0], hh_[1], hh_[2], hh_[3]}; \
;         O[d_] = __builtin_amdgcn_mfma_f32_32x32x16_bf16(pa[ks_], bv_, O[d_], 0, 0, 0); } __builtin_amdgcn_sched_barrier(0); } while (0)
; #define LGKM0() do { __builtin_amdgcn_sched_barrier(0); asm volatile("s_waitcnt lgkmcnt(0)" ::: "memory"); __builtin_amdgcn_sched_barrier(0); } while (0)
; __device__ __forceinline__ void attn_unit(LAS unsigned char* lds, const bf16_t* Z, bf16_t* A2, const float* tabg, int seq_base, int S, int h, int qb, float lam) {
;     ...
;             for (int ds = 0; ds < 4; ++ds) { kf[2 * ds] = *(const LAS bf16x8*)(Kt + (kfo ^ (unsigned)(ds << 5))); kf[2 * ds + 1] = *(const LAS bf16x8*)(Kt + 32 * 256 + (kfo ^ (unsigned)(ds << 5))); }
;             __builtin_amdgcn_sched_barrier(0);
;             p0 = __builtin_amdgcn_mfma_f32_32x32x16_bf16(kf[0], qf[0], cblk, 0, 0, 0);
;             p1 = __builtin_amdgcn_mfma_f32_32x32x16_bf16(kf[1], qf[0], cblk, 0, 0, 0);
; #pragma unroll
;             for (int ds = 1; ds < 4; ++ds) {
;                 p0 = __builtin_amdgcn_mfma_f32_32x32x16_bf16(kf[2 * ds], qf[ds], p0, 0, 0, 0);
;                 p1 = __builtin_amdgcn_mfma_f32_32x32x16_bf16(kf[2 * ds + 1], qf[ds], p1, 0, 0, 0);
;             }
;     ...
; #pragma unroll
;         for (int r = 0; r < 16; ++r) { p0[r] = __builtin_amdgcn_exp2f(p0[r]); p1[r] = __builtin_amdgcn_exp2f(p1[r]); }
; #pragma unroll
;         for (int r = 0; r < 16; r += 2) { ls2 += (f32x2){p0[r], p0[r + 1]}; ls2 += (f32x2){p1[r], p1[r + 1]}; }
;         bf16x8 pa[4]; pa[0] = pack8(p0, 0); pa[1] = pack8(p0, 8); pa[2] = pack8(p1, 0); pa[3] = pack8(p1, 8);
;         LGKM0(); VREADS1(vb, 1); PV1(va, 0); LGKM0(); VREADS1(va, 2); PV1(vb, 1); LGKM0(); VREADS1(vb, 3); PV1(va, 2); LGKM0(); PV1(vb, 3);
.LatB_evret_m0:
	s_waitcnt lgkmcnt(12)
	v_mfma_f32_32x32x16_bf16 v[20:35], v[188:191], v[132:135], v[20:35]
	ds_read_b64_tr_b16 v[236:237], v171 offset:4096
	ds_read_b64_tr_b16 v[238:239], v171 offset:6144
	v_exp_f32_e32 v84, v84
	v_exp_f32_e32 v85, v85
	s_waitcnt lgkmcnt(12)
	v_mfma_f32_32x32x16_bf16 v[36:51], v[188:191], v[136:139], v[36:51]
	ds_read_b64_tr_b16 v[132:133], v168 offset:8192
	ds_read_b64_tr_b16 v[134:135], v168 offset:10240
	v_exp_f32_e32 v86, v86
	v_exp_f32_e32 v87, v87
	s_waitcnt lgkmcnt(12)
	v_mfma_f32_32x32x16_bf16 v[52:67], v[188:191], v[140:143], v[52:67]
	ds_read_b64_tr_b16 v[136:137], v169 offset:8192
	ds_read_b64_tr_b16 v[138:139], v169 offset:10240
	v_exp_f32_e32 v88, v88
	v_add_f32_e32 v252, v84, v86
	v_add_f32_e32 v253, v85, v87
	v_exp_f32_e32 v89, v89
	s_waitcnt lgkmcnt(12)
	s_add_u32 m0, s25, 0x1d000
	v_mfma_f32_32x32x16_bf16 v[68:83], v[188:191], v[144:147], v[68:83]
	global_load_lds_dwordx4 v172, s[8:9]
	ds_read_b64_tr_b16 v[140:141], v170 offset:8192
	ds_read_b64_tr_b16 v[142:143], v170 offset:10240
	v_cvt_pk_bf16_f32 v84, v84, v85
	v_cvt_pk_bf16_f32 v85, v86, v87
	v_exp_f32_e32 v90, v90
	s_waitcnt lgkmcnt(12)
	v_mfma_f32_32x32x16_bf16 v[20:35], v[192:195], v[220:223], v[20:35]
	ds_read_b64_tr_b16 v[144:145], v171 offset:8192
	ds_read_b64_tr_b16 v[146:147], v171 offset:10240
	v_exp_f32_e32 v91, v91
	v_add_f32_e32 v252, v252, v88
	v_add_f32_e32 v253, v253, v89
	v_add_f32_e32 v252, v252, v90
	s_waitcnt lgkmcnt(12)
	v_mfma_f32_32x32x16_bf16 v[36:51], v[192:195], v[224:227], v[36:51]
	ds_read_b64_tr_b16 v[220:221], v168 offset:12288
	ds_read_b64_tr_b16 v[222:223], v168 offset:14336
	v_add_f32_e32 v253, v253, v91
	v_cvt_pk_bf16_f32 v86, v88, v89
	v_cvt_pk_bf16_f32 v87, v90, v91
	v_exp_f32_e32 v92, v92
	s_waitcnt lgkmcnt(12)
	v_mfma_f32_32x32x16_bf16 v[52:67], v[192:195], v[232:235], v[52:67]
	ds_read_b64_tr_b16 v[224:225], v169 offset:12288
	ds_read_b64_tr_b16 v[226:227], v169 offset:14336
	v_exp_f32_e32 v93, v93
	v_exp_f32_e32 v94, v94
	s_waitcnt lgkmcnt(12)
	s_add_u32 m0, s27, 0x8000
	v_mfma_f32_32x32x16_bf16 v[68:83], v[192:195], v[236:239], v[68:83]
	global_load_lds_dwordx4 v174, s[8:9]
	ds_read_b64_tr_b16 v[232:233], v170 offset:12288
	ds_read_b64_tr_b16 v[234:235], v170 offset:14336
	v_exp_f32_e32 v95, v95
	v_add_f32_e32 v252, v252, v92
	v_add_f32_e32 v253, v253, v93
	v_add_f32_e32 v252, v252, v94
	s_waitcnt lgkmcnt(12)
	v_mfma_f32_32x32x16_bf16 v[20:35], v[204:207], v[132:135], v[20:35]
	ds_read_b64_tr_b16 v[236:237], v171 offset:12288
	ds_read_b64_tr_b16 v[238:239], v171 offset:14336
	v_add_f32_e32 v253, v253, v95
	v_exp_f32_e32 v96, v96
	s_waitcnt lgkmcnt(12)
	v_mfma_f32_32x32x16_bf16 v[36:51], v[204:207], v[136:139], v[36:51]
	ds_read_b128 v[132:135], v19 offset:16384
	v_exp_f32_e32 v97, v97
	v_cvt_pk_bf16_f32 v88, v92, v93
	v_cvt_pk_bf16_f32 v89, v94, v95
	v_exp_f32_e32 v98, v98
	s_waitcnt lgkmcnt(11)
	v_mfma_f32_32x32x16_bf16 v[52:67], v[204:207], v[140:143], v[52:67]
	ds_read_b128 v[136:139], v19 offset:24576
	v_exp_f32_e32 v99, v99
	v_add_f32_e32 v252, v252, v96
	v_add_f32_e32 v253, v253, v97
	s_waitcnt lgkmcnt(10)
	s_add_u32 m0, s25, 0x1f000
	v_mfma_f32_32x32x16_bf16 v[68:83], v[204:207], v[144:147], v[68:83]
	global_load_lds_dwordx4 v173, s[8:9]
	ds_read_b128 v[140:143], v180 offset:16384
	v_add_f32_e32 v252, v252, v98
	v_add_f32_e32 v253, v253, v99
	v_cvt_pk_bf16_f32 v90, v96, v97
	v_cvt_pk_bf16_f32 v91, v98, v99
	s_waitcnt lgkmcnt(9)
	v_mfma_f32_32x32x16_bf16 v[20:35], v[208:211], v[220:223], v[20:35]
	ds_read_b128 v[144:147], v180 offset:24576
	v_exp_f32_e32 v100, v100
	v_exp_f32_e32 v101, v101
	v_exp_f32_e32 v102, v102
	s_waitcnt lgkmcnt(8)
	v_mfma_f32_32x32x16_bf16 v[36:51], v[208:211], v[224:227], v[36:51]
	ds_read_b128 v[220:223], v181 offset:16384
	v_exp_f32_e32 v103, v103
	v_add_f32_e32 v252, v252, v100
	v_add_f32_e32 v253, v253, v101
	s_waitcnt lgkmcnt(7)
	v_mfma_f32_32x32x16_bf16 v[52:67], v[208:211], v[232:235], v[52:67]
	ds_read_b128 v[224:227], v181 offset:24576
	v_add_f32_e32 v252, v252, v102
	v_add_f32_e32 v253, v253, v103
	v_exp_f32_e32 v104, v104
	s_waitcnt lgkmcnt(6)
	s_add_u32 m0, s27, 0xa000
	v_mfma_f32_32x32x16_bf16 v[68:83], v[208:211], v[236:239], v[68:83]
	global_load_lds_dwordx4 v175, s[8:9]
	ds_read_b128 v[232:235], v182 offset:16384
	v_exp_f32_e32 v105, v105
	v_cvt_pk_bf16_f32 v100, v100, v101
	v_cvt_pk_bf16_f32 v101, v102, v103
	s_waitcnt lgkmcnt(6)
	v_mfma_f32_32x32x16_bf16 v[188:203], v[132:135], v[116:119], v[2:17]
	ds_read_b128 v[236:239], v182 offset:24576
	v_exp_f32_e32 v106, v106
	v_exp_f32_e32 v107, v107
	v_add_f32_e32 v252, v252, v104
	v_add_f32_e32 v253, v253, v105
	s_waitcnt lgkmcnt(6)
	v_mfma_f32_32x32x16_bf16 v[204:219], v[136:139], v[116:119], v[2:17]
	ds_read_b64_tr_b16 v[132:133], v228 offset:0
	ds_read_b64_tr_b16 v[134:135], v228 offset:2048
	v_add_f32_e32 v252, v252, v106
	v_add_f32_e32 v253, v253, v107
	v_cvt_pk_bf16_f32 v102, v104, v105
	v_cvt_pk_bf16_f32 v103, v106, v107
	s_waitcnt lgkmcnt(7)
	v_mfma_f32_32x32x16_bf16 v[188:203], v[140:143], v[120:123], v[188:203]
	ds_read_b64_tr_b16 v[136:137], v229 offset:0
	ds_read_b64_tr_b16 v[138:139], v229 offset:2048
	v_exp_f32_e32 v108, v108
	v_exp_f32_e32 v109, v109
	s_waitcnt lgkmcnt(8)
	v_mfma_f32_32x32x16_bf16 v[204:219], v[144:147], v[120:123], v[204:219]
	ds_read_b64_tr_b16 v[140:141], v230 offset:0
	ds_read_b64_tr_b16 v[142:143], v230 offset:2048
	v_exp_f32_e32 v110, v110
	v_exp_f32_e32 v111, v111
	v_add_f32_e32 v252, v252, v108
	v_add_f32_e32 v253, v253, v109
	s_waitcnt lgkmcnt(9)
	v_mfma_f32_32x32x16_bf16 v[188:203], v[220:223], v[124:127], v[188:203]
	ds_read_b64_tr_b16 v[144:145], v231 offset:0
	ds_read_b64_tr_b16 v[146:147], v231 offset:2048
	v_add_f32_e32 v252, v252, v110
	v_add_f32_e32 v253, v253, v111
	v_exp_f32_e32 v112, v112
	s_waitcnt lgkmcnt(10)
	v_mfma_f32_32x32x16_bf16 v[204:219], v[224:227], v[124:127], v[204:219]
	ds_read_b64_tr_b16 v[220:221], v228 offset:4096
	ds_read_b64_tr_b16 v[222:223], v228 offset:6144
	v_exp_f32_e32 v113, v113
	v_cvt_pk_bf16_f32 v104, v108, v109
	v_cvt_pk_bf16_f32 v105, v110, v111
	s_waitcnt lgkmcnt(11)
	v_mfma_f32_32x32x16_bf16 v[188:203], v[232:235], v[128:131], v[188:203]
	ds_read_b64_tr_b16 v[224:225], v229 offset:4096
	ds_read_b64_tr_b16 v[226:227], v229 offset:6144
	v_exp_f32_e32 v114, v114
	v_exp_f32_e32 v115, v115
	v_add_f32_e32 v252, v252, v112
	s_waitcnt lgkmcnt(12)
	v_mfma_f32_32x32x16_bf16 v[204:219], v[236:239], v[128:131], v[204:219]
	ds_read_b64_tr_b16 v[232:233], v230 offset:4096
	ds_read_b64_tr_b16 v[234:235], v230 offset:6144
	v_add_f32_e32 v253, v253, v113
	v_add_f32_e32 v252, v252, v114
	v_add_f32_e32 v253, v253, v115
	v_cvt_pk_bf16_f32 v106, v112, v113
	v_cvt_pk_bf16_f32 v107, v114, v115
	v_max_f32_e32 v251, v252, v253
	v_cmp_nge_f32_e32 vcc, 0x45800000, v251
	s_cbranch_vccnz .LatB_recs_m0

; #define LAS __attribute__((address_space(3)))
; #define VREADS1(arr, d_) do { const unsigned ad_ = vbase ^ (unsigned)((d_) << 6); __builtin_amdgcn_sched_barrier(0); \
;         _Pragma("unroll") for (int ks_ = 0; ks_ < 4; ++ks_) { VTR(arr[ks_ * 2], ad_, ks_ * 4096); VTR(arr[ks_ * 2 + 1], ad_, ks_ * 4096 + 2048); } __builtin_amdgcn_sched_barrier(0); } while (0)
; #define PV1(arr, d_) do { _Pragma("unroll") for (int ks_ = 0; ks_ < 4; ++ks_) { const s16x4 lo_ = arr[ks_ * 2], hh_ = arr[ks_ * 2 + 1]; \
;         const bf16x8 bv_ = (bf16x8){lo_[0], lo_[1], lo_[2], lo_[3], hh_[0], hh_[1], hh_[2], hh_[3]}; \
;         O[d_] = __builtin_amdgcn_mfma_f32_32x32x16_bf16(pa[ks_], bv_, O[d_], 0, 0, 0); } __builtin_amdgcn_sched_barrier(0); } while (0)
; #define LGKM0() do { __builtin_amdgcn_sched_barrier(0); asm volatile("s_waitcnt lgkmcnt(0)" ::: "memory"); __builtin_amdgcn_sched_barrier(0); } while (0)
; __device__ __forceinline__ void attn_unit(LAS unsigned char* lds, const bf16_t* Z, bf16_t* A2, const float* tabg, int seq_base, int S, int h, int qb, float lam) {
;     ...
;             for (int ds = 0; ds < 4; ++ds) { kf[2 * ds] = *(const LAS bf16x8*)(Kt + (kfo ^ (unsigned)(ds << 5))); kf[2 * ds + 1] = *(const LAS bf16x8*)(Kt + 32 * 256 + (kfo ^ (unsigned)(ds << 5))); }
;             __builtin_amdgcn_sched_barrier(0);
;             p0 = __builtin_amdgcn_mfma_f32_32x32x16_bf16(kf[0], qf[0], cblk, 0, 0, 0);
;             p1 = __builtin_amdgcn_mfma_f32_32x32x16_bf16(kf[1], qf[0], cblk, 0, 0, 0);
; #pragma unroll
;             for (int ds = 1; ds < 4; ++ds) {
;                 p0 = __builtin_amdgcn_mfma_f32_32x32x16_bf16(kf[2 * ds], qf[ds], p0, 0, 0, 0);
;                 p1 = __builtin_amdgcn_mfma_f32_32x32x16_bf16(kf[2 * ds + 1], qf[ds], p1, 0, 0, 0);
;             }
;     ...
; #pragma unroll
;         for (int r = 0; r < 16; ++r) { p0[r] = __builtin_amdgcn_exp2f(p0[r]); p1[r] = __builtin_amdgcn_exp2f(p1[r]); }
; #pragma unroll
;         for (int r = 0; r < 16; r += 2) { ls2 += (f32x2){p0[r], p0[r + 1]}; ls2 += (f32x2){p1[r], p1[r + 1]}; }
;         bf16x8 pa[4]; pa[0] = pack8(p0, 0); pa[1] = pack8(p0, 8); pa[2] = pack8(p1, 0); pa[3] = pack8(p1, 8);
;         LGKM0(); VREADS1(vb, 1); PV1(va, 0); LGKM0(); VREADS1(va, 2); PV1(vb, 1); LGKM0(); VREADS1(vb, 3); PV1(va, 2); LGKM0(); PV1(vb, 3);
.LatB_evret_x3:
	s_waitcnt lgkmcnt(12)
	v_mfma_f32_32x32x16_bf16 v[20:35], v[84:87], v[132:135], v[20:35]
	ds_read_b64_tr_b16 v[236:237], v231 offset:4096
	ds_read_b64_tr_b16 v[238:239], v231 offset:6144
	v_exp_f32_e32 v188, v188
	v_exp_f32_e32 v189, v189
	s_waitcnt lgkmcnt(12)
	v_mfma_f32_32x32x16_bf16 v[36:51], v[84:87], v[136:139], v[36:51]
	ds_read_b64_tr_b16 v[132:133], v228 offset:8192
	ds_read_b64_tr_b16 v[134:135], v228 offset:10240
	v_exp_f32_e32 v190, v190
	v_exp_f32_e32 v191, v191
	s_waitcnt lgkmcnt(12)
	v_mfma_f32_32x32x16_bf16 v[52:67], v[84:87], v[140:143], v[52:67]
	ds_read_b64_tr_b16 v[136:137], v229 offset:8192
	ds_read_b64_tr_b16 v[138:139], v229 offset:10240
	v_exp_f32_e32 v192, v192
	v_add_f32_e32 v252, v188, v190
	v_add_f32_e32 v253, v189, v191
	v_exp_f32_e32 v193, v193
	s_waitcnt lgkmcnt(12)
	v_mfma_f32_32x32x16_bf16 v[68:83], v[84:87], v[144:147], v[68:83]
	ds_read_b64_tr_b16 v[140:141], v230 offset:8192
	ds_read_b64_tr_b16 v[142:143], v230 offset:10240
	v_cvt_pk_bf16_f32 v188, v188, v189
	v_cvt_pk_bf16_f32 v189, v190, v191
	v_exp_f32_e32 v194, v194
	s_waitcnt lgkmcnt(12)
	v_mfma_f32_32x32x16_bf16 v[20:35], v[88:91], v[220:223], v[20:35]
	ds_read_b64_tr_b16 v[144:145], v231 offset:8192
	ds_read_b64_tr_b16 v[146:147], v231 offset:10240
	v_exp_f32_e32 v195, v195
	v_add_f32_e32 v252, v252, v192
	v_add_f32_e32 v253, v253, v193
	v_add_f32_e32 v252, v252, v194
	s_waitcnt lgkmcnt(12)
	v_mfma_f32_32x32x16_bf16 v[36:51], v[88:91], v[224:227], v[36:51]
	ds_read_b64_tr_b16 v[220:221], v228 offset:12288
	ds_read_b64_tr_b16 v[222:223], v228 offset:14336
	v_add_f32_e32 v253, v253, v195
	v_cvt_pk_bf16_f32 v190, v192, v193
	v_cvt_pk_bf16_f32 v191, v194, v195
	v_exp_f32_e32 v196, v196
	s_waitcnt lgkmcnt(12)
	v_mfma_f32_32x32x16_bf16 v[52:67], v[88:91], v[232:235], v[52:67]
	ds_read_b64_tr_b16 v[224:225], v229 offset:12288
	ds_read_b64_tr_b16 v[226:227], v229 offset:14336
	v_exp_f32_e32 v197, v197
	v_exp_f32_e32 v198, v198
	s_waitcnt lgkmcnt(12)
	s_add_u32 m0, s27, 0xd000
	v_mfma_f32_32x32x16_bf16 v[68:83], v[88:91], v[236:239], v[68:83]
	global_load_lds_dwordx4 v174, s[8:9]
	ds_read_b64_tr_b16 v[232:233], v230 offset:12288
	ds_read_b64_tr_b16 v[234:235], v230 offset:14336
	v_exp_f32_e32 v199, v199
	v_add_f32_e32 v252, v252, v196
	v_add_f32_e32 v253, v253, v197
	v_add_f32_e32 v252, v252, v198
	s_waitcnt lgkmcnt(12)
	v_mfma_f32_32x32x16_bf16 v[20:35], v[100:103], v[132:135], v[20:35]
	ds_read_b64_tr_b16 v[236:237], v231 offset:12288
	ds_read_b64_tr_b16 v[238:239], v231 offset:14336
	v_add_f32_e32 v253, v253, v199
	v_exp_f32_e32 v200, v200
	s_waitcnt lgkmcnt(12)
	v_mfma_f32_32x32x16_bf16 v[36:51], v[100:103], v[136:139], v[36:51]
	ds_read_b128 v[132:135], v19 offset:32768
	v_exp_f32_e32 v201, v201
	v_cvt_pk_bf16_f32 v192, v196, v197
	v_cvt_pk_bf16_f32 v193, v198, v199
	v_exp_f32_e32 v202, v202
	s_waitcnt lgkmcnt(11)
	v_mfma_f32_32x32x16_bf16 v[52:67], v[100:103], v[140:143], v[52:67]
	ds_read_b128 v[136:139], v19 offset:40960
	v_exp_f32_e32 v203, v203
	v_add_f32_e32 v252, v252, v200
	v_add_f32_e32 v253, v253, v201
	s_waitcnt lgkmcnt(10)
	v_mfma_f32_32x32x16_bf16 v[68:83], v[100:103], v[144:147], v[68:83]
	ds_read_b128 v[140:143], v180 offset:32768
	v_add_f32_e32 v252, v252, v202
	v_add_f32_e32 v253, v253, v203
	v_cvt_pk_bf16_f32 v194, v200, v201
	v_cvt_pk_bf16_f32 v195, v202, v203
	s_waitcnt lgkmcnt(9)
	v_mfma_f32_32x32x16_bf16 v[20:35], v[104:107], v[220:223], v[20:35]
	ds_read_b128 v[144:147], v180 offset:40960
	v_exp_f32_e32 v204, v204
	v_exp_f32_e32 v205, v205
	v_exp_f32_e32 v206, v206
	s_waitcnt lgkmcnt(8)
	v_mfma_f32_32x32x16_bf16 v[36:51], v[104:107], v[224:227], v[36:51]
	ds_read_b128 v[220:223], v181 offset:32768
	v_exp_f32_e32 v207, v207
	v_add_f32_e32 v252, v252, v204
	v_add_f32_e32 v253, v253, v205
	s_waitcnt lgkmcnt(7)
	v_mfma_f32_32x32x16_bf16 v[52:67], v[104:107], v[232:235], v[52:67]
	ds_read_b128 v[224:227], v181 offset:40960
	v_add_f32_e32 v252, v252, v206
	v_add_f32_e32 v253, v253, v207
	v_exp_f32_e32 v208, v208
	s_waitcnt lgkmcnt(6)
	s_add_u32 m0, s27, 0xf000
	v_mfma_f32_32x32x16_bf16 v[68:83], v[104:107], v[236:239], v[68:83]
	global_load_lds_dwordx4 v175, s[8:9]
	ds_read_b128 v[232:235], v182 offset:32768
	v_exp_f32_e32 v209, v209
	v_cvt_pk_bf16_f32 v204, v204, v205
	v_cvt_pk_bf16_f32 v205, v206, v207
	s_waitcnt lgkmcnt(6)
	v_mfma_f32_32x32x16_bf16 v[84:99], v[132:135], v[116:119], v[2:17]
	ds_read_b128 v[236:239], v182 offset:40960
	v_exp_f32_e32 v210, v210
	v_exp_f32_e32 v211, v211
	v_add_f32_e32 v252, v252, v208
	v_add_f32_e32 v253, v253, v209
	s_waitcnt lgkmcnt(6)
	v_mfma_f32_32x32x16_bf16 v[100:115], v[136:139], v[116:119], v[2:17]
	ds_read_b64_tr_b16 v[132:133], v228 offset:16384
	ds_read_b64_tr_b16 v[134:135], v228 offset:18432
	v_add_f32_e32 v252, v252, v210
	v_add_f32_e32 v253, v253, v211
	v_cvt_pk_bf16_f32 v206, v208, v209
	v_cvt_pk_bf16_f32 v207, v210, v211
	s_waitcnt lgkmcnt(7)
	v_mfma_f32_32x32x16_bf16 v[84:99], v[140:143], v[120:123], v[84:99]
	ds_read_b64_tr_b16 v[136:137], v229 offset:16384
	ds_read_b64_tr_b16 v[138:139], v229 offset:18432
	v_exp_f32_e32 v212, v212
	v_exp_f32_e32 v213, v213
	s_waitcnt lgkmcnt(8)
	v_mfma_f32_32x32x16_bf16 v[100:115], v[144:147], v[120:123], v[100:115]
	ds_read_b64_tr_b16 v[140:141], v230 offset:16384
	ds_read_b64_tr_b16 v[142:143], v230 offset:18432
	v_exp_f32_e32 v214, v214
	v_exp_f32_e32 v215, v215
	v_add_f32_e32 v252, v252, v212
	v_add_f32_e32 v253, v253, v213
	s_waitcnt lgkmcnt(9)
	v_mfma_f32_32x32x16_bf16 v[84:99], v[220:223], v[124:127], v[84:99]
	ds_read_b64_tr_b16 v[144:145], v231 offset:16384
	ds_read_b64_tr_b16 v[146:147], v231 offset:18432
	v_add_f32_e32 v252, v252, v214
	v_add_f32_e32 v253, v253, v215
	v_exp_f32_e32 v216, v216
	s_waitcnt lgkmcnt(10)
	v_mfma_f32_32x32x16_bf16 v[100:115], v[224:227], v[124:127], v[100:115]
	ds_read_b64_tr_b16 v[220:221], v228 offset:20480
	ds_read_b64_tr_b16 v[222:223], v228 offset:22528
	v_exp_f32_e32 v217, v217
	v_cvt_pk_bf16_f32 v208, v212, v213
	v_cvt_pk_bf16_f32 v209, v214, v215
	s_waitcnt lgkmcnt(11)
	v_mfma_f32_32x32x16_bf16 v[84:99], v[232:235], v[128:131], v[84:99]
	ds_read_b64_tr_b16 v[224:225], v229 offset:20480
	ds_read_b64_tr_b16 v[226:227], v229 offset:22528
	v_exp_f32_e32 v218, v218
	v_exp_f32_e32 v219, v219
	v_add_f32_e32 v252, v252, v216
	s_waitcnt lgkmcnt(12)
	v_mfma_f32_32x32x16_bf16 v[100:115], v[236:239], v[128:131], v[100:115]
	ds_read_b64_tr_b16 v[232:233], v230 offset:20480
	ds_read_b64_tr_b16 v[234:235], v230 offset:22528
	v_add_f32_e32 v253, v253, v217
	v_add_f32_e32 v252, v252, v218
	v_add_f32_e32 v253, v253, v219
	v_cvt_pk_bf16_f32 v210, v216, v217
	v_cvt_pk_bf16_f32 v211, v218, v219
	v_max_f32_e32 v251, v252, v253
	v_cmp_nge_f32_e32 vcc, 0x45800000, v251
	s_cbranch_vccnz .LatB_recs_x3

; #define LAS __attribute__((address_space(3)))
; __device__ __forceinline__ float max2f(float a, float b) { float r; asm("v_max_f32_e32 %0, %1, %2" : "=v"(r) : "v"(a), "v"(b)); return r; }
; __device__ __forceinline__ void attn_unit(LAS unsigned char* lds, const bf16_t* Z, bf16_t* A2, const float* tabg, int seq_base, int S, int h, int qb, float lam) {
;     ...
;         if (first || __any(mx > THR)) {
;             { auto rr = __builtin_amdgcn_permlane32_swap(__float_as_uint(mx), __float_as_uint(mx), false, false); mx = max2f(__uint_as_float(rr[0]), __uint_as_float(rr[1])); }
;             const float delta = first ? mx : fmaxf(mx, 0.f);
;             const float alpha = first ? 1.0f : __builtin_amdgcn_exp2f(-delta);
;             mu += delta; ls2 *= alpha;
;             if (!first) {
;                 asm volatile("" ::: "memory");
;                 scr[r32] = alpha;
;                 asm volatile("s_waitcnt lgkmcnt(0)" ::: "memory");
; #pragma unroll
;                 for (int g = 0; g < 4; ++g) { const f32x4 a4 = *(const LAS f32x4*)(scr + 8 * g + 4 * hi);
; #pragma unroll
;                     for (int d = 0; d < 4; ++d) { O[d][4 * g + 0] *= a4[0]; O[d][4 * g + 1] *= a4[1]; O[d][4 * g + 2] *= a4[2]; O[d][4 * g + 3] *= a4[3]; } }
;                 asm volatile("s_waitcnt lgkmcnt(0)" ::: "memory");
;             }
; #pragma unroll
;             for (int r = 0; r < 16; ++r) { p0[r] -= delta; p1[r] -= delta; }
.LatB_recnn_0:
	v_max3_f32 v251, v84, v85, v86
	v_max3_f32 v252, v87, v88, v89
	v_max3_f32 v251, v251, v90, v91
	v_max3_f32 v252, v252, v92, v93
	v_max3_f32 v251, v251, v94, v95
	v_max3_f32 v252, v252, v96, v97
	v_max3_f32 v251, v251, v98, v99
	v_max3_f32 v252, v252, v100, v101
	v_max3_f32 v251, v251, v102, v103
	v_max3_f32 v252, v252, v104, v105
	v_max3_f32 v251, v251, v106, v107
	v_max3_f32 v252, v252, v108, v109
	v_max3_f32 v251, v251, v110, v111
	v_max3_f32 v252, v252, v112, v113
	v_max3_f32 v251, v251, v114, v115
	v_max_f32_e32 v251, v251, v252
	v_mov_b32_e32 v252, v251
	s_nop 1
	v_permlane32_swap_b32_e32 v251, v252
	v_max_f32_e32 v251, v251, v252
	v_max_f32_e32 v253, 0, v251
	v_exp_f32_e64 v254, -v253
	v_add_f32_e32 v186, v186, v253
	s_nop 0
	v_mul_f32_e32 v150, v150, v254
	v_mul_f32_e32 v151, v151, v254
	ds_write_b32 v184, v254
	s_waitcnt lgkmcnt(0)
	ds_read_b128 v[132:135], v185
	ds_read_b128 v[136:139], v185 offset:32
	ds_read_b128 v[140:143], v185 offset:64
	ds_read_b128 v[144:147], v185 offset:96
	s_waitcnt lgkmcnt(0)
	v_pk_mul_f32 v[20:21], v[20:21], v[132:133]
	v_pk_mul_f32 v[22:23], v[22:23], v[134:135]
	v_pk_mul_f32 v[24:25], v[24:25], v[136:137]
	v_pk_mul_f32 v[26:27], v[26:27], v[138:139]
	v_pk_mul_f32 v[28:29], v[28:29], v[140:141]
	v_pk_mul_f32 v[30:31], v[30:31], v[142:143]
	v_pk_mul_f32 v[32:33], v[32:33], v[144:145]
	v_pk_mul_f32 v[34:35], v[34:35], v[146:147]
	v_pk_mul_f32 v[36:37], v[36:37], v[132:133]
	v_pk_mul_f32 v[38:39], v[38:39], v[134:135]
	v_pk_mul_f32 v[40:41], v[40:41], v[136:137]
	v_pk_mul_f32 v[42:43], v[42:43], v[138:139]
	v_pk_mul_f32 v[44:45], v[44:45], v[140:141]
	v_pk_mul_f32 v[46:47], v[46:47], v[142:143]
	v_pk_mul_f32 v[48:49], v[48:49], v[144:145]
	v_pk_mul_f32 v[50:51], v[50:51], v[146:147]
	v_pk_mul_f32 v[52:53], v[52:53], v[132:133]
	v_pk_mul_f32 v[54:55], v[54:55], v[134:135]
	v_pk_mul_f32 v[56:57], v[56:57], v[136:137]
	v_pk_mul_f32 v[58:59], v[58:59], v[138:139]
	v_pk_mul_f32 v[60:61], v[60:61], v[140:141]
	v_pk_mul_f32 v[62:63], v[62:63], v[142:143]
	v_pk_mul_f32 v[64:65], v[64:65], v[144:145]
	v_pk_mul_f32 v[66:67], v[66:67], v[146:147]
	v_pk_mul_f32 v[68:69], v[68:69], v[132:133]
	v_pk_mul_f32 v[70:71], v[70:71], v[134:135]
	v_pk_mul_f32 v[72:73], v[72:73], v[136:137]
	v_pk_mul_f32 v[74:75], v[74:75], v[138:139]
	v_pk_mul_f32 v[76:77], v[76:77], v[140:141]
	v_pk_mul_f32 v[78:79], v[78:79], v[142:143]
	v_pk_mul_f32 v[80:81], v[80:81], v[144:145]
	v_pk_mul_f32 v[82:83], v[82:83], v[146:147]
	v_mov_b32_e32 v252, v253
	v_pk_add_f32 v[84:85], v[84:85], v[252:253] neg_lo:[0,1] neg_hi:[0,1]
	v_pk_add_f32 v[86:87], v[86:87], v[252:253] neg_lo:[0,1] neg_hi:[0,1]
	v_pk_add_f32 v[88:89], v[88:89], v[252:253] neg_lo:[0,1] neg_hi:[0,1]
	v_pk_add_f32 v[90:91], v[90:91], v[252:253] neg_lo:[0,1] neg_hi:[0,1]
	v_pk_add_f32 v[92:93], v[92:93], v[252:253] neg_lo:[0,1] neg_hi:[0,1]
	v_pk_add_f32 v[94:95], v[94:95], v[252:253] neg_lo:[0,1] neg_hi:[0,1]
	v_pk_add_f32 v[96:97], v[96:97], v[252:253] neg_lo:[0,1] neg_hi:[0,1]
	v_pk_add_f32 v[98:99], v[98:99], v[252:253] neg_lo:[0,1] neg_hi:[0,1]
	v_pk_add_f32 v[100:101], v[100:101], v[252:253] neg_lo:[0,1] neg_hi:[0,1]
	v_pk_add_f32 v[102:103], v[102:103], v[252:253] neg_lo:[0,1] neg_hi:[0,1]
	v_pk_add_f32 v[104:105], v[104:105], v[252:253] neg_lo:[0,1] neg_hi:[0,1]
	v_pk_add_f32 v[106:107], v[106:107], v[252:253] neg_lo:[0,1] neg_hi:[0,1]
	v_pk_add_f32 v[108:109], v[108:109], v[252:253] neg_lo:[0,1] neg_hi:[0,1]
	v_pk_add_f32 v[110:111], v[110:111], v[252:253] neg_lo:[0,1] neg_hi:[0,1]
	v_pk_add_f32 v[112:113], v[112:113], v[252:253] neg_lo:[0,1] neg_hi:[0,1]
	v_pk_add_f32 v[114:115], v[114:115], v[252:253] neg_lo:[0,1] neg_hi:[0,1]
	v_pk_add_f32 v[188:189], v[188:189], v[252:253] neg_lo:[0,1] neg_hi:[0,1]
	v_pk_add_f32 v[190:191], v[190:191], v[252:253] neg_lo:[0,1] neg_hi:[0,1]
	v_pk_add_f32 v[192:193], v[192:193], v[252:253] neg_lo:[0,1] neg_hi:[0,1]
	v_pk_add_f32 v[194:195], v[194:195], v[252:253] neg_lo:[0,1] neg_hi:[0,1]
	v_pk_add_f32 v[196:197], v[196:197], v[252:253] neg_lo:[0,1] neg_hi:[0,1]
	v_pk_add_f32 v[198:199], v[198:199], v[252:253] neg_lo:[0,1] neg_hi:[0,1]
	v_pk_add_f32 v[200:201], v[200:201], v[252:253] neg_lo:[0,1] neg_hi:[0,1]
	v_pk_add_f32 v[202:203], v[202:203], v[252:253] neg_lo:[0,1] neg_hi:[0,1]
; __device__ __forceinline__ void attn_unit(LAS unsigned char* lds, const bf16_t* Z, bf16_t* A2, const float* tabg, int seq_base, int S, int h, int qb, float lam) {
;     ...
;         if (kv0 - (qlo + 31) >= 128) { near = false; cc = tabR; } else if (qlo - (kv0 + 63) >= 128) { near = false; cc = tabL; }
;         { const float coff = cc - mu;
;           if (__any(!(coff == coff_cur))) { coff_cur = coff;
; #pragma unroll
;               for (int r = 0; r < 16; ++r) cblk[r] = coff;
;               asm volatile("" : "+v"(cblk)); } }
;     ...
;             for (int r = 0; r < 16; ++r) { p0[r] -= delta; p1[r] -= delta; }
;             asm volatile("" : "+v"(p0), "+v"(p1));
;         }
; #pragma unroll
;         for (int r = 0; r < 16; ++r) { p0[r] = __builtin_amdgcn_exp2f(p0[r]); p1[r] = __builtin_amdgcn_exp2f(p1[r]); }
; #pragma unroll
;         for (int r = 0; r < 16; r += 2) { ls2 += (f32x2){p0[r], p0[r + 1]}; ls2 += (f32x2){p1[r], p1[r + 1]}; }
;         bf16x8 pa[4]; pa[0] = pack8(p0, 0); pa[1] = pack8(p0, 8); pa[2] = pack8(p1, 0); pa[3] = pack8(p1, 8);
	v_pk_add_f32 v[204:205], v[204:205], v[252:253] neg_lo:[0,1] neg_hi:[0,1]
	v_pk_add_f32 v[206:207], v[206:207], v[252:253] neg_lo:[0,1] neg_hi:[0,1]
	v_pk_add_f32 v[208:209], v[208:209], v[252:253] neg_lo:[0,1] neg_hi:[0,1]
	v_pk_add_f32 v[210:211], v[210:211], v[252:253] neg_lo:[0,1] neg_hi:[0,1]
	v_pk_add_f32 v[212:213], v[212:213], v[252:253] neg_lo:[0,1] neg_hi:[0,1]
	v_pk_add_f32 v[214:215], v[214:215], v[252:253] neg_lo:[0,1] neg_hi:[0,1]
	v_pk_add_f32 v[216:217], v[216:217], v[252:253] neg_lo:[0,1] neg_hi:[0,1]
	v_pk_add_f32 v[218:219], v[218:219], v[252:253] neg_lo:[0,1] neg_hi:[0,1]
	v_exp_f32_e32 v84, v84
	v_exp_f32_e32 v85, v85
	v_exp_f32_e32 v86, v86
	v_exp_f32_e32 v87, v87
	v_exp_f32_e32 v88, v88
	v_add_f32_e32 v252, v84, v86
	v_add_f32_e32 v253, v85, v87
	v_exp_f32_e32 v89, v89
	v_cvt_pk_bf16_f32 v84, v84, v85
	v_cvt_pk_bf16_f32 v85, v86, v87
	v_exp_f32_e32 v90, v90
	v_exp_f32_e32 v91, v91
	v_add_f32_e32 v252, v252, v88
	v_add_f32_e32 v253, v253, v89
	v_add_f32_e32 v252, v252, v90
	v_add_f32_e32 v253, v253, v91
	v_cvt_pk_bf16_f32 v86, v88, v89
	v_cvt_pk_bf16_f32 v87, v90, v91
	v_exp_f32_e32 v92, v92
	v_exp_f32_e32 v93, v93
	v_exp_f32_e32 v94, v94
	v_exp_f32_e32 v95, v95
	v_add_f32_e32 v252, v252, v92
	v_add_f32_e32 v253, v253, v93
	v_add_f32_e32 v252, v252, v94
	v_add_f32_e32 v253, v253, v95
	v_exp_f32_e32 v96, v96
	v_exp_f32_e32 v97, v97
	v_cvt_pk_bf16_f32 v88, v92, v93
	v_cvt_pk_bf16_f32 v89, v94, v95
	v_exp_f32_e32 v98, v98
	v_exp_f32_e32 v99, v99
	v_add_f32_e32 v252, v252, v96
	v_add_f32_e32 v253, v253, v97
	v_add_f32_e32 v252, v252, v98
	v_add_f32_e32 v253, v253, v99
	v_cvt_pk_bf16_f32 v90, v96, v97
	v_cvt_pk_bf16_f32 v91, v98, v99
	v_exp_f32_e32 v100, v100
	v_exp_f32_e32 v101, v101
	v_exp_f32_e32 v102, v102
	v_exp_f32_e32 v103, v103
	v_add_f32_e32 v252, v252, v100
	v_add_f32_e32 v253, v253, v101
	v_add_f32_e32 v252, v252, v102
	v_add_f32_e32 v253, v253, v103
	v_exp_f32_e32 v104, v104
	v_exp_f32_e32 v105, v105
	v_cvt_pk_bf16_f32 v100, v100, v101
	v_cvt_pk_bf16_f32 v101, v102, v103
	v_exp_f32_e32 v106, v106
	v_exp_f32_e32 v107, v107
	v_add_f32_e32 v252, v252, v104
	v_add_f32_e32 v253, v253, v105
	v_add_f32_e32 v252, v252, v106
	v_add_f32_e32 v253, v253, v107
	v_cvt_pk_bf16_f32 v102, v104, v105
	v_cvt_pk_bf16_f32 v103, v106, v107
	v_exp_f32_e32 v108, v108
	v_exp_f32_e32 v109, v109
	v_exp_f32_e32 v110, v110
	v_exp_f32_e32 v111, v111
	v_add_f32_e32 v252, v252, v108
	v_add_f32_e32 v253, v253, v109
	v_add_f32_e32 v252, v252, v110
	v_add_f32_e32 v253, v253, v111
	v_exp_f32_e32 v112, v112
	v_exp_f32_e32 v113, v113
	v_cvt_pk_bf16_f32 v104, v108, v109
	v_cvt_pk_bf16_f32 v105, v110, v111
	v_exp_f32_e32 v114, v114
	v_exp_f32_e32 v115, v115
	v_add_f32_e32 v252, v252, v112
	v_add_f32_e32 v253, v253, v113
	v_add_f32_e32 v252, v252, v114
	v_add_f32_e32 v253, v253, v115
	v_cvt_pk_bf16_f32 v106, v112, v113
	v_cvt_pk_bf16_f32 v107, v114, v115
	s_mov_b32 s24, s23
	s_mov_b32 s35, s24
	v_mov_b32_e32 v251, 0
	s_cmp_eq_u32 s24, 1
	s_cselect_b64 vcc, -1, 0
	v_cndmask_b32_e32 v251, v251, v177, vcc
	s_cmp_eq_u32 s24, 2
	s_cselect_b64 vcc, -1, 0
	v_cndmask_b32_e32 v251, v251, v178, vcc
	v_sub_f32_e32 v2, v251, v186
	v_mov_b32_e32 v3, v2
	v_mov_b64_e32 v[4:5], v[2:3]
	v_mov_b64_e32 v[6:7], v[2:3]
	v_mov_b64_e32 v[8:9], v[2:3]
	v_mov_b64_e32 v[10:11], v[2:3]
	v_mov_b64_e32 v[12:13], v[2:3]
	v_mov_b64_e32 v[14:15], v[2:3]
	v_mov_b64_e32 v[16:17], v[2:3]
	ds_read_b64_tr_b16 v[132:133], v228 offset:0
	ds_read_b64_tr_b16 v[134:135], v228 offset:2048
	ds_read_b64_tr_b16 v[136:137], v229 offset:0
	ds_read_b64_tr_b16 v[138:139], v229 offset:2048
	ds_read_b64_tr_b16 v[140:141], v230 offset:0
	ds_read_b64_tr_b16 v[142:143], v230 offset:2048
	ds_read_b64_tr_b16 v[144:145], v231 offset:0
	ds_read_b64_tr_b16 v[146:147], v231 offset:2048
	ds_read_b64_tr_b16 v[220:221], v228 offset:4096
	ds_read_b64_tr_b16 v[222:223], v228 offset:6144
	ds_read_b64_tr_b16 v[224:225], v229 offset:4096
	ds_read_b64_tr_b16 v[226:227], v229 offset:6144
	ds_read_b64_tr_b16 v[232:233], v230 offset:4096
	ds_read_b64_tr_b16 v[234:235], v230 offset:6144
	s_nop 1
	s_cmp_eq_u32 s22, 0
	s_cbranch_scc1 .LatB_recret_h0
	s_cmp_eq_u32 s22, 1
	s_cbranch_scc1 .LatB_recret_m0
	s_branch .LatB_recret_x4

; #define LAS __attribute__((address_space(3)))
; __device__ __forceinline__ float max2f(float a, float b) { float r; asm("v_max_f32_e32 %0, %1, %2" : "=v"(r) : "v"(a), "v"(b)); return r; }
; __device__ __forceinline__ void attn_unit(LAS unsigned char* lds, const bf16_t* Z, bf16_t* A2, const float* tabg, int seq_base, int S, int h, int qb, float lam) {
;     ...
;         if (first || __any(mx > THR)) {
;             { auto rr = __builtin_amdgcn_permlane32_swap(__float_as_uint(mx), __float_as_uint(mx), false, false); mx = max2f(__uint_as_float(rr[0]), __uint_as_float(rr[1])); }
;             const float delta = first ? mx : fmaxf(mx, 0.f);
;             const float alpha = first ? 1.0f : __builtin_amdgcn_exp2f(-delta);
;             mu += delta; ls2 *= alpha;
;             if (!first) {
;                 asm volatile("" ::: "memory");
;                 scr[r32] = alpha;
;                 asm volatile("s_waitcnt lgkmcnt(0)" ::: "memory");
; #pragma unroll
;                 for (int g = 0; g < 4; ++g) { const f32x4 a4 = *(const LAS f32x4*)(scr + 8 * g + 4 * hi);
; #pragma unroll
;                     for (int d = 0; d < 4; ++d) { O[d][4 * g + 0] *= a4[0]; O[d][4 * g + 1] *= a4[1]; O[d][4 * g + 2] *= a4[2]; O[d][4 * g + 3] *= a4[3]; } }
;                 asm volatile("s_waitcnt lgkmcnt(0)" ::: "memory");
;             }
; #pragma unroll
;             for (int r = 0; r < 16; ++r) { p0[r] -= delta; p1[r] -= delta; }
.LatB_recnn_1:
	v_max3_f32 v251, v188, v189, v190
	v_max3_f32 v252, v191, v192, v193
	v_max3_f32 v251, v251, v194, v195
	v_max3_f32 v252, v252, v196, v197
	v_max3_f32 v251, v251, v198, v199
	v_max3_f32 v252, v252, v200, v201
	v_max3_f32 v251, v251, v202, v203
	v_max3_f32 v252, v252, v204, v205
	v_max3_f32 v251, v251, v206, v207
	v_max3_f32 v252, v252, v208, v209
	v_max3_f32 v251, v251, v210, v211
	v_max3_f32 v252, v252, v212, v213
	v_max3_f32 v251, v251, v214, v215
	v_max3_f32 v252, v252, v216, v217
	v_max3_f32 v251, v251, v218, v219
	v_max_f32_e32 v251, v251, v252
	v_mov_b32_e32 v252, v251
	s_nop 1
	v_permlane32_swap_b32_e32 v251, v252
	v_max_f32_e32 v251, v251, v252
	v_max_f32_e32 v253, 0, v251
	v_exp_f32_e64 v254, -v253
	v_add_f32_e32 v186, v186, v253
	s_nop 0
	v_mul_f32_e32 v150, v150, v254
	v_mul_f32_e32 v151, v151, v254
	ds_write_b32 v184, v254
	s_waitcnt lgkmcnt(0)
	ds_read_b128 v[132:135], v185
	ds_read_b128 v[136:139], v185 offset:32
	ds_read_b128 v[140:143], v185 offset:64
	ds_read_b128 v[144:147], v185 offset:96
	s_waitcnt lgkmcnt(0)
	v_pk_mul_f32 v[20:21], v[20:21], v[132:133]
	v_pk_mul_f32 v[22:23], v[22:23], v[134:135]
	v_pk_mul_f32 v[24:25], v[24:25], v[136:137]
	v_pk_mul_f32 v[26:27], v[26:27], v[138:139]
	v_pk_mul_f32 v[28:29], v[28:29], v[140:141]
	v_pk_mul_f32 v[30:31], v[30:31], v[142:143]
	v_pk_mul_f32 v[32:33], v[32:33], v[144:145]
	v_pk_mul_f32 v[34:35], v[34:35], v[146:147]
	v_pk_mul_f32 v[36:37], v[36:37], v[132:133]
	v_pk_mul_f32 v[38:39], v[38:39], v[134:135]
	v_pk_mul_f32 v[40:41], v[40:41], v[136:137]
	v_pk_mul_f32 v[42:43], v[42:43], v[138:139]
	v_pk_mul_f32 v[44:45], v[44:45], v[140:141]
	v_pk_mul_f32 v[46:47], v[46:47], v[142:143]
	v_pk_mul_f32 v[48:49], v[48:49], v[144:145]
	v_pk_mul_f32 v[50:51], v[50:51], v[146:147]
	v_pk_mul_f32 v[52:53], v[52:53], v[132:133]
	v_pk_mul_f32 v[54:55], v[54:55], v[134:135]
	v_pk_mul_f32 v[56:57], v[56:57], v[136:137]
	v_pk_mul_f32 v[58:59], v[58:59], v[138:139]
	v_pk_mul_f32 v[60:61], v[60:61], v[140:141]
	v_pk_mul_f32 v[62:63], v[62:63], v[142:143]
	v_pk_mul_f32 v[64:65], v[64:65], v[144:145]
	v_pk_mul_f32 v[66:67], v[66:67], v[146:147]
	v_pk_mul_f32 v[68:69], v[68:69], v[132:133]
	v_pk_mul_f32 v[70:71], v[70:71], v[134:135]
	v_pk_mul_f32 v[72:73], v[72:73], v[136:137]
	v_pk_mul_f32 v[74:75], v[74:75], v[138:139]
	v_pk_mul_f32 v[76:77], v[76:77], v[140:141]
	v_pk_mul_f32 v[78:79], v[78:79], v[142:143]
	v_pk_mul_f32 v[80:81], v[80:81], v[144:145]
	v_pk_mul_f32 v[82:83], v[82:83], v[146:147]
	v_mov_b32_e32 v252, v253
	v_pk_add_f32 v[188:189], v[188:189], v[252:253] neg_lo:[0,1] neg_hi:[0,1]
	v_pk_add_f32 v[190:191], v[190:191], v[252:253] neg_lo:[0,1] neg_hi:[0,1]
	v_pk_add_f32 v[192:193], v[192:193], v[252:253] neg_lo:[0,1] neg_hi:[0,1]
	v_pk_add_f32 v[194:195], v[194:195], v[252:253] neg_lo:[0,1] neg_hi:[0,1]
	v_pk_add_f32 v[196:197], v[196:197], v[252:253] neg_lo:[0,1] neg_hi:[0,1]
	v_pk_add_f32 v[198:199], v[198:199], v[252:253] neg_lo:[0,1] neg_hi:[0,1]
	v_pk_add_f32 v[200:201], v[200:201], v[252:253] neg_lo:[0,1] neg_hi:[0,1]
	v_pk_add_f32 v[202:203], v[202:203], v[252:253] neg_lo:[0,1] neg_hi:[0,1]
	v_pk_add_f32 v[204:205], v[204:205], v[252:253] neg_lo:[0,1] neg_hi:[0,1]
	v_pk_add_f32 v[206:207], v[206:207], v[252:253] neg_lo:[0,1] neg_hi:[0,1]
	v_pk_add_f32 v[208:209], v[208:209], v[252:253] neg_lo:[0,1] neg_hi:[0,1]
	v_pk_add_f32 v[210:211], v[210:211], v[252:253] neg_lo:[0,1] neg_hi:[0,1]
	v_pk_add_f32 v[212:213], v[212:213], v[252:253] neg_lo:[0,1] neg_hi:[0,1]
	v_pk_add_f32 v[214:215], v[214:215], v[252:253] neg_lo:[0,1] neg_hi:[0,1]
	v_pk_add_f32 v[216:217], v[216:217], v[252:253] neg_lo:[0,1] neg_hi:[0,1]
	v_pk_add_f32 v[218:219], v[218:219], v[252:253] neg_lo:[0,1] neg_hi:[0,1]
	v_pk_add_f32 v[84:85], v[84:85], v[252:253] neg_lo:[0,1] neg_hi:[0,1]
	v_pk_add_f32 v[86:87], v[86:87], v[252:253] neg_lo:[0,1] neg_hi:[0,1]
	v_pk_add_f32 v[88:89], v[88:89], v[252:253] neg_lo:[0,1] neg_hi:[0,1]
	v_pk_add_f32 v[90:91], v[90:91], v[252:253] neg_lo:[0,1] neg_hi:[0,1]
	v_pk_add_f32 v[92:93], v[92:93], v[252:253] neg_lo:[0,1] neg_hi:[0,1]
	v_pk_add_f32 v[94:95], v[94:95], v[252:253] neg_lo:[0,1] neg_hi:[0,1]
	v_pk_add_f32 v[96:97], v[96:97], v[252:253] neg_lo:[0,1] neg_hi:[0,1]
	v_pk_add_f32 v[98:99], v[98:99], v[252:253] neg_lo:[0,1] neg_hi:[0,1]
; __device__ __forceinline__ void attn_unit(LAS unsigned char* lds, const bf16_t* Z, bf16_t* A2, const float* tabg, int seq_base, int S, int h, int qb, float lam) {
;     ...
;         if (kv0 - (qlo + 31) >= 128) { near = false; cc = tabR; } else if (qlo - (kv0 + 63) >= 128) { near = false; cc = tabL; }
;         { const float coff = cc - mu;
;           if (__any(!(coff == coff_cur))) { coff_cur = coff;
; #pragma unroll
;               for (int r = 0; r < 16; ++r) cblk[r] = coff;
;               asm volatile("" : "+v"(cblk)); } }
;     ...
;             for (int r = 0; r < 16; ++r) { p0[r] -= delta; p1[r] -= delta; }
;             asm volatile("" : "+v"(p0), "+v"(p1));
;         }
; #pragma unroll
;         for (int r = 0; r < 16; ++r) { p0[r] = __builtin_amdgcn_exp2f(p0[r]); p1[r] = __builtin_amdgcn_exp2f(p1[r]); }
; #pragma unroll
;         for (int r = 0; r < 16; r += 2) { ls2 += (f32x2){p0[r], p0[r + 1]}; ls2 += (f32x2){p1[r], p1[r + 1]}; }
;         bf16x8 pa[4]; pa[0] = pack8(p0, 0); pa[1] = pack8(p0, 8); pa[2] = pack8(p1, 0); pa[3] = pack8(p1, 8);
	v_pk_add_f32 v[100:101], v[100:101], v[252:253] neg_lo:[0,1] neg_hi:[0,1]
	v_pk_add_f32 v[102:103], v[102:103], v[252:253] neg_lo:[0,1] neg_hi:[0,1]
	v_pk_add_f32 v[104:105], v[104:105], v[252:253] neg_lo:[0,1] neg_hi:[0,1]
	v_pk_add_f32 v[106:107], v[106:107], v[252:253] neg_lo:[0,1] neg_hi:[0,1]
	v_pk_add_f32 v[108:109], v[108:109], v[252:253] neg_lo:[0,1] neg_hi:[0,1]
	v_pk_add_f32 v[110:111], v[110:111], v[252:253] neg_lo:[0,1] neg_hi:[0,1]
	v_pk_add_f32 v[112:113], v[112:113], v[252:253] neg_lo:[0,1] neg_hi:[0,1]
	v_pk_add_f32 v[114:115], v[114:115], v[252:253] neg_lo:[0,1] neg_hi:[0,1]
	v_exp_f32_e32 v188, v188
	v_exp_f32_e32 v189, v189
	v_exp_f32_e32 v190, v190
	v_exp_f32_e32 v191, v191
	v_exp_f32_e32 v192, v192
	v_add_f32_e32 v252, v188, v190
	v_add_f32_e32 v253, v189, v191
	v_exp_f32_e32 v193, v193
	v_cvt_pk_bf16_f32 v188, v188, v189
	v_cvt_pk_bf16_f32 v189, v190, v191
	v_exp_f32_e32 v194, v194
	v_exp_f32_e32 v195, v195
	v_add_f32_e32 v252, v252, v192
	v_add_f32_e32 v253, v253, v193
	v_add_f32_e32 v252, v252, v194
	v_add_f32_e32 v253, v253, v195
	v_cvt_pk_bf16_f32 v190, v192, v193
	v_cvt_pk_bf16_f32 v191, v194, v195
	v_exp_f32_e32 v196, v196
	v_exp_f32_e32 v197, v197
	v_exp_f32_e32 v198, v198
	v_exp_f32_e32 v199, v199
	v_add_f32_e32 v252, v252, v196
	v_add_f32_e32 v253, v253, v197
	v_add_f32_e32 v252, v252, v198
	v_add_f32_e32 v253, v253, v199
	v_exp_f32_e32 v200, v200
	v_exp_f32_e32 v201, v201
	v_cvt_pk_bf16_f32 v192, v196, v197
	v_cvt_pk_bf16_f32 v193, v198, v199
	v_exp_f32_e32 v202, v202
	v_exp_f32_e32 v203, v203
	v_add_f32_e32 v252, v252, v200
	v_add_f32_e32 v253, v253, v201
	v_add_f32_e32 v252, v252, v202
	v_add_f32_e32 v253, v253, v203
	v_cvt_pk_bf16_f32 v194, v200, v201
	v_cvt_pk_bf16_f32 v195, v202, v203
	v_exp_f32_e32 v204, v204
	v_exp_f32_e32 v205, v205
	v_exp_f32_e32 v206, v206
	v_exp_f32_e32 v207, v207
	v_add_f32_e32 v252, v252, v204
	v_add_f32_e32 v253, v253, v205
	v_add_f32_e32 v252, v252, v206
	v_add_f32_e32 v253, v253, v207
	v_exp_f32_e32 v208, v208
	v_exp_f32_e32 v209, v209
	v_cvt_pk_bf16_f32 v204, v204, v205
	v_cvt_pk_bf16_f32 v205, v206, v207
	v_exp_f32_e32 v210, v210
	v_exp_f32_e32 v211, v211
	v_add_f32_e32 v252, v252, v208
	v_add_f32_e32 v253, v253, v209
	v_add_f32_e32 v252, v252, v210
	v_add_f32_e32 v253, v253, v211
	v_cvt_pk_bf16_f32 v206, v208, v209
	v_cvt_pk_bf16_f32 v207, v210, v211
	v_exp_f32_e32 v212, v212
	v_exp_f32_e32 v213, v213
	v_exp_f32_e32 v214, v214
	v_exp_f32_e32 v215, v215
	v_add_f32_e32 v252, v252, v212
	v_add_f32_e32 v253, v253, v213
	v_add_f32_e32 v252, v252, v214
	v_add_f32_e32 v253, v253, v215
	v_exp_f32_e32 v216, v216
	v_exp_f32_e32 v217, v217
	v_cvt_pk_bf16_f32 v208, v212, v213
	v_cvt_pk_bf16_f32 v209, v214, v215
	v_exp_f32_e32 v218, v218
	v_exp_f32_e32 v219, v219
	v_add_f32_e32 v252, v252, v216
	v_add_f32_e32 v253, v253, v217
	v_add_f32_e32 v252, v252, v218
	v_add_f32_e32 v253, v253, v219
	v_cvt_pk_bf16_f32 v210, v216, v217
	v_cvt_pk_bf16_f32 v211, v218, v219
	s_mov_b32 s24, s23
	s_mov_b32 s35, s24
	v_mov_b32_e32 v251, 0
	s_cmp_eq_u32 s24, 1
	s_cselect_b64 vcc, -1, 0
	v_cndmask_b32_e32 v251, v251, v177, vcc
	s_cmp_eq_u32 s24, 2
	s_cselect_b64 vcc, -1, 0
	v_cndmask_b32_e32 v251, v251, v178, vcc
	v_sub_f32_e32 v2, v251, v186
	v_mov_b32_e32 v3, v2
	v_mov_b64_e32 v[4:5], v[2:3]
	v_mov_b64_e32 v[6:7], v[2:3]
	v_mov_b64_e32 v[8:9], v[2:3]
	v_mov_b64_e32 v[10:11], v[2:3]
	v_mov_b64_e32 v[12:13], v[2:3]
	v_mov_b64_e32 v[14:15], v[2:3]
	v_mov_b64_e32 v[16:17], v[2:3]
	ds_read_b64_tr_b16 v[132:133], v228 offset:16384
	ds_read_b64_tr_b16 v[134:135], v228 offset:18432
	ds_read_b64_tr_b16 v[136:137], v229 offset:16384
	ds_read_b64_tr_b16 v[138:139], v229 offset:18432
	ds_read_b64_tr_b16 v[140:141], v230 offset:16384
	ds_read_b64_tr_b16 v[142:143], v230 offset:18432
	ds_read_b64_tr_b16 v[144:145], v231 offset:16384
	ds_read_b64_tr_b16 v[146:147], v231 offset:18432
	ds_read_b64_tr_b16 v[220:221], v228 offset:20480
	ds_read_b64_tr_b16 v[222:223], v228 offset:22528
	ds_read_b64_tr_b16 v[224:225], v229 offset:20480
	ds_read_b64_tr_b16 v[226:227], v229 offset:22528
	ds_read_b64_tr_b16 v[232:233], v230 offset:20480
	ds_read_b64_tr_b16 v[234:235], v230 offset:22528
	s_nop 1
	s_cmp_eq_u32 s22, 0
	s_cbranch_scc1 .LatB_recret_h1
	s_cmp_eq_u32 s22, 1
	s_cbranch_scc1 .LatB_recret_m1
	s_branch .LatB_recret_x3

; #define LAS __attribute__((address_space(3)))
; __device__ __forceinline__ float max2f(float a, float b) { float r; asm("v_max_f32_e32 %0, %1, %2" : "=v"(r) : "v"(a), "v"(b)); return r; }
; __device__ __forceinline__ void attn_unit(LAS unsigned char* lds, const bf16_t* Z, bf16_t* A2, const float* tabg, int seq_base, int S, int h, int qb, float lam) {
;     ...
;         if (first || __any(mx > THR)) {
;             { auto rr = __builtin_amdgcn_permlane32_swap(__float_as_uint(mx), __float_as_uint(mx), false, false); mx = max2f(__uint_as_float(rr[0]), __uint_as_float(rr[1])); }
;             const float delta = first ? mx : fmaxf(mx, 0.f);
;             const float alpha = first ? 1.0f : __builtin_amdgcn_exp2f(-delta);
;             mu += delta; ls2 *= alpha;
;             if (!first) {
;                 asm volatile("" ::: "memory");
;                 scr[r32] = alpha;
;                 asm volatile("s_waitcnt lgkmcnt(0)" ::: "memory");
; #pragma unroll
;                 for (int g = 0; g < 4; ++g) { const f32x4 a4 = *(const LAS f32x4*)(scr + 8 * g + 4 * hi);
; #pragma unroll
;                     for (int d = 0; d < 4; ++d) { O[d][4 * g + 0] *= a4[0]; O[d][4 * g + 1] *= a4[1]; O[d][4 * g + 2] *= a4[2]; O[d][4 * g + 3] *= a4[3]; } }
;                 asm volatile("s_waitcnt lgkmcnt(0)" ::: "memory");
;             }
; #pragma unroll
;             for (int r = 0; r < 16; ++r) { p0[r] -= delta; p1[r] -= delta; }
.LatB_recnn_2:
	v_max3_f32 v251, v84, v85, v86
	v_max3_f32 v252, v87, v88, v89
	v_max3_f32 v251, v251, v90, v91
	v_max3_f32 v252, v252, v92, v93
	v_max3_f32 v251, v251, v94, v95
	v_max3_f32 v252, v252, v96, v97
	v_max3_f32 v251, v251, v98, v99
	v_max3_f32 v252, v252, v100, v101
	v_max3_f32 v251, v251, v102, v103
	v_max3_f32 v252, v252, v104, v105
	v_max3_f32 v251, v251, v106, v107
	v_max3_f32 v252, v252, v108, v109
	v_max3_f32 v251, v251, v110, v111
	v_max3_f32 v252, v252, v112, v113
	v_max3_f32 v251, v251, v114, v115
	v_max_f32_e32 v251, v251, v252
	v_mov_b32_e32 v252, v251
	s_nop 1
	v_permlane32_swap_b32_e32 v251, v252
	v_max_f32_e32 v251, v251, v252
	v_max_f32_e32 v253, 0, v251
	v_exp_f32_e64 v254, -v253
	v_add_f32_e32 v186, v186, v253
	s_nop 0
	v_mul_f32_e32 v150, v150, v254
	v_mul_f32_e32 v151, v151, v254
	ds_write_b32 v184, v254
	s_waitcnt lgkmcnt(0)
	ds_read_b128 v[132:135], v185
	ds_read_b128 v[136:139], v185 offset:32
	ds_read_b128 v[140:143], v185 offset:64
	ds_read_b128 v[144:147], v185 offset:96
	s_waitcnt lgkmcnt(0)
	v_pk_mul_f32 v[20:21], v[20:21], v[132:133]
	v_pk_mul_f32 v[22:23], v[22:23], v[134:135]
	v_pk_mul_f32 v[24:25], v[24:25], v[136:137]
	v_pk_mul_f32 v[26:27], v[26:27], v[138:139]
	v_pk_mul_f32 v[28:29], v[28:29], v[140:141]
	v_pk_mul_f32 v[30:31], v[30:31], v[142:143]
	v_pk_mul_f32 v[32:33], v[32:33], v[144:145]
	v_pk_mul_f32 v[34:35], v[34:35], v[146:147]
	v_pk_mul_f32 v[36:37], v[36:37], v[132:133]
	v_pk_mul_f32 v[38:39], v[38:39], v[134:135]
	v_pk_mul_f32 v[40:41], v[40:41], v[136:137]
	v_pk_mul_f32 v[42:43], v[42:43], v[138:139]
	v_pk_mul_f32 v[44:45], v[44:45], v[140:141]
	v_pk_mul_f32 v[46:47], v[46:47], v[142:143]
	v_pk_mul_f32 v[48:49], v[48:49], v[144:145]
	v_pk_mul_f32 v[50:51], v[50:51], v[146:147]
	v_pk_mul_f32 v[52:53], v[52:53], v[132:133]
	v_pk_mul_f32 v[54:55], v[54:55], v[134:135]
	v_pk_mul_f32 v[56:57], v[56:57], v[136:137]
	v_pk_mul_f32 v[58:59], v[58:59], v[138:139]
	v_pk_mul_f32 v[60:61], v[60:61], v[140:141]
	v_pk_mul_f32 v[62:63], v[62:63], v[142:143]
	v_pk_mul_f32 v[64:65], v[64:65], v[144:145]
	v_pk_mul_f32 v[66:67], v[66:67], v[146:147]
	v_pk_mul_f32 v[68:69], v[68:69], v[132:133]
	v_pk_mul_f32 v[70:71], v[70:71], v[134:135]
	v_pk_mul_f32 v[72:73], v[72:73], v[136:137]
	v_pk_mul_f32 v[74:75], v[74:75], v[138:139]
	v_pk_mul_f32 v[76:77], v[76:77], v[140:141]
	v_pk_mul_f32 v[78:79], v[78:79], v[142:143]
	v_pk_mul_f32 v[80:81], v[80:81], v[144:145]
	v_pk_mul_f32 v[82:83], v[82:83], v[146:147]
	v_mov_b32_e32 v252, v253
	v_pk_add_f32 v[84:85], v[84:85], v[252:253] neg_lo:[0,1] neg_hi:[0,1]
	v_pk_add_f32 v[86:87], v[86:87], v[252:253] neg_lo:[0,1] neg_hi:[0,1]
	v_pk_add_f32 v[88:89], v[88:89], v[252:253] neg_lo:[0,1] neg_hi:[0,1]
	v_pk_add_f32 v[90:91], v[90:91], v[252:253] neg_lo:[0,1] neg_hi:[0,1]
	v_pk_add_f32 v[92:93], v[92:93], v[252:253] neg_lo:[0,1] neg_hi:[0,1]
	v_pk_add_f32 v[94:95], v[94:95], v[252:253] neg_lo:[0,1] neg_hi:[0,1]
	v_pk_add_f32 v[96:97], v[96:97], v[252:253] neg_lo:[0,1] neg_hi:[0,1]
	v_pk_add_f32 v[98:99], v[98:99], v[252:253] neg_lo:[0,1] neg_hi:[0,1]
	v_pk_add_f32 v[100:101], v[100:101], v[252:253] neg_lo:[0,1] neg_hi:[0,1]
	v_pk_add_f32 v[102:103], v[102:103], v[252:253] neg_lo:[0,1] neg_hi:[0,1]
	v_pk_add_f32 v[104:105], v[104:105], v[252:253] neg_lo:[0,1] neg_hi:[0,1]
	v_pk_add_f32 v[106:107], v[106:107], v[252:253] neg_lo:[0,1] neg_hi:[0,1]
	v_pk_add_f32 v[108:109], v[108:109], v[252:253] neg_lo:[0,1] neg_hi:[0,1]
	v_pk_add_f32 v[110:111], v[110:111], v[252:253] neg_lo:[0,1] neg_hi:[0,1]
	v_pk_add_f32 v[112:113], v[112:113], v[252:253] neg_lo:[0,1] neg_hi:[0,1]
	v_pk_add_f32 v[114:115], v[114:115], v[252:253] neg_lo:[0,1] neg_hi:[0,1]
	v_pk_add_f32 v[188:189], v[188:189], v[252:253] neg_lo:[0,1] neg_hi:[0,1]
	v_pk_add_f32 v[190:191], v[190:191], v[252:253] neg_lo:[0,1] neg_hi:[0,1]
	v_pk_add_f32 v[192:193], v[192:193], v[252:253] neg_lo:[0,1] neg_hi:[0,1]
	v_pk_add_f32 v[194:195], v[194:195], v[252:253] neg_lo:[0,1] neg_hi:[0,1]
	v_pk_add_f32 v[196:197], v[196:197], v[252:253] neg_lo:[0,1] neg_hi:[0,1]
	v_pk_add_f32 v[198:199], v[198:199], v[252:253] neg_lo:[0,1] neg_hi:[0,1]
	v_pk_add_f32 v[200:201], v[200:201], v[252:253] neg_lo:[0,1] neg_hi:[0,1]
	v_pk_add_f32 v[202:203], v[202:203], v[252:253] neg_lo:[0,1] neg_hi:[0,1]
; __device__ __forceinline__ void attn_unit(LAS unsigned char* lds, const bf16_t* Z, bf16_t* A2, const float* tabg, int seq_base, int S, int h, int qb, float lam) {
;     ...
;         if (kv0 - (qlo + 31) >= 128) { near = false; cc = tabR; } else if (qlo - (kv0 + 63) >= 128) { near = false; cc = tabL; }
;         { const float coff = cc - mu;
;           if (__any(!(coff == coff_cur))) { coff_cur = coff;
; #pragma unroll
;               for (int r = 0; r < 16; ++r) cblk[r] = coff;
;               asm volatile("" : "+v"(cblk)); } }
;     ...
;             for (int r = 0; r < 16; ++r) { p0[r] -= delta; p1[r] -= delta; }
;             asm volatile("" : "+v"(p0), "+v"(p1));
;         }
; #pragma unroll
;         for (int r = 0; r < 16; ++r) { p0[r] = __builtin_amdgcn_exp2f(p0[r]); p1[r] = __builtin_amdgcn_exp2f(p1[r]); }
; #pragma unroll
;         for (int r = 0; r < 16; r += 2) { ls2 += (f32x2){p0[r], p0[r + 1]}; ls2 += (f32x2){p1[r], p1[r + 1]}; }
;         bf16x8 pa[4]; pa[0] = pack8(p0, 0); pa[1] = pack8(p0, 8); pa[2] = pack8(p1, 0); pa[3] = pack8(p1, 8);
	v_pk_add_f32 v[204:205], v[204:205], v[252:253] neg_lo:[0,1] neg_hi:[0,1]
	v_pk_add_f32 v[206:207], v[206:207], v[252:253] neg_lo:[0,1] neg_hi:[0,1]
	v_pk_add_f32 v[208:209], v[208:209], v[252:253] neg_lo:[0,1] neg_hi:[0,1]
	v_pk_add_f32 v[210:211], v[210:211], v[252:253] neg_lo:[0,1] neg_hi:[0,1]
	v_pk_add_f32 v[212:213], v[212:213], v[252:253] neg_lo:[0,1] neg_hi:[0,1]
	v_pk_add_f32 v[214:215], v[214:215], v[252:253] neg_lo:[0,1] neg_hi:[0,1]
	v_pk_add_f32 v[216:217], v[216:217], v[252:253] neg_lo:[0,1] neg_hi:[0,1]
	v_pk_add_f32 v[218:219], v[218:219], v[252:253] neg_lo:[0,1] neg_hi:[0,1]
	v_exp_f32_e32 v84, v84
	v_exp_f32_e32 v85, v85
	v_exp_f32_e32 v86, v86
	v_exp_f32_e32 v87, v87
	v_exp_f32_e32 v88, v88
	v_add_f32_e32 v252, v84, v86
	v_add_f32_e32 v253, v85, v87
	v_exp_f32_e32 v89, v89
	v_cvt_pk_bf16_f32 v84, v84, v85
	v_cvt_pk_bf16_f32 v85, v86, v87
	v_exp_f32_e32 v90, v90
	v_exp_f32_e32 v91, v91
	v_add_f32_e32 v252, v252, v88
	v_add_f32_e32 v253, v253, v89
	v_add_f32_e32 v252, v252, v90
	v_add_f32_e32 v253, v253, v91
	v_cvt_pk_bf16_f32 v86, v88, v89
	v_cvt_pk_bf16_f32 v87, v90, v91
	v_exp_f32_e32 v92, v92
	v_exp_f32_e32 v93, v93
	v_exp_f32_e32 v94, v94
	v_exp_f32_e32 v95, v95
	v_add_f32_e32 v252, v252, v92
	v_add_f32_e32 v253, v253, v93
	v_add_f32_e32 v252, v252, v94
	v_add_f32_e32 v253, v253, v95
	v_exp_f32_e32 v96, v96
	v_exp_f32_e32 v97, v97
	v_cvt_pk_bf16_f32 v88, v92, v93
	v_cvt_pk_bf16_f32 v89, v94, v95
	v_exp_f32_e32 v98, v98
	v_exp_f32_e32 v99, v99
	v_add_f32_e32 v252, v252, v96
	v_add_f32_e32 v253, v253, v97
	v_add_f32_e32 v252, v252, v98
	v_add_f32_e32 v253, v253, v99
	v_cvt_pk_bf16_f32 v90, v96, v97
	v_cvt_pk_bf16_f32 v91, v98, v99
	v_exp_f32_e32 v100, v100
	v_exp_f32_e32 v101, v101
	v_exp_f32_e32 v102, v102
	v_exp_f32_e32 v103, v103
	v_add_f32_e32 v252, v252, v100
	v_add_f32_e32 v253, v253, v101
	v_add_f32_e32 v252, v252, v102
	v_add_f32_e32 v253, v253, v103
	v_exp_f32_e32 v104, v104
	v_exp_f32_e32 v105, v105
	v_cvt_pk_bf16_f32 v100, v100, v101
	v_cvt_pk_bf16_f32 v101, v102, v103
	v_exp_f32_e32 v106, v106
	v_exp_f32_e32 v107, v107
	v_add_f32_e32 v252, v252, v104
	v_add_f32_e32 v253, v253, v105
	v_add_f32_e32 v252, v252, v106
	v_add_f32_e32 v253, v253, v107
	v_cvt_pk_bf16_f32 v102, v104, v105
	v_cvt_pk_bf16_f32 v103, v106, v107
	v_exp_f32_e32 v108, v108
	v_exp_f32_e32 v109, v109
	v_exp_f32_e32 v110, v110
	v_exp_f32_e32 v111, v111
	v_add_f32_e32 v252, v252, v108
	v_add_f32_e32 v253, v253, v109
	v_add_f32_e32 v252, v252, v110
	v_add_f32_e32 v253, v253, v111
	v_exp_f32_e32 v112, v112
	v_exp_f32_e32 v113, v113
	v_cvt_pk_bf16_f32 v104, v108, v109
	v_cvt_pk_bf16_f32 v105, v110, v111
	v_exp_f32_e32 v114, v114
	v_exp_f32_e32 v115, v115
	v_add_f32_e32 v252, v252, v112
	v_add_f32_e32 v253, v253, v113
	v_add_f32_e32 v252, v252, v114
	v_add_f32_e32 v253, v253, v115
	v_cvt_pk_bf16_f32 v106, v112, v113
	v_cvt_pk_bf16_f32 v107, v114, v115
	s_mov_b32 s24, s23
	s_mov_b32 s35, s24
	v_mov_b32_e32 v251, 0
	s_cmp_eq_u32 s24, 1
	s_cselect_b64 vcc, -1, 0
	v_cndmask_b32_e32 v251, v251, v177, vcc
	s_cmp_eq_u32 s24, 2
	s_cselect_b64 vcc, -1, 0
	v_cndmask_b32_e32 v251, v251, v178, vcc
	v_sub_f32_e32 v2, v251, v186
	v_mov_b32_e32 v3, v2
	v_mov_b64_e32 v[4:5], v[2:3]
	v_mov_b64_e32 v[6:7], v[2:3]
	v_mov_b64_e32 v[8:9], v[2:3]
	v_mov_b64_e32 v[10:11], v[2:3]
	v_mov_b64_e32 v[12:13], v[2:3]
	v_mov_b64_e32 v[14:15], v[2:3]
	v_mov_b64_e32 v[16:17], v[2:3]
	ds_read_b64_tr_b16 v[132:133], v228 offset:32768
	ds_read_b64_tr_b16 v[134:135], v228 offset:34816
	ds_read_b64_tr_b16 v[136:137], v229 offset:32768
	ds_read_b64_tr_b16 v[138:139], v229 offset:34816
	ds_read_b64_tr_b16 v[140:141], v230 offset:32768
	ds_read_b64_tr_b16 v[142:143], v230 offset:34816
	ds_read_b64_tr_b16 v[144:145], v231 offset:32768
	ds_read_b64_tr_b16 v[146:147], v231 offset:34816
	ds_read_b64_tr_b16 v[220:221], v228 offset:36864
	ds_read_b64_tr_b16 v[222:223], v228 offset:38912
	ds_read_b64_tr_b16 v[224:225], v229 offset:36864
	ds_read_b64_tr_b16 v[226:227], v229 offset:38912
	ds_read_b64_tr_b16 v[232:233], v230 offset:36864
	ds_read_b64_tr_b16 v[234:235], v230 offset:38912
	s_nop 1
	s_cmp_eq_u32 s22, 0
	s_cbranch_scc1 .LatB_recret_h2
	s_cmp_eq_u32 s22, 1
	s_cbranch_scc1 .LatB_recret_m2
	s_branch .LatB_recret_x2

; #define LAS __attribute__((address_space(3)))
; __device__ __forceinline__ float max2f(float a, float b) { float r; asm("v_max_f32_e32 %0, %1, %2" : "=v"(r) : "v"(a), "v"(b)); return r; }
; __device__ __forceinline__ void attn_unit(LAS unsigned char* lds, const bf16_t* Z, bf16_t* A2, const float* tabg, int seq_base, int S, int h, int qb, float lam) {
;     ...
;         if (first || __any(mx > THR)) {
;             { auto rr = __builtin_amdgcn_permlane32_swap(__float_as_uint(mx), __float_as_uint(mx), false, false); mx = max2f(__uint_as_float(rr[0]), __uint_as_float(rr[1])); }
;             const float delta = first ? mx : fmaxf(mx, 0.f);
;             const float alpha = first ? 1.0f : __builtin_amdgcn_exp2f(-delta);
;             mu += delta; ls2 *= alpha;
;             if (!first) {
;                 asm volatile("" ::: "memory");
;                 scr[r32] = alpha;
;                 asm volatile("s_waitcnt lgkmcnt(0)" ::: "memory");
; #pragma unroll
;                 for (int g = 0; g < 4; ++g) { const f32x4 a4 = *(const LAS f32x4*)(scr + 8 * g + 4 * hi);
; #pragma unroll
;                     for (int d = 0; d < 4; ++d) { O[d][4 * g + 0] *= a4[0]; O[d][4 * g + 1] *= a4[1]; O[d][4 * g + 2] *= a4[2]; O[d][4 * g + 3] *= a4[3]; } }
;                 asm volatile("s_waitcnt lgkmcnt(0)" ::: "memory");
;             }
; #pragma unroll
;             for (int r = 0; r < 16; ++r) { p0[r] -= delta; p1[r] -= delta; }
.LatB_recnn_3:
	v_max3_f32 v251, v188, v189, v190
	v_max3_f32 v252, v191, v192, v193
	v_max3_f32 v251, v251, v194, v195
	v_max3_f32 v252, v252, v196, v197
	v_max3_f32 v251, v251, v198, v199
	v_max3_f32 v252, v252, v200, v201
	v_max3_f32 v251, v251, v202, v203
	v_max3_f32 v252, v252, v204, v205
	v_max3_f32 v251, v251, v206, v207
	v_max3_f32 v252, v252, v208, v209
	v_max3_f32 v251, v251, v210, v211
	v_max3_f32 v252, v252, v212, v213
	v_max3_f32 v251, v251, v214, v215
	v_max3_f32 v252, v252, v216, v217
	v_max3_f32 v251, v251, v218, v219
	v_max_f32_e32 v251, v251, v252
	v_mov_b32_e32 v252, v251
	s_nop 1
	v_permlane32_swap_b32_e32 v251, v252
	v_max_f32_e32 v251, v251, v252
	v_max_f32_e32 v253, 0, v251
	v_exp_f32_e64 v254, -v253
	v_add_f32_e32 v186, v186, v253
	s_nop 0
	v_mul_f32_e32 v150, v150, v254
	v_mul_f32_e32 v151, v151, v254
	ds_write_b32 v184, v254
	s_waitcnt lgkmcnt(0)
	ds_read_b128 v[132:135], v185
	ds_read_b128 v[136:139], v185 offset:32
	ds_read_b128 v[140:143], v185 offset:64
	ds_read_b128 v[144:147], v185 offset:96
	s_waitcnt lgkmcnt(0)
	v_pk_mul_f32 v[20:21], v[20:21], v[132:133]
	v_pk_mul_f32 v[22:23], v[22:23], v[134:135]
	v_pk_mul_f32 v[24:25], v[24:25], v[136:137]
	v_pk_mul_f32 v[26:27], v[26:27], v[138:139]
	v_pk_mul_f32 v[28:29], v[28:29], v[140:141]
	v_pk_mul_f32 v[30:31], v[30:31], v[142:143]
	v_pk_mul_f32 v[32:33], v[32:33], v[144:145]
	v_pk_mul_f32 v[34:35], v[34:35], v[146:147]
	v_pk_mul_f32 v[36:37], v[36:37], v[132:133]
	v_pk_mul_f32 v[38:39], v[38:39], v[134:135]
	v_pk_mul_f32 v[40:41], v[40:41], v[136:137]
	v_pk_mul_f32 v[42:43], v[42:43], v[138:139]
	v_pk_mul_f32 v[44:45], v[44:45], v[140:141]
	v_pk_mul_f32 v[46:47], v[46:47], v[142:143]
	v_pk_mul_f32 v[48:49], v[48:49], v[144:145]
	v_pk_mul_f32 v[50:51], v[50:51], v[146:147]
	v_pk_mul_f32 v[52:53], v[52:53], v[132:133]
	v_pk_mul_f32 v[54:55], v[54:55], v[134:135]
	v_pk_mul_f32 v[56:57], v[56:57], v[136:137]
	v_pk_mul_f32 v[58:59], v[58:59], v[138:139]
	v_pk_mul_f32 v[60:61], v[60:61], v[140:141]
	v_pk_mul_f32 v[62:63], v[62:63], v[142:143]
	v_pk_mul_f32 v[64:65], v[64:65], v[144:145]
	v_pk_mul_f32 v[66:67], v[66:67], v[146:147]
	v_pk_mul_f32 v[68:69], v[68:69], v[132:133]
	v_pk_mul_f32 v[70:71], v[70:71], v[134:135]
	v_pk_mul_f32 v[72:73], v[72:73], v[136:137]
	v_pk_mul_f32 v[74:75], v[74:75], v[138:139]
	v_pk_mul_f32 v[76:77], v[76:77], v[140:141]
	v_pk_mul_f32 v[78:79], v[78:79], v[142:143]
	v_pk_mul_f32 v[80:81], v[80:81], v[144:145]
	v_pk_mul_f32 v[82:83], v[82:83], v[146:147]
	v_mov_b32_e32 v252, v253
	v_pk_add_f32 v[188:189], v[188:189], v[252:253] neg_lo:[0,1] neg_hi:[0,1]
	v_pk_add_f32 v[190:191], v[190:191], v[252:253] neg_lo:[0,1] neg_hi:[0,1]
	v_pk_add_f32 v[192:193], v[192:193], v[252:253] neg_lo:[0,1] neg_hi:[0,1]
	v_pk_add_f32 v[194:195], v[194:195], v[252:253] neg_lo:[0,1] neg_hi:[0,1]
	v_pk_add_f32 v[196:197], v[196:197], v[252:253] neg_lo:[0,1] neg_hi:[0,1]
	v_pk_add_f32 v[198:199], v[198:199], v[252:253] neg_lo:[0,1] neg_hi:[0,1]
	v_pk_add_f32 v[200:201], v[200:201], v[252:253] neg_lo:[0,1] neg_hi:[0,1]
	v_pk_add_f32 v[202:203], v[202:203], v[252:253] neg_lo:[0,1] neg_hi:[0,1]
	v_pk_add_f32 v[204:205], v[204:205], v[252:253] neg_lo:[0,1] neg_hi:[0,1]
	v_pk_add_f32 v[206:207], v[206:207], v[252:253] neg_lo:[0,1] neg_hi:[0,1]
	v_pk_add_f32 v[208:209], v[208:209], v[252:253] neg_lo:[0,1] neg_hi:[0,1]
	v_pk_add_f32 v[210:211], v[210:211], v[252:253] neg_lo:[0,1] neg_hi:[0,1]
	v_pk_add_f32 v[212:213], v[212:213], v[252:253] neg_lo:[0,1] neg_hi:[0,1]
	v_pk_add_f32 v[214:215], v[214:215], v[252:253] neg_lo:[0,1] neg_hi:[0,1]
	v_pk_add_f32 v[216:217], v[216:217], v[252:253] neg_lo:[0,1] neg_hi:[0,1]
	v_pk_add_f32 v[218:219], v[218:219], v[252:253] neg_lo:[0,1] neg_hi:[0,1]
	v_pk_add_f32 v[84:85], v[84:85], v[252:253] neg_lo:[0,1] neg_hi:[0,1]
	v_pk_add_f32 v[86:87], v[86:87], v[252:253] neg_lo:[0,1] neg_hi:[0,1]
	v_pk_add_f32 v[88:89], v[88:89], v[252:253] neg_lo:[0,1] neg_hi:[0,1]
	v_pk_add_f32 v[90:91], v[90:91], v[252:253] neg_lo:[0,1] neg_hi:[0,1]
	v_pk_add_f32 v[92:93], v[92:93], v[252:253] neg_lo:[0,1] neg_hi:[0,1]
	v_pk_add_f32 v[94:95], v[94:95], v[252:253] neg_lo:[0,1] neg_hi:[0,1]
	v_pk_add_f32 v[96:97], v[96:97], v[252:253] neg_lo:[0,1] neg_hi:[0,1]
	v_pk_add_f32 v[98:99], v[98:99], v[252:253] neg_lo:[0,1] neg_hi:[0,1]
; __device__ __forceinline__ void attn_unit(LAS unsigned char* lds, const bf16_t* Z, bf16_t* A2, const float* tabg, int seq_base, int S, int h, int qb, float lam) {
;     ...
;         if (kv0 - (qlo + 31) >= 128) { near = false; cc = tabR; } else if (qlo - (kv0 + 63) >= 128) { near = false; cc = tabL; }
;         { const float coff = cc - mu;
;           if (__any(!(coff == coff_cur))) { coff_cur = coff;
; #pragma unroll
;               for (int r = 0; r < 16; ++r) cblk[r] = coff;
;               asm volatile("" : "+v"(cblk)); } }
;     ...
;             for (int r = 0; r < 16; ++r) { p0[r] -= delta; p1[r] -= delta; }
;             asm volatile("" : "+v"(p0), "+v"(p1));
;         }
; #pragma unroll
;         for (int r = 0; r < 16; ++r) { p0[r] = __builtin_amdgcn_exp2f(p0[r]); p1[r] = __builtin_amdgcn_exp2f(p1[r]); }
; #pragma unroll
;         for (int r = 0; r < 16; r += 2) { ls2 += (f32x2){p0[r], p0[r + 1]}; ls2 += (f32x2){p1[r], p1[r + 1]}; }
;         bf16x8 pa[4]; pa[0] = pack8(p0, 0); pa[1] = pack8(p0, 8); pa[2] = pack8(p1, 0); pa[3] = pack8(p1, 8);
	v_pk_add_f32 v[100:101], v[100:101], v[252:253] neg_lo:[0,1] neg_hi:[0,1]
	v_pk_add_f32 v[102:103], v[102:103], v[252:253] neg_lo:[0,1] neg_hi:[0,1]
	v_pk_add_f32 v[104:105], v[104:105], v[252:253] neg_lo:[0,1] neg_hi:[0,1]
	v_pk_add_f32 v[106:107], v[106:107], v[252:253] neg_lo:[0,1] neg_hi:[0,1]
	v_pk_add_f32 v[108:109], v[108:109], v[252:253] neg_lo:[0,1] neg_hi:[0,1]
	v_pk_add_f32 v[110:111], v[110:111], v[252:253] neg_lo:[0,1] neg_hi:[0,1]
	v_pk_add_f32 v[112:113], v[112:113], v[252:253] neg_lo:[0,1] neg_hi:[0,1]
	v_pk_add_f32 v[114:115], v[114:115], v[252:253] neg_lo:[0,1] neg_hi:[0,1]
	v_exp_f32_e32 v188, v188
	v_exp_f32_e32 v189, v189
	v_exp_f32_e32 v190, v190
	v_exp_f32_e32 v191, v191
	v_exp_f32_e32 v192, v192
	v_add_f32_e32 v252, v188, v190
	v_add_f32_e32 v253, v189, v191
	v_exp_f32_e32 v193, v193
	v_cvt_pk_bf16_f32 v188, v188, v189
	v_cvt_pk_bf16_f32 v189, v190, v191
	v_exp_f32_e32 v194, v194
	v_exp_f32_e32 v195, v195
	v_add_f32_e32 v252, v252, v192
	v_add_f32_e32 v253, v253, v193
	v_add_f32_e32 v252, v252, v194
	v_add_f32_e32 v253, v253, v195
	v_cvt_pk_bf16_f32 v190, v192, v193
	v_cvt_pk_bf16_f32 v191, v194, v195
	v_exp_f32_e32 v196, v196
	v_exp_f32_e32 v197, v197
	v_exp_f32_e32 v198, v198
	v_exp_f32_e32 v199, v199
	v_add_f32_e32 v252, v252, v196
	v_add_f32_e32 v253, v253, v197
	v_add_f32_e32 v252, v252, v198
	v_add_f32_e32 v253, v253, v199
	v_exp_f32_e32 v200, v200
	v_exp_f32_e32 v201, v201
	v_cvt_pk_bf16_f32 v192, v196, v197
	v_cvt_pk_bf16_f32 v193, v198, v199
	v_exp_f32_e32 v202, v202
	v_exp_f32_e32 v203, v203
	v_add_f32_e32 v252, v252, v200
	v_add_f32_e32 v253, v253, v201
	v_add_f32_e32 v252, v252, v202
	v_add_f32_e32 v253, v253, v203
	v_cvt_pk_bf16_f32 v194, v200, v201
	v_cvt_pk_bf16_f32 v195, v202, v203
	v_exp_f32_e32 v204, v204
	v_exp_f32_e32 v205, v205
	v_exp_f32_e32 v206, v206
	v_exp_f32_e32 v207, v207
	v_add_f32_e32 v252, v252, v204
	v_add_f32_e32 v253, v253, v205
	v_add_f32_e32 v252, v252, v206
	v_add_f32_e32 v253, v253, v207
	v_exp_f32_e32 v208, v208
	v_exp_f32_e32 v209, v209
	v_cvt_pk_bf16_f32 v204, v204, v205
	v_cvt_pk_bf16_f32 v205, v206, v207
	v_exp_f32_e32 v210, v210
	v_exp_f32_e32 v211, v211
	v_add_f32_e32 v252, v252, v208
	v_add_f32_e32 v253, v253, v209
	v_add_f32_e32 v252, v252, v210
	v_add_f32_e32 v253, v253, v211
	v_cvt_pk_bf16_f32 v206, v208, v209
	v_cvt_pk_bf16_f32 v207, v210, v211
	v_exp_f32_e32 v212, v212
	v_exp_f32_e32 v213, v213
	v_exp_f32_e32 v214, v214
	v_exp_f32_e32 v215, v215
	v_add_f32_e32 v252, v252, v212
	v_add_f32_e32 v253, v253, v213
	v_add_f32_e32 v252, v252, v214
	v_add_f32_e32 v253, v253, v215
	v_exp_f32_e32 v216, v216
	v_exp_f32_e32 v217, v217
	v_cvt_pk_bf16_f32 v208, v212, v213
	v_cvt_pk_bf16_f32 v209, v214, v215
	v_exp_f32_e32 v218, v218
	v_exp_f32_e32 v219, v219
	v_add_f32_e32 v252, v252, v216
	v_add_f32_e32 v253, v253, v217
	v_add_f32_e32 v252, v252, v218
	v_add_f32_e32 v253, v253, v219
	v_cvt_pk_bf16_f32 v210, v216, v217
	v_cvt_pk_bf16_f32 v211, v218, v219
	s_mov_b32 s24, s23
	s_mov_b32 s35, s24
	v_mov_b32_e32 v251, 0
	s_cmp_eq_u32 s24, 1
	s_cselect_b64 vcc, -1, 0
	v_cndmask_b32_e32 v251, v251, v177, vcc
	s_cmp_eq_u32 s24, 2
	s_cselect_b64 vcc, -1, 0
	v_cndmask_b32_e32 v251, v251, v178, vcc
	v_sub_f32_e32 v2, v251, v186
	v_mov_b32_e32 v3, v2
	v_mov_b64_e32 v[4:5], v[2:3]
	v_mov_b64_e32 v[6:7], v[2:3]
	v_mov_b64_e32 v[8:9], v[2:3]
	v_mov_b64_e32 v[10:11], v[2:3]
	v_mov_b64_e32 v[12:13], v[2:3]
	v_mov_b64_e32 v[14:15], v[2:3]
	v_mov_b64_e32 v[16:17], v[2:3]
	ds_read_b64_tr_b16 v[132:133], v168 offset:0
	ds_read_b64_tr_b16 v[134:135], v168 offset:2048
	ds_read_b64_tr_b16 v[136:137], v169 offset:0
	ds_read_b64_tr_b16 v[138:139], v169 offset:2048
	ds_read_b64_tr_b16 v[140:141], v170 offset:0
	ds_read_b64_tr_b16 v[142:143], v170 offset:2048
	ds_read_b64_tr_b16 v[144:145], v171 offset:0
	ds_read_b64_tr_b16 v[146:147], v171 offset:2048
	ds_read_b64_tr_b16 v[220:221], v168 offset:4096
	ds_read_b64_tr_b16 v[222:223], v168 offset:6144
	ds_read_b64_tr_b16 v[224:225], v169 offset:4096
	ds_read_b64_tr_b16 v[226:227], v169 offset:6144
	ds_read_b64_tr_b16 v[232:233], v170 offset:4096
	ds_read_b64_tr_b16 v[234:235], v170 offset:6144
	s_nop 1
	s_cmp_eq_u32 s22, 0
	s_cbranch_scc1 .LatB_recret_h3
	s_cmp_eq_u32 s22, 1
	s_cbranch_scc1 .LatB_recret_m3
	s_branch .LatB_recret_x1
